# GEMM K-loops: first trip peeled with zero C operand, per-tile accumulator clears removed
# speedup vs baseline: 1.0026x; 1.0026x over previous
; #define PG8_WAIT_V(n) asm volatile("s_waitcnt vmcnt(" #n ")" ::: "memory")
; #define PG8_BAR __builtin_amdgcn_s_barrier()
; template <class Epi, class Sched, bool ALIGN_EPI = false, bool SP2 = false>
; __device__ __forceinline__ void gemm_phase(PG8_LAS unsigned char* lds, const Gemm g, const Sched& S, const Epi& E) {
;     int tid_ = threadIdx.x; asm volatile("" : "+v"(tid_));
;     const int tid = tid_, wid = __builtin_amdgcn_readfirstlane(tid >> 6), lane = tid & 63, wr = wid >> 2, wc = wid & 3, fr = lane & 15, fq = lane >> 4;
;     const int K = g.K, nt = K / BK;
;     unsigned voffA[2], voffB[2];
; #pragma unroll
;     for (int i = 0; i < 2; ++i) { int R, C; stage_rc(tid * 16 + i * 8192, R, C); const int Rb = Epi::PERM ? ((R & ~31) + perm32(R & 31)) : R;
;         voffA[i] = (unsigned)(R * K + C) * 2u; voffB[i] = (unsigned)(Rb * K + C) * 2u; }
;     const size_t kstep = (size_t)(BK * 2);
;     const size_t hstep = (size_t)HALF * K * 2;
;     const size_t tstep = 2 * hstep;
;     const unsigned ldsw = (unsigned)wid * 1024u;
;     const int aoff = lds_byte(wr * 64 + fr, fq * 8), boff = lds_byte(wc * 32 + fr, fq * 8);
;     ...
;     Unit cur, nxt; int ui = 0;
;     if (!S.next(0, cur)) return;
;     f32x4 acc[2][2][4][2];
; #pragma unroll
;     for (int a = 0; a < 2; ++a)
; #pragma unroll
;         for (int b = 0; b < 2; ++b)
; #pragma unroll
;             for (int m = 0; m < 4; ++m)
; #pragma unroll
;                 for (int n = 0; n < 2; ++n) acc[a][b][m][n] = (f32x4){0.f, 0.f, 0.f, 0.f};
;     bf16x8 At[4][2], B0[2][2], B1[2][2];
;     const char* cA = (const char*)g.A + (size_t)cur.pm * tstep; const char* cB = (const char*)g.Bt + (size_t)cur.pn * tstep;
;     S.a_ready(cur);
;     if constexpr (SP2) {
;         PG8_STAGE(PG8_SB(0, 0), cB, voffB); PG8_STAGE(PG8_SB(0, 1), cB + hstep, voffB); PG8_STAGE(PG8_SA(0, 0), cA, voffA); PG8_STAGE(PG8_SA(0, 1), cA + hstep, voffA);
;         if (wr == 1) PG8_BAR;
;         PG8_WAIT_V(2); PG8_BAR;
;         PG8_STAGE(PG8_SB(1, 0), cB + kstep, voffB); PG8_STAGE(PG8_SA(1, 0), cA + kstep, voffA); PG8_STAGE(PG8_SB(1, 1), cB + hstep + kstep, voffB);
;         PG8_WAIT_V(6); PG8_BAR;
;     } else {
;         PG8_STAGE(PG8_SB(0, 0), cB, voffB); PG8_STAGE(PG8_SA(0, 0), cA, voffA); PG8_STAGE(PG8_SB(0, 1), cB + hstep, voffB); PG8_STAGE(PG8_SA(0, 1), cA + hstep, voffA);
;         if (wr == 1) PG8_BAR;
;         PG8_WAIT_V(4); PG8_BAR;
.LBB0_162:
	s_or_b64 exec, exec, s[14:15]
	s_nop 0
	s_nop 0
	s_nop 0
	s_nop 0
	s_nop 0
	s_nop 0
	s_nop 0
	s_nop 0
	s_nop 0
	s_nop 0
	s_nop 0
	s_nop 0
	s_nop 0
	s_nop 0
	s_nop 0
	s_nop 0
	s_nop 0
	s_nop 0
	s_nop 0
	s_nop 0
	v_writelane_b32 v254, s34, 49
	s_ashr_i32 s3, s46, 31
	s_ashr_i32 s33, s2, 31
	s_mov_b64 s[24:25], s[0:1]
	s_mov_b64 s[26:27], s[0:1]
	s_mov_b64 s[14:15], s[0:1]
	s_mov_b64 s[16:17], s[0:1]
	s_mov_b64 s[18:19], s[0:1]
	s_mov_b64 s[20:21], s[0:1]
	s_mov_b64 s[22:23], s[0:1]
	v_mov_b32_e32 v14, v216
	v_writelane_b32 v254, s35, 50
	s_waitcnt lgkmcnt(0)
	s_barrier
	s_cmpk_gt_i32 s2, 0x11ff
	v_writelane_b32 v254, s60, 51
	v_readfirstlane_b32 s30, v14
	s_nop 0
	v_writelane_b32 v254, s61, 52
	s_cbranch_scc1 .LBB0_186
	v_lshlrev_b32_e32 v0, 4, v14
	v_add_u32_e32 v1, 0x2000, v0
	v_ashrrev_i32_e32 v2, 31, v1
	v_lshrrev_b32_e32 v2, 22, v2
	v_add_u32_e32 v2, v1, v2
	v_ashrrev_i32_e32 v8, 10, v2
	v_mul_i32_i24_e32 v2, 0x400, v8
	v_sub_u32_e32 v1, v1, v2
	v_lshrrev_b32_e32 v2, 4, v1
	v_bitop3_b32 v1, v2, v1, 32 bitop3:0x6c
	v_ashrrev_i32_e32 v2, 31, v1
	s_load_dwordx2 s[24:25], s[24:25], 0xc8
	s_nop 0
	s_load_dwordx2 s[26:27], s[26:27], 0xc8
	v_lshrrev_b32_e32 v2, 26, v2
	v_add_u32_e32 v2, v1, v2
	v_lshlrev_b32_e32 v3, 3, v8
	v_ashrrev_i32_e32 v9, 6, v2
	v_and_b32_e32 v3, -16, v3
	v_add_u32_e32 v3, v9, v3
	s_waitcnt lgkmcnt(0)
	s_add_u32 s13, s24, 0x7800000
	v_and_b32_e32 v4, 3, v9
	s_mov_b32 s24, 0xfffe0
	v_lshrrev_b32_e32 v5, 2, v3
	v_lshlrev_b32_e32 v6, 1, v3
	v_and_b32_e32 v2, 0xc0, v2
	v_and_or_b32 v4, v3, s24, v4
	v_and_b32_e32 v5, 4, v5
	v_and_b32_e32 v6, 24, v6
	v_sub_u32_e32 v1, v1, v2
	v_mov_b32_e32 v2, 1
	v_or3_b32 v4, v4, v5, v6
	v_lshlrev_b32_e32 v5, 5, v8
	v_ashrrev_i16_sdwa v1, v2, sext(v1) dst_sel:DWORD dst_unused:UNUSED_PAD src0_sel:DWORD src1_sel:BYTE_0
	v_and_b32_e32 v5, 32, v5
	v_bfe_i32 v10, v1, 0, 16
	v_add_lshl_u32 v1, v5, v10, 1
	v_lshl_add_u32 v144, v4, 12, v1
	v_lshl_add_u32 v146, v3, 12, v1
	v_bfe_i32 v1, v14, 27, 1
	v_lshrrev_b32_e32 v1, 22, v1
	v_add_u32_e32 v1, v0, v1
	v_and_b32_e32 v1, 0xfffffc00, v1
	v_sub_u32_e32 v0, v0, v1
	v_lshrrev_b32_e32 v1, 4, v0
	v_ashrrev_i32_e32 v3, 31, v14
	v_bitop3_b32 v0, v1, v0, 32 bitop3:0x6c
	v_lshrrev_b32_e32 v3, 26, v3
	v_ashrrev_i32_e32 v1, 31, v0
	v_add_u32_e32 v3, v14, v3
	v_lshrrev_b32_e32 v1, 26, v1
	v_ashrrev_i32_e32 v12, 6, v3
	v_add_u32_e32 v1, v0, v1
	v_lshlrev_b32_e32 v3, 3, v12
	s_addc_u32 s47, s25, 0
	v_ashrrev_i32_e32 v11, 6, v1
	v_and_b32_e32 v3, -16, v3
	s_add_u32 s48, s26, 0x200000
	v_add_u32_e32 v3, v11, v3
	v_and_b32_e32 v4, 3, v11
	s_addc_u32 s49, s27, 0
	v_and_or_b32 v4, v3, s24, v4
	s_lshr_b32 s24, s33, 29
	s_add_i32 s24, s2, s24
	s_ashr_i32 s25, s30, 6
	s_ashr_i32 s26, s24, 3
	s_and_b32 s24, s24, -8
	s_ashr_i32 s31, s30, 8
	s_lshl_b32 s50, s25, 10
	s_sub_i32 s24, s2, s24
	s_cmp_lt_i32 s24, 0
	s_movk_i32 s51, 0x241
	s_cselect_b32 s27, s51, 0x240
	s_mul_i32 s24, s24, s27
	s_add_i32 s24, s24, s26
	s_mul_hi_i32 s26, s24, 0x38e38e39
	s_lshr_b32 s27, s26, 31
	s_ashr_i32 s26, s26, 5
	s_add_i32 s26, s26, s27
	s_lshl_b32 s27, s26, 2
	s_mulk_i32 s26, 0x90
	s_sub_i32 s26, s24, s26
	s_sext_i32_i16 s24, s26
	s_bfe_u32 s24, s24, 0x2001d
	s_add_i32 s28, s26, s24
	s_sext_i32_i16 s24, s28
	s_and_b32 s28, s28, 0xfffc
	s_sub_i32 s26, s26, s28
	s_sext_i32_i16 s26, s26
	v_lshrrev_b32_e32 v5, 2, v3
	v_lshlrev_b32_e32 v6, 1, v3
	v_and_b32_e32 v1, 0xc0, v1
	s_lshr_b32 s24, s24, 2
	s_add_i32 s36, s27, s26
	v_and_b32_e32 v5, 4, v5
	v_and_b32_e32 v6, 24, v6
	v_sub_u32_e32 v0, v0, v1
	s_ashr_i32 s37, s36, 31
	s_bfe_i64 s[28:29], s[24:25], 0x100000
	v_or3_b32 v4, v4, v5, v6
	v_lshlrev_b32_e32 v5, 5, v12
	v_ashrrev_i16_sdwa v0, v2, sext(v0) dst_sel:DWORD dst_unused:UNUSED_PAD src0_sel:DWORD src1_sel:BYTE_0
	s_lshl_b64 s[26:27], s[36:37], 20
	s_lshl_b64 s[28:29], s[28:29], 20
	v_and_b32_e32 v5, 32, v5
	v_bfe_i32 v13, v0, 0, 16
	s_add_u32 s42, s48, s28
	v_add_lshl_u32 v0, v5, v13, 1
	s_addc_u32 s43, s49, s29
	s_add_i32 s52, s50, 0
	v_lshl_add_u32 v148, v4, 12, v0
	s_add_i32 m0, s52, 0x10000
	v_lshl_add_u32 v150, v3, 12, v0
	global_load_lds_dwordx4 v148, s[42:43]
	s_add_i32 m0, s52, 0x12000
	s_add_u32 s28, s42, 0x80000
	global_load_lds_dwordx4 v144, s[42:43]
	s_addc_u32 s29, s43, 0
	s_add_i32 m0, s52, 0x14000
	v_mov_b32_e32 v153, 0
	global_load_lds_dwordx4 v148, s[28:29]
	s_add_i32 m0, s52, 0x16000
	s_add_u32 s40, s13, s26
	s_addc_u32 s41, s47, s27
	s_add_i32 s53, s52, 0x2000
	global_load_lds_dwordx4 v144, s[28:29]
	s_mov_b32 m0, s52
	s_add_u32 s26, s40, 0x80000
	global_load_lds_dwordx4 v150, s[40:41]
	s_mov_b32 m0, s53
	s_addc_u32 s27, s41, 0
	s_add_i32 s54, s52, 0x4000
	global_load_lds_dwordx4 v146, s[40:41]
	s_mov_b32 m0, s54
	s_add_i32 s55, s52, 0x6000
	global_load_lds_dwordx4 v150, s[26:27]
	s_mov_b32 m0, s55
	v_mov_b32_e32 v149, v153
	global_load_lds_dwordx4 v146, s[26:27]
	s_load_dwordx2 s[28:29], s[14:15], 0xc8
	s_nop 0
	s_load_dwordx2 s[14:15], s[16:17], 0xc8
	s_load_dwordx2 s[26:27], s[18:19], 0xc8
	s_nop 0
	s_load_dwordx2 s[20:21], s[20:21], 0xc8
	s_nop 0
	s_load_dwordx2 s[16:17], s[22:23], 0x98
	v_mov_b32_e32 v145, v153
	v_mov_b32_e32 v151, v153
	v_mov_b32_e32 v147, v153
	s_cmp_eq_u32 s31, 1
	v_lshl_add_u64 v[6:7], s[42:43], 0, v[148:149]
	v_lshl_add_u64 v[2:3], s[42:43], 0, v[144:145]
	v_lshl_add_u64 v[0:1], s[40:41], 0, v[150:151]
	s_cselect_b64 s[18:19], -1, 0
	s_cmp_lg_u32 s31, 1
	v_lshl_add_u64 v[4:5], s[40:41], 0, v[146:147]
	s_cbranch_scc1 .LBB0_165
	s_barrier

; #define PG8_STAGE(bufoff, gbase, voff) do { _Pragma("unroll") for (int _i = 0; _i < 2; ++_i) \
;         __builtin_amdgcn_global_load_lds((const unsigned*)((const char*)(gbase) + (voff)[_i]), (PG8_LAS unsigned*)(lds + (bufoff) + ldsw + _i * 8192), 16, 0, 0); } while (0)
; #define PG8_LDA(dst, b, h) do { _Pragma("unroll") for (int m = 0; m < 4; ++m) _Pragma("unroll") for (int k = 0; k < 2; ++k) dst[m][k] = *(const PG8_LAS bf16x8*)(lds + PG8_SA(b, h) + aoff + m * 2048 + k * 1024); } while (0)
; template <class Epi, class Sched, bool ALIGN_EPI = false, bool SP2 = false>
; __device__ __forceinline__ void gemm_phase(PG8_LAS unsigned char* lds, const Gemm g, const Sched& S, const Epi& E) {
;     ...
;         const bool has_next = S.next(ui + 1, nxt);
;         const char* nA = has_next ? (const char*)g.A + (size_t)nxt.pm * tstep : cA; const char* nB = has_next ? (const char*)g.Bt + (size_t)nxt.pn * tstep : cB;
;         for (int t = 0; t < nt; t += 2) {
;             const bool last = (t == nt - 2);
;             const char* a1 = cA + (size_t)(t + 1) * kstep;
;             const char* a2 = last ? nA : cA + (size_t)(t + 2) * kstep; const char* b2 = last ? nB : cB + (size_t)(t + 2) * kstep;
;             const char* a3 = a2 + kstep; const char* b3 = b2 + kstep;
;             if (last && has_next) S.a_ready(nxt);
;             if constexpr (SP2) {
;             PG8_LDB(B0, 0, 0); PG8_LDB(B1, 0, 1); PG8_SCHED; PG8_LDA(At, 0, 0); PG8_STAGE(PG8_SA(1, 1), a1 + hstep, voffA);
;             PG8_WAIT_V(8); PG8_WAIT_L(0); PG8_BAR; PG8_MMA(0, 0, At, B0); PG8_MMA(0, 1, At, B1); PG8_BAR; PG8_SCHED;
;             PG8_LDA(At, 0, 1); PG8_STAGE(PG8_SB(0, 0), b2, voffB); PG8_STAGE(PG8_SB(0, 1), b2 + hstep, voffB); PG8_STAGE(PG8_SA(0, 0), a2, voffA);
;             PG8_WAIT_V(8); PG8_WAIT_L(0); PG8_BAR; PG8_MMA(1, 0, At, B0); PG8_MMA(1, 1, At, B1); PG8_BAR; PG8_SCHED;
;             PG8_LDB(B0, 1, 0); PG8_LDB(B1, 1, 1); PG8_SCHED; PG8_LDA(At, 1, 0); PG8_STAGE(PG8_SA(0, 1), a2 + hstep, voffA);
;             PG8_WAIT_V(8); PG8_WAIT_L(0); PG8_BAR; PG8_MMA(0, 0, At, B0); PG8_MMA(0, 1, At, B1); PG8_BAR; PG8_SCHED;
;             PG8_LDA(At, 1, 1); PG8_STAGE(PG8_SB(1, 0), b3, voffB); PG8_STAGE(PG8_SB(1, 1), b3 + hstep, voffB); PG8_STAGE(PG8_SA(1, 0), a3, voffA);
;             PG8_WAIT_V(8); PG8_WAIT_L(0); PG8_BAR; PG8_MMA(1, 0, At, B0); PG8_MMA(1, 1, At, B1); PG8_BAR; PG8_SCHED;
.LBB0_170:
	s_ashr_i32 s29, s28, 31
	s_lshl_b64 s[30:31], s[28:29], 20
	s_add_u32 s30, s13, s30
	s_addc_u32 s31, s47, s31
	s_and_b64 s[34:35], s[38:39], exec
	s_cselect_b32 s29, s31, s41
	s_cselect_b32 s37, s30, s40
	s_ashr_i32 s27, s26, 31
	s_lshl_b64 s[34:35], s[26:27], 20
	s_add_u32 s34, s48, s34
	s_addc_u32 s35, s49, s35
	s_and_b64 s[44:45], s[38:39], exec
	s_cselect_b32 s27, s35, s43
	s_cselect_b32 s65, s34, s42
	s_add_u32 s40, s40, 0x80080
	s_addc_u32 s41, s41, 0
	s_add_u32 s67, s42, 0x100
	s_addc_u32 s68, s43, 0
	s_mov_b32 s69, -2
	ds_read_b128 v[128:131], v175
	ds_read_b128 v[132:135], v175 offset:1024
	ds_read_b128 v[136:139], v175 offset:2048
	ds_read_b128 v[140:143], v175 offset:3072
	ds_read_b128 v[164:167], v176
	ds_read_b128 v[168:171], v176 offset:1024
	ds_read_b128 v[178:181], v176 offset:2048
	ds_read_b128 v[182:185], v176 offset:3072
	s_add_u32 s42, s40, 0xfff80080
	s_addc_u32 s43, s41, -1
	s_cmp_eq_u32 s69, 28
	s_cselect_b32 s45, s29, s43
	s_cselect_b32 s44, s37, s42
	s_cselect_b32 s43, s27, s68
	s_cselect_b32 s42, s65, s67
	v_lshl_add_u64 v[190:191], s[40:41], 0, v[156:157]
	s_add_i32 m0, s52, 0xc000
	ds_read_b128 v[186:189], v177
	ds_read_b128 v[194:197], v177 offset:1024
	ds_read_b128 v[198:201], v177 offset:2048
	ds_read_b128 v[202:205], v177 offset:3072
	ds_read_b128 v[206:209], v177 offset:4096
	ds_read_b128 v[210:213], v177 offset:5120
	ds_read_b128 v[218:221], v177 offset:6144
	ds_read_b128 v[222:225], v177 offset:7168
	global_load_lds_dwordx4 v[190:191], off
	v_lshl_add_u64 v[190:191], s[40:41], 0, v[158:159]
	s_add_i32 m0, s52, 0xe000
	s_nop 0
	global_load_lds_dwordx4 v[190:191], off
	s_waitcnt vmcnt(8)
	s_waitcnt lgkmcnt(0)
	s_barrier
	s_setprio 1
	s_waitcnt lgkmcnt(0)
	v_mfma_f32_16x16x32_bf16 v[124:127], v[128:131], v[186:189], 0
	v_mfma_f32_16x16x32_bf16 v[120:123], v[136:139], v[186:189], 0
	v_mfma_f32_16x16x32_bf16 v[116:119], v[128:131], v[198:201], 0
	v_mfma_f32_16x16x32_bf16 v[112:115], v[136:139], v[198:201], 0
	v_mfma_f32_16x16x32_bf16 v[100:103], v[128:131], v[206:209], 0
	v_mfma_f32_16x16x32_bf16 v[96:99], v[136:139], v[206:209], 0
	v_mfma_f32_16x16x32_bf16 v[84:87], v[128:131], v[218:221], 0
	v_mfma_f32_16x16x32_bf16 v[80:83], v[136:139], v[218:221], 0
	v_mfma_f32_16x16x32_bf16 v[124:127], v[132:135], v[194:197], v[124:127]
	v_mfma_f32_16x16x32_bf16 v[120:123], v[140:143], v[194:197], v[120:123]
	v_mfma_f32_16x16x32_bf16 v[116:119], v[132:135], v[202:205], v[116:119]
	v_mfma_f32_16x16x32_bf16 v[112:115], v[140:143], v[202:205], v[112:115]
	v_mfma_f32_16x16x32_bf16 v[100:103], v[132:135], v[210:213], v[100:103]
	v_mfma_f32_16x16x32_bf16 v[96:99], v[140:143], v[210:213], v[96:99]
	v_mfma_f32_16x16x32_bf16 v[84:87], v[132:135], v[222:225], v[84:87]
	v_mfma_f32_16x16x32_bf16 v[80:83], v[140:143], v[222:225], v[80:83]
	s_setprio 0
	s_setprio 1
	v_mfma_f32_16x16x32_bf16 v[108:111], v[164:167], v[186:189], 0
	v_mfma_f32_16x16x32_bf16 v[104:107], v[178:181], v[186:189], 0
	v_mfma_f32_16x16x32_bf16 v[92:95], v[164:167], v[198:201], 0
	v_mfma_f32_16x16x32_bf16 v[88:91], v[178:181], v[198:201], 0
	v_mfma_f32_16x16x32_bf16 v[76:79], v[164:167], v[206:209], 0
	v_mfma_f32_16x16x32_bf16 v[72:75], v[178:181], v[206:209], 0
	v_mfma_f32_16x16x32_bf16 v[68:71], v[164:167], v[218:221], 0
	v_mfma_f32_16x16x32_bf16 v[64:67], v[178:181], v[218:221], 0
	v_mfma_f32_16x16x32_bf16 v[108:111], v[168:171], v[194:197], v[108:111]
	v_mfma_f32_16x16x32_bf16 v[104:107], v[182:185], v[194:197], v[104:107]
	v_mfma_f32_16x16x32_bf16 v[92:95], v[168:171], v[202:205], v[92:95]
	v_mfma_f32_16x16x32_bf16 v[88:91], v[182:185], v[202:205], v[88:91]
	v_mfma_f32_16x16x32_bf16 v[76:79], v[168:171], v[210:213], v[76:79]
	v_mfma_f32_16x16x32_bf16 v[72:75], v[182:185], v[210:213], v[72:75]
	v_mfma_f32_16x16x32_bf16 v[68:71], v[168:171], v[222:225], v[68:71]
	v_mfma_f32_16x16x32_bf16 v[64:67], v[182:185], v[222:225], v[64:67]
	s_setprio 0
	s_barrier
	s_add_i32 s70, s61, s50
	v_lshl_add_u64 v[190:191], s[42:43], 0, v[148:149]
	s_mov_b32 m0, s70
	ds_read_b128 v[186:189], v177 offset:16384
	ds_read_b128 v[194:197], v177 offset:17408
	ds_read_b128 v[198:201], v177 offset:18432
	ds_read_b128 v[202:205], v177 offset:19456
	ds_read_b128 v[206:209], v177 offset:20480
	ds_read_b128 v[210:213], v177 offset:21504
	ds_read_b128 v[218:221], v177 offset:22528
	ds_read_b128 v[222:225], v177 offset:23552
	global_load_lds_dwordx4 v[190:191], off
	s_add_i32 m0, s70, 0x2000
	s_add_u32 s70, s42, 0x80000
	v_lshl_add_u64 v[214:215], s[42:43], 0, v[144:145]
	s_addc_u32 s71, s43, 0
	s_add_i32 s72, s62, s50
	global_load_lds_dwordx4 v[214:215], off
	v_lshl_add_u64 v[226:227], s[70:71], 0, v[148:149]
	s_mov_b32 m0, s72
	v_lshl_add_u64 v[228:229], s[44:45], 0, v[146:147]
	global_load_lds_dwordx4 v[226:227], off
	v_lshl_add_u64 v[226:227], s[70:71], 0, v[144:145]
	s_add_i32 m0, s72, 0x2000
	s_nop 0
	global_load_lds_dwordx4 v[226:227], off
	v_lshl_add_u64 v[226:227], s[44:45], 0, v[150:151]
	s_mov_b32 m0, s52
	s_nop 0
	global_load_lds_dwordx4 v[226:227], off
	s_mov_b32 m0, s53
	s_nop 0
	global_load_lds_dwordx4 v[228:229], off
	s_waitcnt vmcnt(8)
	s_waitcnt lgkmcnt(0)
	s_barrier
; #define PG8_STAGE(bufoff, gbase, voff) do { _Pragma("unroll") for (int _i = 0; _i < 2; ++_i) \
;         __builtin_amdgcn_global_load_lds((const unsigned*)((const char*)(gbase) + (voff)[_i]), (PG8_LAS unsigned*)(lds + (bufoff) + ldsw + _i * 8192), 16, 0, 0); } while (0)
; #define PG8_LDA(dst, b, h) do { _Pragma("unroll") for (int m = 0; m < 4; ++m) _Pragma("unroll") for (int k = 0; k < 2; ++k) dst[m][k] = *(const PG8_LAS bf16x8*)(lds + PG8_SA(b, h) + aoff + m * 2048 + k * 1024); } while (0)
; #define PG8_LDB(dst, b, h) do { _Pragma("unroll") for (int n = 0; n < 2; ++n) _Pragma("unroll") for (int k = 0; k < 2; ++k) dst[n][k] = *(const PG8_LAS bf16x8*)(lds + PG8_SB(b, h) + boff + n * 2048 + k * 1024); } while (0)
; #define PG8_MMA(ai, bj, At, Bt) do { __builtin_amdgcn_s_setprio(1); _Pragma("unroll") for (int m = 0; m < 4; ++m) _Pragma("unroll") for (int n = 0; n < 2; ++n) _Pragma("unroll") for (int k = 0; k < 2; ++k) \
;         acc[ai][bj][m][n] = __builtin_amdgcn_mfma_f32_16x16x32_bf16(Bt[n][k], At[m][k], acc[ai][bj][m][n], 0, 0, 0); __builtin_amdgcn_s_setprio(0); } while (0)
; #define PG8_WAIT_V(n) asm volatile("s_waitcnt vmcnt(" #n ")" ::: "memory")
; #define PG8_WAIT_L(n) asm volatile("s_waitcnt lgkmcnt(" #n ")" ::: "memory")
; #define PG8_BAR __builtin_amdgcn_s_barrier()
; #define PG8_SCHED __builtin_amdgcn_sched_barrier(0)
; template <class Epi, class Sched, bool ALIGN_EPI = false, bool SP2 = false>
; __device__ __forceinline__ void gemm_phase(PG8_LAS unsigned char* lds, const Gemm g, const Sched& S, const Epi& E) {
;     ...
;             PG8_WAIT_V(8); PG8_WAIT_L(0); PG8_BAR; PG8_MMA(1, 0, At, B0); PG8_MMA(1, 1, At, B1); PG8_BAR; PG8_SCHED;
;             PG8_LDB(B0, 1, 0); PG8_LDB(B1, 1, 1); PG8_SCHED; PG8_LDA(At, 1, 0); PG8_STAGE(PG8_SA(0, 1), a2 + hstep, voffA);
;             PG8_WAIT_V(8); PG8_WAIT_L(0); PG8_BAR; PG8_MMA(0, 0, At, B0); PG8_MMA(0, 1, At, B1); PG8_BAR; PG8_SCHED;
	s_setprio 1
	s_waitcnt lgkmcnt(0)
	v_mfma_f32_16x16x32_bf16 v[60:63], v[128:131], v[186:189], 0
	v_mfma_f32_16x16x32_bf16 v[56:59], v[136:139], v[186:189], 0
	v_mfma_f32_16x16x32_bf16 v[52:55], v[128:131], v[198:201], 0
	v_mfma_f32_16x16x32_bf16 v[48:51], v[136:139], v[198:201], 0
	v_mfma_f32_16x16x32_bf16 v[36:39], v[128:131], v[206:209], 0
	v_mfma_f32_16x16x32_bf16 v[32:35], v[136:139], v[206:209], 0
	v_mfma_f32_16x16x32_bf16 v[20:23], v[128:131], v[218:221], 0
	v_mfma_f32_16x16x32_bf16 v[16:19], v[136:139], v[218:221], 0
	v_mfma_f32_16x16x32_bf16 v[60:63], v[132:135], v[194:197], v[60:63]
	v_mfma_f32_16x16x32_bf16 v[56:59], v[140:143], v[194:197], v[56:59]
	v_mfma_f32_16x16x32_bf16 v[52:55], v[132:135], v[202:205], v[52:55]
	v_mfma_f32_16x16x32_bf16 v[48:51], v[140:143], v[202:205], v[48:51]
	v_mfma_f32_16x16x32_bf16 v[36:39], v[132:135], v[210:213], v[36:39]
	v_mfma_f32_16x16x32_bf16 v[32:35], v[140:143], v[210:213], v[32:35]
	v_mfma_f32_16x16x32_bf16 v[20:23], v[132:135], v[222:225], v[20:23]
	v_mfma_f32_16x16x32_bf16 v[16:19], v[140:143], v[222:225], v[16:19]
	s_setprio 0
	s_setprio 1
	v_mfma_f32_16x16x32_bf16 v[44:47], v[164:167], v[186:189], 0
	v_mfma_f32_16x16x32_bf16 v[40:43], v[178:181], v[186:189], 0
	v_mfma_f32_16x16x32_bf16 v[28:31], v[164:167], v[198:201], 0
	v_mfma_f32_16x16x32_bf16 v[24:27], v[178:181], v[198:201], 0
	v_mfma_f32_16x16x32_bf16 v[12:15], v[164:167], v[206:209], 0
	v_mfma_f32_16x16x32_bf16 v[8:11], v[178:181], v[206:209], 0
	v_mfma_f32_16x16x32_bf16 v[4:7], v[164:167], v[218:221], 0
	v_mfma_f32_16x16x32_bf16 v[0:3], v[178:181], v[218:221], 0
	v_mfma_f32_16x16x32_bf16 v[44:47], v[168:171], v[194:197], v[44:47]
	v_mfma_f32_16x16x32_bf16 v[40:43], v[182:185], v[194:197], v[40:43]
	v_mfma_f32_16x16x32_bf16 v[28:31], v[168:171], v[202:205], v[28:31]
	v_mfma_f32_16x16x32_bf16 v[24:27], v[182:185], v[202:205], v[24:27]
	v_mfma_f32_16x16x32_bf16 v[12:15], v[168:171], v[210:213], v[12:15]
	v_mfma_f32_16x16x32_bf16 v[8:11], v[182:185], v[210:213], v[8:11]
	v_mfma_f32_16x16x32_bf16 v[4:7], v[168:171], v[222:225], v[4:7]
	v_mfma_f32_16x16x32_bf16 v[0:3], v[182:185], v[222:225], v[0:3]
	s_setprio 0
	s_barrier
	s_add_i32 s70, 0, 0x18000
	s_add_i32 s71, 0, 0x1c000
	v_add_u32_e32 v140, s70, v173
	v_add_u32_e32 v182, s71, v173
	ds_read_b128 v[128:131], v140
	ds_read_b128 v[132:135], v140 offset:1024
	ds_read_b128 v[136:139], v140 offset:2048
	ds_read_b128 v[140:143], v140 offset:3072
	ds_read_b128 v[164:167], v182
	ds_read_b128 v[168:171], v182 offset:1024
	ds_read_b128 v[178:181], v182 offset:2048
	ds_read_b128 v[182:185], v182 offset:3072
	s_add_u32 s44, s44, 0x80000
	s_addc_u32 s45, s45, 0
	s_mov_b32 m0, s54
	v_lshl_add_u64 v[230:231], s[44:45], 0, v[150:151]
	ds_read_b128 v[186:189], v177 offset:32768
	ds_read_b128 v[194:197], v177 offset:33792
	ds_read_b128 v[198:201], v177 offset:34816
	ds_read_b128 v[202:205], v177 offset:35840
	ds_read_b128 v[206:209], v177 offset:36864
	ds_read_b128 v[210:213], v177 offset:37888
	ds_read_b128 v[218:221], v177 offset:38912
	ds_read_b128 v[222:225], v177 offset:39936
	global_load_lds_dwordx4 v[230:231], off
	v_lshl_add_u64 v[230:231], s[44:45], 0, v[146:147]
	s_mov_b32 m0, s55
	s_nop 0
	global_load_lds_dwordx4 v[230:231], off
	s_waitcnt vmcnt(8)
	s_waitcnt lgkmcnt(0)
	s_barrier
	s_setprio 1
	s_waitcnt lgkmcnt(0)
	v_mfma_f32_16x16x32_bf16 v[124:127], v[128:131], v[186:189], v[124:127]
	v_mfma_f32_16x16x32_bf16 v[120:123], v[136:139], v[186:189], v[120:123]
	v_mfma_f32_16x16x32_bf16 v[116:119], v[128:131], v[198:201], v[116:119]
	v_mfma_f32_16x16x32_bf16 v[112:115], v[136:139], v[198:201], v[112:115]
	v_mfma_f32_16x16x32_bf16 v[100:103], v[128:131], v[206:209], v[100:103]
	v_mfma_f32_16x16x32_bf16 v[96:99], v[136:139], v[206:209], v[96:99]
	v_mfma_f32_16x16x32_bf16 v[84:87], v[128:131], v[218:221], v[84:87]
	v_mfma_f32_16x16x32_bf16 v[80:83], v[136:139], v[218:221], v[80:83]
	v_mfma_f32_16x16x32_bf16 v[124:127], v[132:135], v[194:197], v[124:127]
	v_mfma_f32_16x16x32_bf16 v[120:123], v[140:143], v[194:197], v[120:123]
	v_mfma_f32_16x16x32_bf16 v[116:119], v[132:135], v[202:205], v[116:119]
	v_mfma_f32_16x16x32_bf16 v[112:115], v[140:143], v[202:205], v[112:115]
	v_mfma_f32_16x16x32_bf16 v[100:103], v[132:135], v[210:213], v[100:103]
	v_mfma_f32_16x16x32_bf16 v[96:99], v[140:143], v[210:213], v[96:99]
	v_mfma_f32_16x16x32_bf16 v[84:87], v[132:135], v[222:225], v[84:87]
	v_mfma_f32_16x16x32_bf16 v[80:83], v[140:143], v[222:225], v[80:83]
	s_setprio 0
	s_setprio 1
	v_mfma_f32_16x16x32_bf16 v[108:111], v[164:167], v[186:189], v[108:111]
	v_mfma_f32_16x16x32_bf16 v[104:107], v[178:181], v[186:189], v[104:107]
	v_mfma_f32_16x16x32_bf16 v[92:95], v[164:167], v[198:201], v[92:95]
	v_mfma_f32_16x16x32_bf16 v[88:91], v[178:181], v[198:201], v[88:91]
	v_mfma_f32_16x16x32_bf16 v[76:79], v[164:167], v[206:209], v[76:79]
	v_mfma_f32_16x16x32_bf16 v[72:75], v[178:181], v[206:209], v[72:75]
	v_mfma_f32_16x16x32_bf16 v[68:71], v[164:167], v[218:221], v[68:71]
	v_mfma_f32_16x16x32_bf16 v[64:67], v[178:181], v[218:221], v[64:67]
	v_mfma_f32_16x16x32_bf16 v[108:111], v[168:171], v[194:197], v[108:111]
	v_mfma_f32_16x16x32_bf16 v[104:107], v[182:185], v[194:197], v[104:107]
	v_mfma_f32_16x16x32_bf16 v[92:95], v[168:171], v[202:205], v[92:95]
	v_mfma_f32_16x16x32_bf16 v[88:91], v[182:185], v[202:205], v[88:91]
	v_mfma_f32_16x16x32_bf16 v[76:79], v[168:171], v[210:213], v[76:79]
	v_mfma_f32_16x16x32_bf16 v[72:75], v[182:185], v[210:213], v[72:75]
	v_mfma_f32_16x16x32_bf16 v[68:71], v[168:171], v[222:225], v[68:71]
	v_mfma_f32_16x16x32_bf16 v[64:67], v[182:185], v[222:225], v[64:67]
	s_setprio 0
	s_barrier
; #define PG8_STAGE(bufoff, gbase, voff) do { _Pragma("unroll") for (int _i = 0; _i < 2; ++_i) \
;         __builtin_amdgcn_global_load_lds((const unsigned*)((const char*)(gbase) + (voff)[_i]), (PG8_LAS unsigned*)(lds + (bufoff) + ldsw + _i * 8192), 16, 0, 0); } while (0)
; #define PG8_LDA(dst, b, h) do { _Pragma("unroll") for (int m = 0; m < 4; ++m) _Pragma("unroll") for (int k = 0; k < 2; ++k) dst[m][k] = *(const PG8_LAS bf16x8*)(lds + PG8_SA(b, h) + aoff + m * 2048 + k * 1024); } while (0)
; #define PG8_MMA(ai, bj, At, Bt) do { __builtin_amdgcn_s_setprio(1); _Pragma("unroll") for (int m = 0; m < 4; ++m) _Pragma("unroll") for (int n = 0; n < 2; ++n) _Pragma("unroll") for (int k = 0; k < 2; ++k) \
;         acc[ai][bj][m][n] = __builtin_amdgcn_mfma_f32_16x16x32_bf16(Bt[n][k], At[m][k], acc[ai][bj][m][n], 0, 0, 0); __builtin_amdgcn_s_setprio(0); } while (0)
; #define PG8_WAIT_V(n) asm volatile("s_waitcnt vmcnt(" #n ")" ::: "memory")
; #define PG8_WAIT_L(n) asm volatile("s_waitcnt lgkmcnt(" #n ")" ::: "memory")
; #define PG8_BAR __builtin_amdgcn_s_barrier()
; #define PG8_SCHED __builtin_amdgcn_sched_barrier(0)
; template <class Epi, class Sched, bool ALIGN_EPI = false, bool SP2 = false>
; __device__ __forceinline__ void gemm_phase(PG8_LAS unsigned char* lds, const Gemm g, const Sched& S, const Epi& E) {
;     ...
;         for (int t = 0; t < nt; t += 2) {
;     ...
;             PG8_LDA(At, 1, 1); PG8_STAGE(PG8_SB(1, 0), b3, voffB); PG8_STAGE(PG8_SB(1, 1), b3 + hstep, voffB); PG8_STAGE(PG8_SA(1, 0), a3, voffA);
;             PG8_WAIT_V(8); PG8_WAIT_L(0); PG8_BAR; PG8_MMA(1, 0, At, B0); PG8_MMA(1, 1, At, B1); PG8_BAR; PG8_SCHED;
	s_add_i32 s44, s70, s50
	v_lshl_add_u64 v[190:191], v[190:191], 0, s[22:23]
	s_mov_b32 m0, s44
	ds_read_b128 v[186:189], v177 offset:49152
	ds_read_b128 v[194:197], v177 offset:50176
	ds_read_b128 v[198:201], v177 offset:51200
	ds_read_b128 v[202:205], v177 offset:52224
	ds_read_b128 v[206:209], v177 offset:53248
	ds_read_b128 v[210:213], v177 offset:54272
	ds_read_b128 v[218:221], v177 offset:55296
	ds_read_b128 v[222:225], v177 offset:56320
	global_load_lds_dwordx4 v[190:191], off
	s_add_i32 m0, s44, 0x2000
	s_add_u32 s42, s42, 0x80080
	v_lshl_add_u64 v[190:191], v[214:215], 0, s[22:23]
	s_addc_u32 s43, s43, 0
	s_add_i32 s44, s71, s50
	global_load_lds_dwordx4 v[190:191], off
	v_lshl_add_u64 v[190:191], s[42:43], 0, v[148:149]
	s_mov_b32 m0, s44
	s_nop 0
	global_load_lds_dwordx4 v[190:191], off
	v_lshl_add_u64 v[190:191], s[42:43], 0, v[144:145]
	s_add_i32 m0, s44, 0x2000
	s_nop 0
	global_load_lds_dwordx4 v[190:191], off
	v_lshl_add_u64 v[190:191], v[226:227], 0, s[22:23]
	s_mov_b32 m0, s59
	s_nop 0
	global_load_lds_dwordx4 v[190:191], off
	v_lshl_add_u64 v[190:191], v[228:229], 0, s[22:23]
	s_mov_b32 m0, s60
	s_nop 0
	global_load_lds_dwordx4 v[190:191], off
	s_waitcnt vmcnt(8)
	s_waitcnt lgkmcnt(0)
	s_barrier
	s_setprio 1
	s_waitcnt lgkmcnt(0)
	v_mfma_f32_16x16x32_bf16 v[60:63], v[128:131], v[186:189], v[60:63]
	v_mfma_f32_16x16x32_bf16 v[56:59], v[136:139], v[186:189], v[56:59]
	v_mfma_f32_16x16x32_bf16 v[52:55], v[128:131], v[198:201], v[52:55]
	v_mfma_f32_16x16x32_bf16 v[48:51], v[136:139], v[198:201], v[48:51]
	v_mfma_f32_16x16x32_bf16 v[36:39], v[128:131], v[206:209], v[36:39]
	v_mfma_f32_16x16x32_bf16 v[32:35], v[136:139], v[206:209], v[32:35]
	v_mfma_f32_16x16x32_bf16 v[20:23], v[128:131], v[218:221], v[20:23]
	v_mfma_f32_16x16x32_bf16 v[16:19], v[136:139], v[218:221], v[16:19]
	v_mfma_f32_16x16x32_bf16 v[60:63], v[132:135], v[194:197], v[60:63]
	v_mfma_f32_16x16x32_bf16 v[56:59], v[140:143], v[194:197], v[56:59]
	v_mfma_f32_16x16x32_bf16 v[52:55], v[132:135], v[202:205], v[52:55]
	v_mfma_f32_16x16x32_bf16 v[48:51], v[140:143], v[202:205], v[48:51]
	v_mfma_f32_16x16x32_bf16 v[36:39], v[132:135], v[210:213], v[36:39]
	v_mfma_f32_16x16x32_bf16 v[32:35], v[140:143], v[210:213], v[32:35]
	v_mfma_f32_16x16x32_bf16 v[20:23], v[132:135], v[222:225], v[20:23]
	v_mfma_f32_16x16x32_bf16 v[16:19], v[140:143], v[222:225], v[16:19]
	s_setprio 0
	s_setprio 1
	v_mfma_f32_16x16x32_bf16 v[44:47], v[164:167], v[186:189], v[44:47]
	v_mfma_f32_16x16x32_bf16 v[40:43], v[178:181], v[186:189], v[40:43]
	v_mfma_f32_16x16x32_bf16 v[28:31], v[164:167], v[198:201], v[28:31]
	v_mfma_f32_16x16x32_bf16 v[24:27], v[178:181], v[198:201], v[24:27]
	v_mfma_f32_16x16x32_bf16 v[12:15], v[164:167], v[206:209], v[12:15]
	v_mfma_f32_16x16x32_bf16 v[8:11], v[178:181], v[206:209], v[8:11]
	v_mfma_f32_16x16x32_bf16 v[4:7], v[164:167], v[218:221], v[4:7]
	v_mfma_f32_16x16x32_bf16 v[0:3], v[178:181], v[218:221], v[0:3]
	v_mfma_f32_16x16x32_bf16 v[44:47], v[168:171], v[194:197], v[44:47]
	v_mfma_f32_16x16x32_bf16 v[40:43], v[182:185], v[194:197], v[40:43]
	v_mfma_f32_16x16x32_bf16 v[28:31], v[168:171], v[202:205], v[28:31]
	v_mfma_f32_16x16x32_bf16 v[24:27], v[182:185], v[202:205], v[24:27]
	v_mfma_f32_16x16x32_bf16 v[12:15], v[168:171], v[210:213], v[12:15]
	v_mfma_f32_16x16x32_bf16 v[8:11], v[182:185], v[210:213], v[8:11]
	v_mfma_f32_16x16x32_bf16 v[4:7], v[168:171], v[222:225], v[4:7]
	v_mfma_f32_16x16x32_bf16 v[0:3], v[182:185], v[222:225], v[0:3]
	s_setprio 0
	s_barrier
	s_add_i32 s69, s69, 2
	s_add_u32 s40, s40, 0x100
	s_addc_u32 s41, s41, 0
	s_add_u32 s67, s67, 0x100
	s_addc_u32 s68, s68, 0
	s_cmp_gt_u32 s69, 29

; #define PG8_WAIT_V(n) asm volatile("s_waitcnt vmcnt(" #n ")" ::: "memory")
; #define PG8_BAR __builtin_amdgcn_s_barrier()
; #define WSP(off) ((bf16*)((unsigned char*)kargp(25) + (off)))
; template <class Epi, class Sched, bool ALIGN_EPI = false, bool SP2 = false>
; __device__ __forceinline__ void gemm_phase(PG8_LAS unsigned char* lds, const Gemm g, const Sched& S, const Epi& E) {
;     ...
;     const int tid = tid_, wid = __builtin_amdgcn_readfirstlane(tid >> 6), lane = tid & 63, wr = wid >> 2, wc = wid & 3, fr = lane & 15, fq = lane >> 4;
;     const int K = g.K, nt = K / BK;
;     unsigned voffA[2], voffB[2];
; #pragma unroll
;     for (int i = 0; i < 2; ++i) { int R, C; stage_rc(tid * 16 + i * 8192, R, C); const int Rb = Epi::PERM ? ((R & ~31) + perm32(R & 31)) : R;
;         voffA[i] = (unsigned)(R * K + C) * 2u; voffB[i] = (unsigned)(Rb * K + C) * 2u; }
;     const size_t kstep = (size_t)(BK * 2);
;     const size_t hstep = (size_t)HALF * K * 2;
;     const size_t tstep = 2 * hstep;
;     const unsigned ldsw = (unsigned)wid * 1024u;
;     const int aoff = lds_byte(wr * 64 + fr, fq * 8), boff = lds_byte(wc * 32 + fr, fq * 8);
;     ...
;     Unit cur, nxt; int ui = 0;
;     if (!S.next(0, cur)) return;
;     f32x4 acc[2][2][4][2];
; #pragma unroll
;     for (int a = 0; a < 2; ++a)
; #pragma unroll
;         for (int b = 0; b < 2; ++b)
; #pragma unroll
;             for (int m = 0; m < 4; ++m)
; #pragma unroll
;                 for (int n = 0; n < 2; ++n) acc[a][b][m][n] = (f32x4){0.f, 0.f, 0.f, 0.f};
;     bf16x8 At[4][2], B0[2][2], B1[2][2];
;     const char* cA = (const char*)g.A + (size_t)cur.pm * tstep; const char* cB = (const char*)g.Bt + (size_t)cur.pn * tstep;
;     S.a_ready(cur);
;     if constexpr (SP2) {
;         PG8_STAGE(PG8_SB(0, 0), cB, voffB); PG8_STAGE(PG8_SB(0, 1), cB + hstep, voffB); PG8_STAGE(PG8_SA(0, 0), cA, voffA); PG8_STAGE(PG8_SA(0, 1), cA + hstep, voffA);
;         if (wr == 1) PG8_BAR;
;         PG8_WAIT_V(2); PG8_BAR;
; __global__ void __launch_bounds__(NTHR, 2) mega_fwd(Args args) {
;     ...
;         bf16* YC = WSP(WS_YC); bf16* OA = WSP(WS_OA); bf16* WC = WSP(WS_WC); bf16* WA = WSP(WS_WA); bf16* MG = WSP(WS_MG); bf16* GT = WSP(WS_GT);
;         pg8::StaticOrder S; S.init(T, DM, G, bx);
;         { pg8::Gemm g{YC, WC, T, DM, CW}; pg8::EpiMerge<false> E{MG, GT}; pg8::gemm_phase<pg8::EpiMerge<false>, pg8::StaticOrder, true, true>(L, g, S, E); }
.LBB0_540:
	s_or_b64 exec, exec, s[14:15]
	s_nop 0
	s_nop 0
	s_nop 0
	s_nop 0
	s_nop 0
	s_nop 0
	s_nop 0
	s_nop 0
	s_nop 0
	s_nop 0
	s_nop 0
	s_nop 0
	s_nop 0
	s_nop 0
	s_cmpk_lt_i32 s2, 0x400
	s_mov_b64 s[22:23], s[0:1]
	s_mov_b64 s[16:17], s[0:1]
	s_mov_b64 s[24:25], s[0:1]
	s_mov_b64 s[18:19], s[0:1]
	s_mov_b64 s[14:15], s[0:1]
	s_waitcnt lgkmcnt(0)
	s_barrier
	s_cselect_b64 s[48:49], -1, 0
	s_lshr_b32 s13, s33, 29
	s_add_i32 s13, s2, s13
	s_load_dwordx2 s[14:15], s[14:15], 0xc8
	s_ashr_i32 s56, s13, 3
	s_and_b32 s13, s13, -8
	s_load_dwordx2 s[20:21], s[16:17], 0xc8
	s_nop 0
	s_load_dwordx2 s[18:19], s[18:19], 0xc8
	s_mov_b64 s[16:17], s[0:1]
	s_sub_i32 s59, s2, s13
	s_cmp_lt_i32 s59, 0
	s_load_dwordx2 s[16:17], s[16:17], 0xc8
	s_cselect_b64 s[42:43], -1, 0
	s_lshl_b32 s57, s59, 7
	s_waitcnt lgkmcnt(0)
	s_add_u32 s14, s14, 0x2f800000
	s_addc_u32 s15, s15, 0
	s_waitcnt vmcnt(27)
	v_mov_b32_e32 v14, v216
	s_cmpk_gt_i32 s2, 0x3ff
	s_mul_i32 s58, s59, 0x81
	s_nop 0
	v_readfirstlane_b32 s28, v14
	s_cbranch_scc1 .LBB0_560
	v_lshlrev_b32_e32 v0, 4, v14
	v_add_u32_e32 v1, 0x2000, v0
	v_ashrrev_i32_e32 v2, 31, v1
	v_lshrrev_b32_e32 v2, 22, v2
	v_add_u32_e32 v2, v1, v2
	v_ashrrev_i32_e32 v8, 10, v2
	v_mul_i32_i24_e32 v2, 0x400, v8
	v_sub_u32_e32 v1, v1, v2
	v_lshrrev_b32_e32 v2, 4, v1
	v_bitop3_b32 v1, v2, v1, 32 bitop3:0x6c
	v_ashrrev_i32_e32 v2, 31, v1
	s_load_dwordx2 s[22:23], s[22:23], 0xc8
	s_nop 0
	s_load_dwordx2 s[24:25], s[24:25], 0xc8
	v_lshrrev_b32_e32 v2, 26, v2
	v_add_u32_e32 v2, v1, v2
	v_lshlrev_b32_e32 v3, 3, v8
	v_ashrrev_i32_e32 v9, 6, v2
	v_and_b32_e32 v3, -16, v3
	v_add_u32_e32 v3, v9, v3
	s_waitcnt lgkmcnt(0)
	s_add_u32 s13, s22, 0x3b800000
	v_and_b32_e32 v4, 3, v9
	s_mov_b32 s22, 0x1fffe0
	v_lshrrev_b32_e32 v5, 2, v3
	v_lshlrev_b32_e32 v6, 1, v3
	v_and_b32_e32 v2, 0xc0, v2
	v_and_or_b32 v4, v3, s22, v4
	v_and_b32_e32 v5, 4, v5
	v_and_b32_e32 v6, 24, v6
	v_sub_u32_e32 v1, v1, v2
	v_mov_b32_e32 v2, 1
	v_or3_b32 v4, v4, v5, v6
	v_lshlrev_b32_e32 v5, 5, v8
	v_ashrrev_i16_sdwa v1, v2, sext(v1) dst_sel:DWORD dst_unused:UNUSED_PAD src0_sel:DWORD src1_sel:BYTE_0
	v_and_b32_e32 v5, 32, v5
	v_bfe_i32 v10, v1, 0, 16
	v_add_lshl_u32 v1, v5, v10, 1
	s_waitcnt vmcnt(6)
	v_lshl_add_u32 v152, v4, 11, v1
	v_lshl_add_u32 v154, v3, 11, v1
	v_bfe_i32 v1, v14, 27, 1
	v_lshrrev_b32_e32 v1, 22, v1
	v_add_u32_e32 v1, v0, v1
	v_and_b32_e32 v1, 0xfffffc00, v1
	v_sub_u32_e32 v0, v0, v1
	v_lshrrev_b32_e32 v1, 4, v0
	v_ashrrev_i32_e32 v3, 31, v14
	v_bitop3_b32 v0, v1, v0, 32 bitop3:0x6c
	v_lshrrev_b32_e32 v3, 26, v3
	v_ashrrev_i32_e32 v1, 31, v0
	v_add_u32_e32 v3, v14, v3
	s_addc_u32 s47, s23, 0
	v_lshrrev_b32_e32 v1, 26, v1
	v_ashrrev_i32_e32 v12, 6, v3
	s_add_u32 s60, s24, 0x2600000
	v_add_u32_e32 v1, v0, v1
	v_lshlrev_b32_e32 v3, 3, v12
	s_addc_u32 s61, s25, 0
	s_ashr_i32 s26, s28, 6
	v_ashrrev_i32_e32 v11, 6, v1
	v_and_b32_e32 v3, -16, v3
	s_ashr_i32 s27, s28, 8
	s_lshl_b32 s62, s26, 10
	v_add_u32_e32 v3, v11, v3
	v_and_b32_e32 v4, 3, v11
	v_and_or_b32 v4, v3, s22, v4
	s_and_b64 s[22:23], s[42:43], exec
	s_cselect_b32 s22, s58, s57
	s_add_i32 s22, s22, s56
	s_ashr_i32 s23, s22, 31
	s_lshr_b32 s23, s23, 27
	s_add_i32 s23, s22, s23
	s_ashr_i32 s24, s23, 5
	s_and_b32 s23, s23, 0xffe0
	s_sub_i32 s22, s22, s23
	s_bfe_i32 s23, s22, 0x80000
	s_bfe_u32 s23, s23, 0x2000d
	s_add_i32 s23, s22, s23
	s_lshl_b32 s25, s24, 2
	s_bfe_i32 s24, s23, 0x80000
	s_and_b32 s23, s23, 0xfc
	s_sub_i32 s22, s22, s23
	s_sext_i32_i16 s24, s24
	s_sext_i32_i8 s22, s22
	v_lshrrev_b32_e32 v5, 2, v3
	v_lshlrev_b32_e32 v6, 1, v3
	v_and_b32_e32 v1, 0xc0, v1
	s_lshr_b32 s24, s24, 2
	s_add_i32 s44, s25, s22
	v_and_b32_e32 v5, 4, v5
	v_and_b32_e32 v6, 24, v6
	v_sub_u32_e32 v0, v0, v1
	s_ashr_i32 s45, s44, 31
	s_bfe_i64 s[30:31], s[24:25], 0x100000
	v_or3_b32 v4, v4, v5, v6
	v_lshlrev_b32_e32 v5, 5, v12
	v_ashrrev_i16_sdwa v0, v2, sext(v0) dst_sel:DWORD dst_unused:UNUSED_PAD src0_sel:DWORD src1_sel:BYTE_0
	s_lshl_b64 s[22:23], s[44:45], 19
	s_lshl_b64 s[30:31], s[30:31], 19
	v_and_b32_e32 v5, 32, v5
	v_bfe_i32 v13, v0, 0, 16
	s_add_u32 s52, s60, s30
	v_add_lshl_u32 v0, v5, v13, 1
	s_addc_u32 s53, s61, s31
	s_add_i32 s63, s62, 0
	v_lshl_add_u32 v156, v4, 11, v0
	s_add_i32 m0, s63, 0x10000
	v_lshl_add_u32 v158, v3, 11, v0
	global_load_lds_dwordx4 v156, s[52:53]
	s_add_i32 m0, s63, 0x12000
	s_add_u32 s30, s52, 0x40000
	global_load_lds_dwordx4 v152, s[52:53]
	s_addc_u32 s31, s53, 0
	s_add_i32 m0, s63, 0x14000
	v_mov_b32_e32 v157, 0
	global_load_lds_dwordx4 v156, s[30:31]
	s_add_i32 m0, s63, 0x16000
	s_add_u32 s50, s13, s22
	s_addc_u32 s51, s47, s23
	s_add_i32 s64, s63, 0x2000
	global_load_lds_dwordx4 v152, s[30:31]
	s_mov_b32 m0, s63
	s_add_u32 s22, s50, 0x40000
	global_load_lds_dwordx4 v158, s[50:51]
	s_mov_b32 m0, s64
	s_addc_u32 s23, s51, 0
	s_add_i32 s65, s63, 0x4000
	global_load_lds_dwordx4 v154, s[50:51]
	s_mov_b32 m0, s65
	s_add_i32 s66, s63, 0x6000
	global_load_lds_dwordx4 v158, s[22:23]
	s_mov_b32 m0, s66
	v_mov_b32_e32 v153, v157
	global_load_lds_dwordx4 v154, s[22:23]
	v_mov_b32_e32 v159, v157
	v_mov_b32_e32 v155, v157
	s_cmp_eq_u32 s27, 1
	v_lshl_add_u64 v[6:7], s[52:53], 0, v[156:157]
	v_lshl_add_u64 v[4:5], s[52:53], 0, v[152:153]
	v_lshl_add_u64 v[0:1], s[50:51], 0, v[158:159]
	s_cselect_b64 s[22:23], -1, 0
	s_cmp_lg_u32 s27, 1
	v_lshl_add_u64 v[2:3], s[50:51], 0, v[154:155]
	s_cbranch_scc1 .LBB0_543
	s_barrier

; #define PG8_STAGE(bufoff, gbase, voff) do { _Pragma("unroll") for (int _i = 0; _i < 2; ++_i) \
;         __builtin_amdgcn_global_load_lds((const unsigned*)((const char*)(gbase) + (voff)[_i]), (PG8_LAS unsigned*)(lds + (bufoff) + ldsw + _i * 8192), 16, 0, 0); } while (0)
; #define PG8_LDA(dst, b, h) do { _Pragma("unroll") for (int m = 0; m < 4; ++m) _Pragma("unroll") for (int k = 0; k < 2; ++k) dst[m][k] = *(const PG8_LAS bf16x8*)(lds + PG8_SA(b, h) + aoff + m * 2048 + k * 1024); } while (0)
; template <class Epi, class Sched, bool ALIGN_EPI = false, bool SP2 = false>
; __device__ __forceinline__ void gemm_phase(PG8_LAS unsigned char* lds, const Gemm g, const Sched& S, const Epi& E) {
;     ...
;         const bool has_next = S.next(ui + 1, nxt);
;         const char* nA = has_next ? (const char*)g.A + (size_t)nxt.pm * tstep : cA; const char* nB = has_next ? (const char*)g.Bt + (size_t)nxt.pn * tstep : cB;
;         for (int t = 0; t < nt; t += 2) {
;             const bool last = (t == nt - 2);
;             const char* a1 = cA + (size_t)(t + 1) * kstep;
;             const char* a2 = last ? nA : cA + (size_t)(t + 2) * kstep; const char* b2 = last ? nB : cB + (size_t)(t + 2) * kstep;
;             const char* a3 = a2 + kstep; const char* b3 = b2 + kstep;
;             if (last && has_next) S.a_ready(nxt);
;             if constexpr (SP2) {
;             PG8_LDB(B0, 0, 0); PG8_LDB(B1, 0, 1); PG8_SCHED; PG8_LDA(At, 0, 0); PG8_STAGE(PG8_SA(1, 1), a1 + hstep, voffA);
;             PG8_WAIT_V(8); PG8_WAIT_L(0); PG8_BAR; PG8_MMA(0, 0, At, B0); PG8_MMA(0, 1, At, B1); PG8_BAR; PG8_SCHED;
;             PG8_LDA(At, 0, 1); PG8_STAGE(PG8_SB(0, 0), b2, voffB); PG8_STAGE(PG8_SB(0, 1), b2 + hstep, voffB); PG8_STAGE(PG8_SA(0, 0), a2, voffA);
;             PG8_WAIT_V(8); PG8_WAIT_L(0); PG8_BAR; PG8_MMA(1, 0, At, B0); PG8_MMA(1, 1, At, B1); PG8_BAR; PG8_SCHED;
;             PG8_LDB(B0, 1, 0); PG8_LDB(B1, 1, 1); PG8_SCHED; PG8_LDA(At, 1, 0); PG8_STAGE(PG8_SA(0, 1), a2 + hstep, voffA);
;             PG8_WAIT_V(8); PG8_WAIT_L(0); PG8_BAR; PG8_MMA(0, 0, At, B0); PG8_MMA(0, 1, At, B1); PG8_BAR; PG8_SCHED;
;             PG8_LDA(At, 1, 1); PG8_STAGE(PG8_SB(1, 0), b3, voffB); PG8_STAGE(PG8_SB(1, 1), b3 + hstep, voffB); PG8_STAGE(PG8_SA(1, 0), a3, voffA);
;             PG8_WAIT_V(8); PG8_WAIT_L(0); PG8_BAR; PG8_MMA(1, 0, At, B0); PG8_MMA(1, 1, At, B1); PG8_BAR; PG8_SCHED;
.LBB0_552:
	s_ashr_i32 s35, s34, 31
	s_lshl_b64 s[36:37], s[34:35], 19
	s_add_u32 s36, s13, s36
	s_addc_u32 s37, s47, s37
	s_and_b64 s[40:41], s[38:39], exec
	s_cselect_b32 s35, s37, s51
	s_cselect_b32 s72, s36, s50
	s_ashr_i32 s31, s30, 31
	s_lshl_b64 s[40:41], s[30:31], 19
	s_add_u32 s40, s60, s40
	s_addc_u32 s41, s61, s41
	s_and_b64 s[54:55], s[38:39], exec
	s_cselect_b32 s31, s41, s53
	s_cselect_b32 s73, s40, s52
	s_add_u32 s50, s50, 0x40080
	s_addc_u32 s51, s51, 0
	s_add_u32 s74, s52, 0x100
	s_addc_u32 s75, s53, 0
	s_mov_b32 s76, -2
	s_waitcnt vmcnt(0)
	ds_read_b128 v[128:131], v181
	ds_read_b128 v[132:135], v181 offset:1024
	ds_read_b128 v[136:139], v181 offset:2048
	ds_read_b128 v[140:143], v181 offset:3072
	ds_read_b128 v[144:147], v182
	ds_read_b128 v[148:151], v182 offset:1024
	ds_read_b128 v[168:171], v182 offset:2048
	ds_read_b128 v[172:175], v182 offset:3072
	s_add_u32 s52, s50, 0xfffc0080
	s_addc_u32 s53, s51, -1
	s_cmp_eq_u32 s76, 12
	s_cselect_b32 s55, s35, s53
	s_cselect_b32 s54, s72, s52
	s_cselect_b32 s53, s31, s75
	s_cselect_b32 s52, s73, s74
	v_lshl_add_u64 v[176:177], s[50:51], 0, v[160:161]
	s_add_i32 m0, s63, 0xc000
	ds_read_b128 v[184:187], v183
	ds_read_b128 v[188:191], v183 offset:1024
	ds_read_b128 v[194:197], v183 offset:2048
	ds_read_b128 v[198:201], v183 offset:3072
	ds_read_b128 v[202:205], v183 offset:4096
	ds_read_b128 v[206:209], v183 offset:5120
	ds_read_b128 v[210:213], v183 offset:6144
	ds_read_b128 v[218:221], v183 offset:7168
	global_load_lds_dwordx4 v[176:177], off
	v_lshl_add_u64 v[176:177], s[50:51], 0, v[162:163]
	s_add_i32 m0, s63, 0xe000
	s_nop 0
	global_load_lds_dwordx4 v[176:177], off
	s_waitcnt vmcnt(8)
	s_waitcnt lgkmcnt(0)
	s_barrier
	s_setprio 1
	s_waitcnt lgkmcnt(0)
	v_mfma_f32_16x16x32_bf16 v[124:127], v[128:131], v[184:187], 0
	v_mfma_f32_16x16x32_bf16 v[120:123], v[136:139], v[184:187], 0
	v_mfma_f32_16x16x32_bf16 v[108:111], v[128:131], v[194:197], 0
	v_mfma_f32_16x16x32_bf16 v[104:107], v[136:139], v[194:197], 0
	v_mfma_f32_16x16x32_bf16 v[96:99], v[128:131], v[202:205], 0
	v_mfma_f32_16x16x32_bf16 v[88:91], v[136:139], v[202:205], 0
	v_mfma_f32_16x16x32_bf16 v[80:83], v[128:131], v[210:213], 0
	v_mfma_f32_16x16x32_bf16 v[72:75], v[136:139], v[210:213], 0
	v_mfma_f32_16x16x32_bf16 v[124:127], v[132:135], v[188:191], v[124:127]
	v_mfma_f32_16x16x32_bf16 v[120:123], v[140:143], v[188:191], v[120:123]
	v_mfma_f32_16x16x32_bf16 v[108:111], v[132:135], v[198:201], v[108:111]
	v_mfma_f32_16x16x32_bf16 v[104:107], v[140:143], v[198:201], v[104:107]
	v_mfma_f32_16x16x32_bf16 v[96:99], v[132:135], v[206:209], v[96:99]
	v_mfma_f32_16x16x32_bf16 v[88:91], v[140:143], v[206:209], v[88:91]
	v_mfma_f32_16x16x32_bf16 v[80:83], v[132:135], v[218:221], v[80:83]
	v_mfma_f32_16x16x32_bf16 v[72:75], v[140:143], v[218:221], v[72:75]
	s_setprio 0
	s_setprio 1
	v_mfma_f32_16x16x32_bf16 v[116:119], v[144:147], v[184:187], 0
	v_mfma_f32_16x16x32_bf16 v[112:115], v[168:171], v[184:187], 0
	v_mfma_f32_16x16x32_bf16 v[100:103], v[144:147], v[194:197], 0
	v_mfma_f32_16x16x32_bf16 v[92:95], v[168:171], v[194:197], 0
	v_mfma_f32_16x16x32_bf16 v[84:87], v[144:147], v[202:205], 0
	v_mfma_f32_16x16x32_bf16 v[76:79], v[168:171], v[202:205], 0
	v_mfma_f32_16x16x32_bf16 v[68:71], v[144:147], v[210:213], 0
	v_mfma_f32_16x16x32_bf16 v[64:67], v[168:171], v[210:213], 0
	v_mfma_f32_16x16x32_bf16 v[116:119], v[148:151], v[188:191], v[116:119]
	v_mfma_f32_16x16x32_bf16 v[112:115], v[172:175], v[188:191], v[112:115]
	v_mfma_f32_16x16x32_bf16 v[100:103], v[148:151], v[198:201], v[100:103]
	v_mfma_f32_16x16x32_bf16 v[92:95], v[172:175], v[198:201], v[92:95]
	v_mfma_f32_16x16x32_bf16 v[84:87], v[148:151], v[206:209], v[84:87]
	v_mfma_f32_16x16x32_bf16 v[76:79], v[172:175], v[206:209], v[76:79]
	v_mfma_f32_16x16x32_bf16 v[68:71], v[148:151], v[218:221], v[68:71]
	v_mfma_f32_16x16x32_bf16 v[64:67], v[172:175], v[218:221], v[64:67]
	s_setprio 0
	s_barrier
	s_add_i32 s77, s70, s62
	v_lshl_add_u64 v[176:177], s[52:53], 0, v[156:157]
	s_mov_b32 m0, s77
	ds_read_b128 v[184:187], v183 offset:16384
	ds_read_b128 v[188:191], v183 offset:17408
	ds_read_b128 v[194:197], v183 offset:18432
	ds_read_b128 v[198:201], v183 offset:19456
	ds_read_b128 v[202:205], v183 offset:20480
	ds_read_b128 v[206:209], v183 offset:21504
	ds_read_b128 v[210:213], v183 offset:22528
	ds_read_b128 v[218:221], v183 offset:23552
	global_load_lds_dwordx4 v[176:177], off
	s_add_i32 m0, s77, 0x2000
	s_add_u32 s78, s52, 0x40000
	v_lshl_add_u64 v[214:215], s[52:53], 0, v[152:153]
	s_addc_u32 s79, s53, 0
	s_add_i32 s77, s71, s62
	global_load_lds_dwordx4 v[214:215], off
	v_lshl_add_u64 v[222:223], s[78:79], 0, v[156:157]
	s_mov_b32 m0, s77
	v_lshl_add_u64 v[224:225], s[54:55], 0, v[154:155]
	global_load_lds_dwordx4 v[222:223], off
	v_lshl_add_u64 v[222:223], s[78:79], 0, v[152:153]
	s_add_i32 m0, s77, 0x2000
	s_nop 0
	global_load_lds_dwordx4 v[222:223], off
	v_lshl_add_u64 v[222:223], s[54:55], 0, v[158:159]
	s_mov_b32 m0, s63
	s_nop 0
	global_load_lds_dwordx4 v[222:223], off
	s_mov_b32 m0, s64
	s_nop 0
	global_load_lds_dwordx4 v[224:225], off
	s_waitcnt vmcnt(8)
	s_waitcnt lgkmcnt(0)
	s_barrier
; #define PG8_STAGE(bufoff, gbase, voff) do { _Pragma("unroll") for (int _i = 0; _i < 2; ++_i) \
;         __builtin_amdgcn_global_load_lds((const unsigned*)((const char*)(gbase) + (voff)[_i]), (PG8_LAS unsigned*)(lds + (bufoff) + ldsw + _i * 8192), 16, 0, 0); } while (0)
; #define PG8_LDA(dst, b, h) do { _Pragma("unroll") for (int m = 0; m < 4; ++m) _Pragma("unroll") for (int k = 0; k < 2; ++k) dst[m][k] = *(const PG8_LAS bf16x8*)(lds + PG8_SA(b, h) + aoff + m * 2048 + k * 1024); } while (0)
; #define PG8_LDB(dst, b, h) do { _Pragma("unroll") for (int n = 0; n < 2; ++n) _Pragma("unroll") for (int k = 0; k < 2; ++k) dst[n][k] = *(const PG8_LAS bf16x8*)(lds + PG8_SB(b, h) + boff + n * 2048 + k * 1024); } while (0)
; #define PG8_MMA(ai, bj, At, Bt) do { __builtin_amdgcn_s_setprio(1); _Pragma("unroll") for (int m = 0; m < 4; ++m) _Pragma("unroll") for (int n = 0; n < 2; ++n) _Pragma("unroll") for (int k = 0; k < 2; ++k) \
;         acc[ai][bj][m][n] = __builtin_amdgcn_mfma_f32_16x16x32_bf16(Bt[n][k], At[m][k], acc[ai][bj][m][n], 0, 0, 0); __builtin_amdgcn_s_setprio(0); } while (0)
; #define PG8_WAIT_V(n) asm volatile("s_waitcnt vmcnt(" #n ")" ::: "memory")
; #define PG8_WAIT_L(n) asm volatile("s_waitcnt lgkmcnt(" #n ")" ::: "memory")
; #define PG8_BAR __builtin_amdgcn_s_barrier()
; #define PG8_SCHED __builtin_amdgcn_sched_barrier(0)
; template <class Epi, class Sched, bool ALIGN_EPI = false, bool SP2 = false>
; __device__ __forceinline__ void gemm_phase(PG8_LAS unsigned char* lds, const Gemm g, const Sched& S, const Epi& E) {
;     ...
;             PG8_WAIT_V(8); PG8_WAIT_L(0); PG8_BAR; PG8_MMA(1, 0, At, B0); PG8_MMA(1, 1, At, B1); PG8_BAR; PG8_SCHED;
;             PG8_LDB(B0, 1, 0); PG8_LDB(B1, 1, 1); PG8_SCHED; PG8_LDA(At, 1, 0); PG8_STAGE(PG8_SA(0, 1), a2 + hstep, voffA);
;             PG8_WAIT_V(8); PG8_WAIT_L(0); PG8_BAR; PG8_MMA(0, 0, At, B0); PG8_MMA(0, 1, At, B1); PG8_BAR; PG8_SCHED;
	s_setprio 1
	s_waitcnt lgkmcnt(0)
	v_mfma_f32_16x16x32_bf16 v[60:63], v[128:131], v[184:187], 0
	v_mfma_f32_16x16x32_bf16 v[56:59], v[136:139], v[184:187], 0
	v_mfma_f32_16x16x32_bf16 v[48:51], v[128:131], v[194:197], 0
	v_mfma_f32_16x16x32_bf16 v[40:43], v[136:139], v[194:197], 0
	v_mfma_f32_16x16x32_bf16 v[32:35], v[128:131], v[202:205], 0
	v_mfma_f32_16x16x32_bf16 v[24:27], v[136:139], v[202:205], 0
	v_mfma_f32_16x16x32_bf16 v[16:19], v[128:131], v[210:213], 0
	v_mfma_f32_16x16x32_bf16 v[8:11], v[136:139], v[210:213], 0
	v_mfma_f32_16x16x32_bf16 v[60:63], v[132:135], v[188:191], v[60:63]
	v_mfma_f32_16x16x32_bf16 v[56:59], v[140:143], v[188:191], v[56:59]
	v_mfma_f32_16x16x32_bf16 v[48:51], v[132:135], v[198:201], v[48:51]
	v_mfma_f32_16x16x32_bf16 v[40:43], v[140:143], v[198:201], v[40:43]
	v_mfma_f32_16x16x32_bf16 v[32:35], v[132:135], v[206:209], v[32:35]
	v_mfma_f32_16x16x32_bf16 v[24:27], v[140:143], v[206:209], v[24:27]
	v_mfma_f32_16x16x32_bf16 v[16:19], v[132:135], v[218:221], v[16:19]
	v_mfma_f32_16x16x32_bf16 v[8:11], v[140:143], v[218:221], v[8:11]
	s_setprio 0
	s_setprio 1
	v_mfma_f32_16x16x32_bf16 v[52:55], v[144:147], v[184:187], 0
	v_mfma_f32_16x16x32_bf16 v[44:47], v[168:171], v[184:187], 0
	v_mfma_f32_16x16x32_bf16 v[36:39], v[144:147], v[194:197], 0
	v_mfma_f32_16x16x32_bf16 v[28:31], v[168:171], v[194:197], 0
	v_mfma_f32_16x16x32_bf16 v[20:23], v[144:147], v[202:205], 0
	v_mfma_f32_16x16x32_bf16 v[12:15], v[168:171], v[202:205], 0
	v_mfma_f32_16x16x32_bf16 v[4:7], v[144:147], v[210:213], 0
	v_mfma_f32_16x16x32_bf16 v[0:3], v[168:171], v[210:213], 0
	v_mfma_f32_16x16x32_bf16 v[52:55], v[148:151], v[188:191], v[52:55]
	v_mfma_f32_16x16x32_bf16 v[44:47], v[172:175], v[188:191], v[44:47]
	v_mfma_f32_16x16x32_bf16 v[36:39], v[148:151], v[198:201], v[36:39]
	v_mfma_f32_16x16x32_bf16 v[28:31], v[172:175], v[198:201], v[28:31]
	v_mfma_f32_16x16x32_bf16 v[20:23], v[148:151], v[206:209], v[20:23]
	v_mfma_f32_16x16x32_bf16 v[12:15], v[172:175], v[206:209], v[12:15]
	v_mfma_f32_16x16x32_bf16 v[4:7], v[148:151], v[218:221], v[4:7]
	v_mfma_f32_16x16x32_bf16 v[0:3], v[172:175], v[218:221], v[0:3]
	s_setprio 0
	s_barrier
	s_add_i32 s77, 0, 0x18000
	s_add_i32 s78, 0, 0x1c000
	v_add_u32_e32 v140, s77, v179
	v_add_u32_e32 v172, s78, v179
	ds_read_b128 v[128:131], v140
	ds_read_b128 v[132:135], v140 offset:1024
	ds_read_b128 v[136:139], v140 offset:2048
	ds_read_b128 v[140:143], v140 offset:3072
	ds_read_b128 v[144:147], v172
	ds_read_b128 v[148:151], v172 offset:1024
	ds_read_b128 v[168:171], v172 offset:2048
	ds_read_b128 v[172:175], v172 offset:3072
	s_add_u32 s54, s54, 0x40000
	s_addc_u32 s55, s55, 0
	s_mov_b32 m0, s65
	v_lshl_add_u64 v[226:227], s[54:55], 0, v[158:159]
	ds_read_b128 v[184:187], v183 offset:32768
	ds_read_b128 v[188:191], v183 offset:33792
	ds_read_b128 v[194:197], v183 offset:34816
	ds_read_b128 v[198:201], v183 offset:35840
	ds_read_b128 v[202:205], v183 offset:36864
	ds_read_b128 v[206:209], v183 offset:37888
	ds_read_b128 v[210:213], v183 offset:38912
	ds_read_b128 v[218:221], v183 offset:39936
	global_load_lds_dwordx4 v[226:227], off
	v_lshl_add_u64 v[226:227], s[54:55], 0, v[154:155]
	s_mov_b32 m0, s66
	s_nop 0
	global_load_lds_dwordx4 v[226:227], off
	s_waitcnt vmcnt(8)
	s_waitcnt lgkmcnt(0)
	s_barrier
	s_setprio 1
	s_waitcnt lgkmcnt(0)
	v_mfma_f32_16x16x32_bf16 v[124:127], v[128:131], v[184:187], v[124:127]
	v_mfma_f32_16x16x32_bf16 v[120:123], v[136:139], v[184:187], v[120:123]
	v_mfma_f32_16x16x32_bf16 v[108:111], v[128:131], v[194:197], v[108:111]
	v_mfma_f32_16x16x32_bf16 v[104:107], v[136:139], v[194:197], v[104:107]
	v_mfma_f32_16x16x32_bf16 v[96:99], v[128:131], v[202:205], v[96:99]
	v_mfma_f32_16x16x32_bf16 v[88:91], v[136:139], v[202:205], v[88:91]
	v_mfma_f32_16x16x32_bf16 v[80:83], v[128:131], v[210:213], v[80:83]
	v_mfma_f32_16x16x32_bf16 v[72:75], v[136:139], v[210:213], v[72:75]
	v_mfma_f32_16x16x32_bf16 v[124:127], v[132:135], v[188:191], v[124:127]
	v_mfma_f32_16x16x32_bf16 v[120:123], v[140:143], v[188:191], v[120:123]
	v_mfma_f32_16x16x32_bf16 v[108:111], v[132:135], v[198:201], v[108:111]
	v_mfma_f32_16x16x32_bf16 v[104:107], v[140:143], v[198:201], v[104:107]
	v_mfma_f32_16x16x32_bf16 v[96:99], v[132:135], v[206:209], v[96:99]
	v_mfma_f32_16x16x32_bf16 v[88:91], v[140:143], v[206:209], v[88:91]
	v_mfma_f32_16x16x32_bf16 v[80:83], v[132:135], v[218:221], v[80:83]
	v_mfma_f32_16x16x32_bf16 v[72:75], v[140:143], v[218:221], v[72:75]
	s_setprio 0
	s_setprio 1
	v_mfma_f32_16x16x32_bf16 v[116:119], v[144:147], v[184:187], v[116:119]
	v_mfma_f32_16x16x32_bf16 v[112:115], v[168:171], v[184:187], v[112:115]
	v_mfma_f32_16x16x32_bf16 v[100:103], v[144:147], v[194:197], v[100:103]
	v_mfma_f32_16x16x32_bf16 v[92:95], v[168:171], v[194:197], v[92:95]
	v_mfma_f32_16x16x32_bf16 v[84:87], v[144:147], v[202:205], v[84:87]
	v_mfma_f32_16x16x32_bf16 v[76:79], v[168:171], v[202:205], v[76:79]
	v_mfma_f32_16x16x32_bf16 v[68:71], v[144:147], v[210:213], v[68:71]
	v_mfma_f32_16x16x32_bf16 v[64:67], v[168:171], v[210:213], v[64:67]
	v_mfma_f32_16x16x32_bf16 v[116:119], v[148:151], v[188:191], v[116:119]
	v_mfma_f32_16x16x32_bf16 v[112:115], v[172:175], v[188:191], v[112:115]
	v_mfma_f32_16x16x32_bf16 v[100:103], v[148:151], v[198:201], v[100:103]
	v_mfma_f32_16x16x32_bf16 v[92:95], v[172:175], v[198:201], v[92:95]
	v_mfma_f32_16x16x32_bf16 v[84:87], v[148:151], v[206:209], v[84:87]
	v_mfma_f32_16x16x32_bf16 v[76:79], v[172:175], v[206:209], v[76:79]
	v_mfma_f32_16x16x32_bf16 v[68:71], v[148:151], v[218:221], v[68:71]
	v_mfma_f32_16x16x32_bf16 v[64:67], v[172:175], v[218:221], v[64:67]
	s_setprio 0
	s_barrier
; #define PG8_STAGE(bufoff, gbase, voff) do { _Pragma("unroll") for (int _i = 0; _i < 2; ++_i) \
;         __builtin_amdgcn_global_load_lds((const unsigned*)((const char*)(gbase) + (voff)[_i]), (PG8_LAS unsigned*)(lds + (bufoff) + ldsw + _i * 8192), 16, 0, 0); } while (0)
; #define PG8_LDA(dst, b, h) do { _Pragma("unroll") for (int m = 0; m < 4; ++m) _Pragma("unroll") for (int k = 0; k < 2; ++k) dst[m][k] = *(const PG8_LAS bf16x8*)(lds + PG8_SA(b, h) + aoff + m * 2048 + k * 1024); } while (0)
; #define PG8_MMA(ai, bj, At, Bt) do { __builtin_amdgcn_s_setprio(1); _Pragma("unroll") for (int m = 0; m < 4; ++m) _Pragma("unroll") for (int n = 0; n < 2; ++n) _Pragma("unroll") for (int k = 0; k < 2; ++k) \
;         acc[ai][bj][m][n] = __builtin_amdgcn_mfma_f32_16x16x32_bf16(Bt[n][k], At[m][k], acc[ai][bj][m][n], 0, 0, 0); __builtin_amdgcn_s_setprio(0); } while (0)
; #define PG8_WAIT_V(n) asm volatile("s_waitcnt vmcnt(" #n ")" ::: "memory")
; #define PG8_WAIT_L(n) asm volatile("s_waitcnt lgkmcnt(" #n ")" ::: "memory")
; #define PG8_BAR __builtin_amdgcn_s_barrier()
; #define PG8_SCHED __builtin_amdgcn_sched_barrier(0)
; template <class Epi, class Sched, bool ALIGN_EPI = false, bool SP2 = false>
; __device__ __forceinline__ void gemm_phase(PG8_LAS unsigned char* lds, const Gemm g, const Sched& S, const Epi& E) {
;     ...
;         for (int t = 0; t < nt; t += 2) {
;     ...
;             PG8_LDA(At, 1, 1); PG8_STAGE(PG8_SB(1, 0), b3, voffB); PG8_STAGE(PG8_SB(1, 1), b3 + hstep, voffB); PG8_STAGE(PG8_SA(1, 0), a3, voffA);
;             PG8_WAIT_V(8); PG8_WAIT_L(0); PG8_BAR; PG8_MMA(1, 0, At, B0); PG8_MMA(1, 1, At, B1); PG8_BAR; PG8_SCHED;
	s_add_i32 s54, s77, s62
	v_lshl_add_u64 v[176:177], v[176:177], 0, s[26:27]
	s_mov_b32 m0, s54
	ds_read_b128 v[184:187], v183 offset:49152
	ds_read_b128 v[188:191], v183 offset:50176
	ds_read_b128 v[194:197], v183 offset:51200
	ds_read_b128 v[198:201], v183 offset:52224
	ds_read_b128 v[202:205], v183 offset:53248
	ds_read_b128 v[206:209], v183 offset:54272
	ds_read_b128 v[210:213], v183 offset:55296
	ds_read_b128 v[218:221], v183 offset:56320
	global_load_lds_dwordx4 v[176:177], off
	s_add_i32 m0, s54, 0x2000
	s_add_u32 s52, s52, 0x40080
	v_lshl_add_u64 v[176:177], v[214:215], 0, s[26:27]
	s_addc_u32 s53, s53, 0
	s_add_i32 s54, s78, s62
	global_load_lds_dwordx4 v[176:177], off
	v_lshl_add_u64 v[176:177], s[52:53], 0, v[156:157]
	s_mov_b32 m0, s54
	s_nop 0
	global_load_lds_dwordx4 v[176:177], off
	v_lshl_add_u64 v[176:177], s[52:53], 0, v[152:153]
	s_add_i32 m0, s54, 0x2000
	s_nop 0
	global_load_lds_dwordx4 v[176:177], off
	v_lshl_add_u64 v[176:177], v[222:223], 0, s[26:27]
	s_mov_b32 m0, s68
	s_nop 0
	global_load_lds_dwordx4 v[176:177], off
	v_lshl_add_u64 v[176:177], v[224:225], 0, s[26:27]
	s_mov_b32 m0, s69
	s_nop 0
	global_load_lds_dwordx4 v[176:177], off
	s_waitcnt vmcnt(8)
	s_waitcnt lgkmcnt(0)
	s_barrier
	s_setprio 1
	s_waitcnt lgkmcnt(0)
	v_mfma_f32_16x16x32_bf16 v[60:63], v[128:131], v[184:187], v[60:63]
	v_mfma_f32_16x16x32_bf16 v[56:59], v[136:139], v[184:187], v[56:59]
	v_mfma_f32_16x16x32_bf16 v[48:51], v[128:131], v[194:197], v[48:51]
	v_mfma_f32_16x16x32_bf16 v[40:43], v[136:139], v[194:197], v[40:43]
	v_mfma_f32_16x16x32_bf16 v[32:35], v[128:131], v[202:205], v[32:35]
	v_mfma_f32_16x16x32_bf16 v[24:27], v[136:139], v[202:205], v[24:27]
	v_mfma_f32_16x16x32_bf16 v[16:19], v[128:131], v[210:213], v[16:19]
	v_mfma_f32_16x16x32_bf16 v[8:11], v[136:139], v[210:213], v[8:11]
	v_mfma_f32_16x16x32_bf16 v[60:63], v[132:135], v[188:191], v[60:63]
	v_mfma_f32_16x16x32_bf16 v[56:59], v[140:143], v[188:191], v[56:59]
	v_mfma_f32_16x16x32_bf16 v[48:51], v[132:135], v[198:201], v[48:51]
	v_mfma_f32_16x16x32_bf16 v[40:43], v[140:143], v[198:201], v[40:43]
	v_mfma_f32_16x16x32_bf16 v[32:35], v[132:135], v[206:209], v[32:35]
	v_mfma_f32_16x16x32_bf16 v[24:27], v[140:143], v[206:209], v[24:27]
	v_mfma_f32_16x16x32_bf16 v[16:19], v[132:135], v[218:221], v[16:19]
	v_mfma_f32_16x16x32_bf16 v[8:11], v[140:143], v[218:221], v[8:11]
	s_setprio 0
	s_setprio 1
	v_mfma_f32_16x16x32_bf16 v[52:55], v[144:147], v[184:187], v[52:55]
	v_mfma_f32_16x16x32_bf16 v[44:47], v[168:171], v[184:187], v[44:47]
	v_mfma_f32_16x16x32_bf16 v[36:39], v[144:147], v[194:197], v[36:39]
	v_mfma_f32_16x16x32_bf16 v[28:31], v[168:171], v[194:197], v[28:31]
	v_mfma_f32_16x16x32_bf16 v[20:23], v[144:147], v[202:205], v[20:23]
	v_mfma_f32_16x16x32_bf16 v[12:15], v[168:171], v[202:205], v[12:15]
	v_mfma_f32_16x16x32_bf16 v[4:7], v[144:147], v[210:213], v[4:7]
	v_mfma_f32_16x16x32_bf16 v[0:3], v[168:171], v[210:213], v[0:3]
	v_mfma_f32_16x16x32_bf16 v[52:55], v[148:151], v[188:191], v[52:55]
	v_mfma_f32_16x16x32_bf16 v[44:47], v[172:175], v[188:191], v[44:47]
	v_mfma_f32_16x16x32_bf16 v[36:39], v[148:151], v[198:201], v[36:39]
	v_mfma_f32_16x16x32_bf16 v[28:31], v[172:175], v[198:201], v[28:31]
	v_mfma_f32_16x16x32_bf16 v[20:23], v[148:151], v[206:209], v[20:23]
	v_mfma_f32_16x16x32_bf16 v[12:15], v[172:175], v[206:209], v[12:15]
	v_mfma_f32_16x16x32_bf16 v[4:7], v[148:151], v[218:221], v[4:7]
	v_mfma_f32_16x16x32_bf16 v[0:3], v[172:175], v[218:221], v[0:3]
	s_setprio 0
	s_barrier
	s_add_i32 s76, s76, 2
	s_add_u32 s50, s50, 0x100
	s_addc_u32 s51, s51, 0
	s_add_u32 s74, s74, 0x100
	s_addc_u32 s75, s75, 0
	s_cmp_gt_u32 s76, 13

; #define PG8_STAGE(bufoff, gbase, voff) do { _Pragma("unroll") for (int _i = 0; _i < 2; ++_i) \
;         __builtin_amdgcn_global_load_lds((const unsigned*)((const char*)(gbase) + (voff)[_i]), (PG8_LAS unsigned*)(lds + (bufoff) + ldsw + _i * 8192), 16, 0, 0); } while (0)
; #define PG8_WAIT_V(n) asm volatile("s_waitcnt vmcnt(" #n ")" ::: "memory")
; template <class Epi, class Sched, bool ALIGN_EPI = false, bool SP2 = false>
; __device__ __forceinline__ void gemm_phase(PG8_LAS unsigned char* lds, const Gemm g, const Sched& S, const Epi& E) {
;     ...
;     const int tid = tid_, wid = __builtin_amdgcn_readfirstlane(tid >> 6), lane = tid & 63, wr = wid >> 2, wc = wid & 3, fr = lane & 15, fq = lane >> 4;
;     const int K = g.K, nt = K / BK;
;     unsigned voffA[2], voffB[2];
; #pragma unroll
;     for (int i = 0; i < 2; ++i) { int R, C; stage_rc(tid * 16 + i * 8192, R, C); const int Rb = Epi::PERM ? ((R & ~31) + perm32(R & 31)) : R;
;         voffA[i] = (unsigned)(R * K + C) * 2u; voffB[i] = (unsigned)(Rb * K + C) * 2u; }
;     const size_t kstep = (size_t)(BK * 2);
;     const size_t hstep = (size_t)HALF * K * 2;
;     const size_t tstep = 2 * hstep;
;     const unsigned ldsw = (unsigned)wid * 1024u;
;     const int aoff = lds_byte(wr * 64 + fr, fq * 8), boff = lds_byte(wc * 32 + fr, fq * 8);
;     ...
;     Unit cur, nxt; int ui = 0;
;     if (!S.next(0, cur)) return;
;     f32x4 acc[2][2][4][2];
; #pragma unroll
;     for (int a = 0; a < 2; ++a)
; #pragma unroll
;         for (int b = 0; b < 2; ++b)
; #pragma unroll
;             for (int m = 0; m < 4; ++m)
; #pragma unroll
;                 for (int n = 0; n < 2; ++n) acc[a][b][m][n] = (f32x4){0.f, 0.f, 0.f, 0.f};
;     bf16x8 At[4][2], B0[2][2], B1[2][2];
;     const char* cA = (const char*)g.A + (size_t)cur.pm * tstep; const char* cB = (const char*)g.Bt + (size_t)cur.pn * tstep;
;     S.a_ready(cur);
;     if constexpr (SP2) {
;         PG8_STAGE(PG8_SB(0, 0), cB, voffB); PG8_STAGE(PG8_SB(0, 1), cB + hstep, voffB); PG8_STAGE(PG8_SA(0, 0), cA, voffA); PG8_STAGE(PG8_SA(0, 1), cA + hstep, voffA);
;         if (wr == 1) PG8_BAR;
;         PG8_WAIT_V(2); PG8_BAR;
; __global__ void __launch_bounds__(NTHR, 2) mega_fwd(Args args) {
;     ...
;         { pg8::Gemm g{OA, WA, T, DM, CW}; pg8::EpiMerge<true> E{MG, GT + 2048}; pg8::gemm_phase<pg8::EpiMerge<true>, pg8::StaticOrder, true, true>(L, g, S, E); }
.LBB0_560:
	v_mov_b32_e32 v14, v216
	s_nop 0
	s_nop 0
	s_nop 0
	s_nop 0
	s_nop 0
	s_nop 0
	s_nop 0
	s_nop 0
	s_nop 0
	s_nop 0
	v_cndmask_b32_e64 v0, 0, 1, s[48:49]
	v_cmp_ne_u32_e64 s[38:39], 1, v0
	s_andn2_b64 vcc, exec, s[48:49]
	v_readfirstlane_b32 s22, v14
	s_cbranch_vccnz .LBB0_580
	v_lshlrev_b32_e32 v0, 4, v14
	v_add_u32_e32 v1, 0x2000, v0
	v_ashrrev_i32_e32 v2, 31, v1
	v_lshrrev_b32_e32 v2, 22, v2
	v_add_u32_e32 v2, v1, v2
	v_ashrrev_i32_e32 v8, 10, v2
	v_mul_i32_i24_e32 v2, 0x400, v8
	v_sub_u32_e32 v1, v1, v2
	v_lshrrev_b32_e32 v2, 4, v1
	v_bitop3_b32 v1, v2, v1, 32 bitop3:0x6c
	v_ashrrev_i32_e32 v2, 31, v1
	s_ashr_i32 s23, s22, 6
	v_lshrrev_b32_e32 v2, 26, v2
	s_ashr_i32 s24, s22, 8
	s_lshl_b32 s13, s23, 10
	v_add_u32_e32 v2, v1, v2
	v_lshlrev_b32_e32 v3, 3, v8
	s_add_u32 s47, s20, 0x17800000
	v_ashrrev_i32_e32 v9, 6, v2
	v_and_b32_e32 v3, -16, v3
	s_addc_u32 s52, s21, 0
	v_add_u32_e32 v3, v9, v3
	s_add_u32 s53, s18, 0x2a00000
	v_and_b32_e32 v4, 3, v9
	s_mov_b32 s18, 0x1fffe0
	v_lshrrev_b32_e32 v5, 2, v3
	v_lshlrev_b32_e32 v6, 1, v3
	v_and_b32_e32 v2, 0xc0, v2
	v_and_or_b32 v4, v3, s18, v4
	v_and_b32_e32 v5, 4, v5
	v_and_b32_e32 v6, 24, v6
	v_sub_u32_e32 v1, v1, v2
	v_mov_b32_e32 v2, 1
	v_or3_b32 v4, v4, v5, v6
	v_lshlrev_b32_e32 v5, 5, v8
	v_ashrrev_i16_sdwa v1, v2, sext(v1) dst_sel:DWORD dst_unused:UNUSED_PAD src0_sel:DWORD src1_sel:BYTE_0
	v_and_b32_e32 v5, 32, v5
	v_bfe_i32 v10, v1, 0, 16
	v_add_lshl_u32 v1, v5, v10, 1
	v_lshl_add_u32 v184, v4, 11, v1
	v_lshl_add_u32 v186, v3, 11, v1
	v_bfe_i32 v1, v14, 27, 1
	v_lshrrev_b32_e32 v1, 22, v1
	v_add_u32_e32 v1, v0, v1
	v_and_b32_e32 v1, 0xfffffc00, v1
	v_sub_u32_e32 v0, v0, v1
	v_lshrrev_b32_e32 v1, 4, v0
	v_ashrrev_i32_e32 v3, 31, v14
	v_bitop3_b32 v0, v1, v0, 32 bitop3:0x6c
	v_lshrrev_b32_e32 v3, 26, v3
	v_ashrrev_i32_e32 v1, 31, v0
	v_add_u32_e32 v3, v14, v3
	v_lshrrev_b32_e32 v1, 26, v1
	v_ashrrev_i32_e32 v12, 6, v3
	v_add_u32_e32 v1, v0, v1
	v_lshlrev_b32_e32 v3, 3, v12
	v_ashrrev_i32_e32 v11, 6, v1
	v_and_b32_e32 v3, -16, v3
	s_addc_u32 s54, s19, 0
	v_add_u32_e32 v3, v11, v3
	v_and_b32_e32 v4, 3, v11
	v_and_or_b32 v4, v3, s18, v4
	s_and_b64 s[18:19], s[42:43], exec
	s_cselect_b32 s18, s58, s57
	s_add_i32 s18, s18, s56
	s_ashr_i32 s19, s18, 31
	s_lshr_b32 s19, s19, 27
	s_add_i32 s19, s18, s19
	s_ashr_i32 s20, s19, 5
	s_and_b32 s19, s19, 0xffe0
	s_sub_i32 s18, s18, s19
	s_bfe_i32 s19, s18, 0x80000
	s_bfe_u32 s19, s19, 0x2000d
	s_add_i32 s19, s18, s19
	s_lshl_b32 s21, s20, 2
	s_bfe_i32 s20, s19, 0x80000
	s_and_b32 s19, s19, 0xfc
	s_sub_i32 s18, s18, s19
	s_sext_i32_i16 s20, s20
	s_sext_i32_i8 s18, s18
	v_lshrrev_b32_e32 v5, 2, v3
	v_lshlrev_b32_e32 v6, 1, v3
	v_and_b32_e32 v1, 0xc0, v1
	s_lshr_b32 s20, s20, 2
	s_add_i32 s34, s21, s18
	v_and_b32_e32 v5, 4, v5
	v_and_b32_e32 v6, 24, v6
	v_sub_u32_e32 v0, v0, v1
	s_ashr_i32 s35, s34, 31
	s_bfe_i64 s[26:27], s[20:21], 0x100000
	v_or3_b32 v4, v4, v5, v6
	v_lshlrev_b32_e32 v5, 5, v12
	v_ashrrev_i16_sdwa v0, v2, sext(v0) dst_sel:DWORD dst_unused:UNUSED_PAD src0_sel:DWORD src1_sel:BYTE_0
	s_lshl_b64 s[18:19], s[34:35], 19
	s_lshl_b64 s[26:27], s[26:27], 19
	v_and_b32_e32 v5, 32, v5
	v_bfe_i32 v13, v0, 0, 16
	s_add_u32 s44, s53, s26
	v_add_lshl_u32 v0, v5, v13, 1
	s_addc_u32 s45, s54, s27
	s_add_i32 s55, s13, 0
	v_lshl_add_u32 v188, v4, 11, v0
	s_add_i32 m0, s55, 0x10000
	v_lshl_add_u32 v190, v3, 11, v0
	global_load_lds_dwordx4 v188, s[44:45]
	s_add_i32 m0, s55, 0x12000
	s_add_u32 s26, s44, 0x40000
	global_load_lds_dwordx4 v184, s[44:45]
	s_addc_u32 s27, s45, 0
	s_add_i32 m0, s55, 0x14000
	v_mov_b32_e32 v189, 0
	global_load_lds_dwordx4 v188, s[26:27]
	s_add_i32 m0, s55, 0x16000
	s_add_u32 s36, s47, s18
	s_addc_u32 s37, s52, s19
	s_add_i32 s60, s55, 0x2000
	global_load_lds_dwordx4 v184, s[26:27]
	s_mov_b32 m0, s55
	s_add_u32 s18, s36, 0x40000
	global_load_lds_dwordx4 v190, s[36:37]
	s_mov_b32 m0, s60
	s_addc_u32 s19, s37, 0
	s_add_i32 s61, s55, 0x4000
	global_load_lds_dwordx4 v186, s[36:37]
	s_mov_b32 m0, s61
	s_add_i32 s62, s55, 0x6000
	global_load_lds_dwordx4 v190, s[18:19]
	s_mov_b32 m0, s62
	v_mov_b32_e32 v185, v189
	global_load_lds_dwordx4 v186, s[18:19]
	v_mov_b32_e32 v191, v189
	v_mov_b32_e32 v187, v189
	s_cmp_eq_u32 s24, 1
	s_mov_b32 s63, 0
	v_lshl_add_u64 v[6:7], s[44:45], 0, v[188:189]
	v_lshl_add_u64 v[4:5], s[44:45], 0, v[184:185]
	v_lshl_add_u64 v[0:1], s[36:37], 0, v[190:191]
	s_cselect_b64 s[18:19], -1, 0
	s_cmp_lg_u32 s24, 1
	v_lshl_add_u64 v[2:3], s[36:37], 0, v[186:187]
	s_cbranch_scc1 .LBB0_563
	s_barrier

; #define PG8_STAGE(bufoff, gbase, voff) do { _Pragma("unroll") for (int _i = 0; _i < 2; ++_i) \
;         __builtin_amdgcn_global_load_lds((const unsigned*)((const char*)(gbase) + (voff)[_i]), (PG8_LAS unsigned*)(lds + (bufoff) + ldsw + _i * 8192), 16, 0, 0); } while (0)
; #define PG8_LDA(dst, b, h) do { _Pragma("unroll") for (int m = 0; m < 4; ++m) _Pragma("unroll") for (int k = 0; k < 2; ++k) dst[m][k] = *(const PG8_LAS bf16x8*)(lds + PG8_SA(b, h) + aoff + m * 2048 + k * 1024); } while (0)
; template <class Epi, class Sched, bool ALIGN_EPI = false, bool SP2 = false>
; __device__ __forceinline__ void gemm_phase(PG8_LAS unsigned char* lds, const Gemm g, const Sched& S, const Epi& E) {
;     ...
;         const bool has_next = S.next(ui + 1, nxt);
;         const char* nA = has_next ? (const char*)g.A + (size_t)nxt.pm * tstep : cA; const char* nB = has_next ? (const char*)g.Bt + (size_t)nxt.pn * tstep : cB;
;         for (int t = 0; t < nt; t += 2) {
;             const bool last = (t == nt - 2);
;             const char* a1 = cA + (size_t)(t + 1) * kstep;
;             const char* a2 = last ? nA : cA + (size_t)(t + 2) * kstep; const char* b2 = last ? nB : cB + (size_t)(t + 2) * kstep;
;             const char* a3 = a2 + kstep; const char* b3 = b2 + kstep;
;             if (last && has_next) S.a_ready(nxt);
;             if constexpr (SP2) {
;             PG8_LDB(B0, 0, 0); PG8_LDB(B1, 0, 1); PG8_SCHED; PG8_LDA(At, 0, 0); PG8_STAGE(PG8_SA(1, 1), a1 + hstep, voffA);
;             PG8_WAIT_V(8); PG8_WAIT_L(0); PG8_BAR; PG8_MMA(0, 0, At, B0); PG8_MMA(0, 1, At, B1); PG8_BAR; PG8_SCHED;
;             PG8_LDA(At, 0, 1); PG8_STAGE(PG8_SB(0, 0), b2, voffB); PG8_STAGE(PG8_SB(0, 1), b2 + hstep, voffB); PG8_STAGE(PG8_SA(0, 0), a2, voffA);
;             PG8_WAIT_V(8); PG8_WAIT_L(0); PG8_BAR; PG8_MMA(1, 0, At, B0); PG8_MMA(1, 1, At, B1); PG8_BAR; PG8_SCHED;
;             PG8_LDB(B0, 1, 0); PG8_LDB(B1, 1, 1); PG8_SCHED; PG8_LDA(At, 1, 0); PG8_STAGE(PG8_SA(0, 1), a2 + hstep, voffA);
;             PG8_WAIT_V(8); PG8_WAIT_L(0); PG8_BAR; PG8_MMA(0, 0, At, B0); PG8_MMA(0, 1, At, B1); PG8_BAR; PG8_SCHED;
;             PG8_LDA(At, 1, 1); PG8_STAGE(PG8_SB(1, 0), b3, voffB); PG8_STAGE(PG8_SB(1, 1), b3 + hstep, voffB); PG8_STAGE(PG8_SA(1, 0), a3, voffA);
;             PG8_WAIT_V(8); PG8_WAIT_L(0); PG8_BAR; PG8_MMA(1, 0, At, B0); PG8_MMA(1, 1, At, B1); PG8_BAR; PG8_SCHED;
.LBB0_572:
	s_ashr_i32 s27, s26, 31
	s_lshl_b64 s[28:29], s[26:27], 19
	s_add_u32 s28, s47, s28
	s_addc_u32 s29, s52, s29
	s_and_b64 s[30:31], s[40:41], exec
	s_cselect_b32 s27, s29, s37
	s_cselect_b32 s68, s28, s36
	s_ashr_i32 s25, s24, 31
	s_lshl_b64 s[30:31], s[24:25], 19
	s_add_u32 s30, s53, s30
	s_addc_u32 s31, s54, s31
	s_and_b64 s[50:51], s[40:41], exec
	s_cselect_b32 s25, s31, s45
	s_cselect_b32 s69, s30, s44
	s_add_u32 s36, s36, 0x40080
	s_addc_u32 s37, s37, 0
	s_add_u32 s70, s44, 0x100
	s_addc_u32 s71, s45, 0
	s_mov_b32 s72, -2
	ds_read_b128 v[128:131], v220
	ds_read_b128 v[132:135], v220 offset:1024
	ds_read_b128 v[136:139], v220 offset:2048
	ds_read_b128 v[140:143], v220 offset:3072
	ds_read_b128 v[144:147], v221
	ds_read_b128 v[148:151], v221 offset:1024
	ds_read_b128 v[152:155], v221 offset:2048
	ds_read_b128 v[156:159], v221 offset:3072
	s_add_u32 s44, s36, 0xfffc0080
	s_addc_u32 s45, s37, -1
	s_cmp_eq_u32 s72, 12
	s_cselect_b32 s51, s27, s45
	s_cselect_b32 s50, s68, s44
	s_cselect_b32 s45, s25, s71
	s_cselect_b32 s44, s69, s70
	v_lshl_add_u64 v[210:211], s[36:37], 0, v[194:195]
	s_add_i32 m0, s55, 0xc000
	ds_read_b128 v[160:163], v222
	ds_read_b128 v[164:167], v222 offset:1024
	ds_read_b128 v[168:171], v222 offset:2048
	ds_read_b128 v[172:175], v222 offset:3072
	ds_read_b128 v[176:179], v222 offset:4096
	ds_read_b128 v[180:183], v222 offset:5120
	ds_read_b128 v[202:205], v222 offset:6144
	ds_read_b128 v[206:209], v222 offset:7168
	global_load_lds_dwordx4 v[210:211], off
	v_lshl_add_u64 v[210:211], s[36:37], 0, v[196:197]
	s_add_i32 m0, s55, 0xe000
	s_nop 0
	global_load_lds_dwordx4 v[210:211], off
	s_waitcnt vmcnt(8)
	s_waitcnt lgkmcnt(0)
	s_barrier
	s_setprio 1
	s_waitcnt lgkmcnt(0)
	v_mfma_f32_16x16x32_bf16 v[124:127], v[128:131], v[160:163], 0
	v_mfma_f32_16x16x32_bf16 v[120:123], v[136:139], v[160:163], 0
	v_mfma_f32_16x16x32_bf16 v[108:111], v[128:131], v[168:171], 0
	v_mfma_f32_16x16x32_bf16 v[104:107], v[136:139], v[168:171], 0
	v_mfma_f32_16x16x32_bf16 v[92:95], v[128:131], v[176:179], 0
	v_mfma_f32_16x16x32_bf16 v[88:91], v[136:139], v[176:179], 0
	v_mfma_f32_16x16x32_bf16 v[76:79], v[128:131], v[202:205], 0
	v_mfma_f32_16x16x32_bf16 v[72:75], v[136:139], v[202:205], 0
	v_mfma_f32_16x16x32_bf16 v[124:127], v[132:135], v[164:167], v[124:127]
	v_mfma_f32_16x16x32_bf16 v[120:123], v[140:143], v[164:167], v[120:123]
	v_mfma_f32_16x16x32_bf16 v[108:111], v[132:135], v[172:175], v[108:111]
	v_mfma_f32_16x16x32_bf16 v[104:107], v[140:143], v[172:175], v[104:107]
	v_mfma_f32_16x16x32_bf16 v[92:95], v[132:135], v[180:183], v[92:95]
	v_mfma_f32_16x16x32_bf16 v[88:91], v[140:143], v[180:183], v[88:91]
	v_mfma_f32_16x16x32_bf16 v[76:79], v[132:135], v[206:209], v[76:79]
	v_mfma_f32_16x16x32_bf16 v[72:75], v[140:143], v[206:209], v[72:75]
	s_setprio 0
	s_setprio 1
	v_mfma_f32_16x16x32_bf16 v[116:119], v[144:147], v[160:163], 0
	v_mfma_f32_16x16x32_bf16 v[112:115], v[152:155], v[160:163], 0
	v_mfma_f32_16x16x32_bf16 v[100:103], v[144:147], v[168:171], 0
	v_mfma_f32_16x16x32_bf16 v[96:99], v[152:155], v[168:171], 0
	v_mfma_f32_16x16x32_bf16 v[84:87], v[144:147], v[176:179], 0
	v_mfma_f32_16x16x32_bf16 v[80:83], v[152:155], v[176:179], 0
	v_mfma_f32_16x16x32_bf16 v[68:71], v[144:147], v[202:205], 0
	v_mfma_f32_16x16x32_bf16 v[64:67], v[152:155], v[202:205], 0
	v_mfma_f32_16x16x32_bf16 v[116:119], v[148:151], v[164:167], v[116:119]
	v_mfma_f32_16x16x32_bf16 v[112:115], v[156:159], v[164:167], v[112:115]
	v_mfma_f32_16x16x32_bf16 v[100:103], v[148:151], v[172:175], v[100:103]
	v_mfma_f32_16x16x32_bf16 v[96:99], v[156:159], v[172:175], v[96:99]
	v_mfma_f32_16x16x32_bf16 v[84:87], v[148:151], v[180:183], v[84:87]
	v_mfma_f32_16x16x32_bf16 v[80:83], v[156:159], v[180:183], v[80:83]
	v_mfma_f32_16x16x32_bf16 v[68:71], v[148:151], v[206:209], v[68:71]
	v_mfma_f32_16x16x32_bf16 v[64:67], v[156:159], v[206:209], v[64:67]
	s_setprio 0
	s_barrier
	s_add_i32 s73, s66, s13
	v_lshl_add_u64 v[210:211], s[44:45], 0, v[188:189]
	s_mov_b32 m0, s73
	ds_read_b128 v[160:163], v222 offset:16384
	ds_read_b128 v[164:167], v222 offset:17408
	ds_read_b128 v[168:171], v222 offset:18432
	ds_read_b128 v[172:175], v222 offset:19456
	ds_read_b128 v[176:179], v222 offset:20480
	ds_read_b128 v[180:183], v222 offset:21504
	ds_read_b128 v[202:205], v222 offset:22528
	ds_read_b128 v[206:209], v222 offset:23552
	global_load_lds_dwordx4 v[210:211], off
	s_add_i32 m0, s73, 0x2000
	s_add_u32 s74, s44, 0x40000
	v_lshl_add_u64 v[212:213], s[44:45], 0, v[184:185]
	s_addc_u32 s75, s45, 0
	s_add_i32 s73, s67, s13
	global_load_lds_dwordx4 v[212:213], off
	v_lshl_add_u64 v[214:215], s[74:75], 0, v[188:189]
	s_mov_b32 m0, s73
	v_lshl_add_u64 v[224:225], s[50:51], 0, v[186:187]
	global_load_lds_dwordx4 v[214:215], off
	v_lshl_add_u64 v[214:215], s[74:75], 0, v[184:185]
	s_add_i32 m0, s73, 0x2000
	s_nop 0
	global_load_lds_dwordx4 v[214:215], off
	v_lshl_add_u64 v[214:215], s[50:51], 0, v[190:191]
	s_mov_b32 m0, s55
	s_nop 0
	global_load_lds_dwordx4 v[214:215], off
	s_mov_b32 m0, s60
	s_nop 0
	global_load_lds_dwordx4 v[224:225], off
	s_waitcnt vmcnt(8)
	s_waitcnt lgkmcnt(0)
	s_barrier
; #define PG8_STAGE(bufoff, gbase, voff) do { _Pragma("unroll") for (int _i = 0; _i < 2; ++_i) \
;         __builtin_amdgcn_global_load_lds((const unsigned*)((const char*)(gbase) + (voff)[_i]), (PG8_LAS unsigned*)(lds + (bufoff) + ldsw + _i * 8192), 16, 0, 0); } while (0)
; #define PG8_LDA(dst, b, h) do { _Pragma("unroll") for (int m = 0; m < 4; ++m) _Pragma("unroll") for (int k = 0; k < 2; ++k) dst[m][k] = *(const PG8_LAS bf16x8*)(lds + PG8_SA(b, h) + aoff + m * 2048 + k * 1024); } while (0)
; #define PG8_LDB(dst, b, h) do { _Pragma("unroll") for (int n = 0; n < 2; ++n) _Pragma("unroll") for (int k = 0; k < 2; ++k) dst[n][k] = *(const PG8_LAS bf16x8*)(lds + PG8_SB(b, h) + boff + n * 2048 + k * 1024); } while (0)
; #define PG8_MMA(ai, bj, At, Bt) do { __builtin_amdgcn_s_setprio(1); _Pragma("unroll") for (int m = 0; m < 4; ++m) _Pragma("unroll") for (int n = 0; n < 2; ++n) _Pragma("unroll") for (int k = 0; k < 2; ++k) \
;         acc[ai][bj][m][n] = __builtin_amdgcn_mfma_f32_16x16x32_bf16(Bt[n][k], At[m][k], acc[ai][bj][m][n], 0, 0, 0); __builtin_amdgcn_s_setprio(0); } while (0)
; #define PG8_WAIT_V(n) asm volatile("s_waitcnt vmcnt(" #n ")" ::: "memory")
; #define PG8_WAIT_L(n) asm volatile("s_waitcnt lgkmcnt(" #n ")" ::: "memory")
; #define PG8_BAR __builtin_amdgcn_s_barrier()
; #define PG8_SCHED __builtin_amdgcn_sched_barrier(0)
; template <class Epi, class Sched, bool ALIGN_EPI = false, bool SP2 = false>
; __device__ __forceinline__ void gemm_phase(PG8_LAS unsigned char* lds, const Gemm g, const Sched& S, const Epi& E) {
;     ...
;             PG8_WAIT_V(8); PG8_WAIT_L(0); PG8_BAR; PG8_MMA(1, 0, At, B0); PG8_MMA(1, 1, At, B1); PG8_BAR; PG8_SCHED;
;             PG8_LDB(B0, 1, 0); PG8_LDB(B1, 1, 1); PG8_SCHED; PG8_LDA(At, 1, 0); PG8_STAGE(PG8_SA(0, 1), a2 + hstep, voffA);
;             PG8_WAIT_V(8); PG8_WAIT_L(0); PG8_BAR; PG8_MMA(0, 0, At, B0); PG8_MMA(0, 1, At, B1); PG8_BAR; PG8_SCHED;
	s_setprio 1
	s_waitcnt lgkmcnt(0)
	v_mfma_f32_16x16x32_bf16 v[60:63], v[128:131], v[160:163], 0
	v_mfma_f32_16x16x32_bf16 v[56:59], v[136:139], v[160:163], 0
	v_mfma_f32_16x16x32_bf16 v[44:47], v[128:131], v[168:171], 0
	v_mfma_f32_16x16x32_bf16 v[40:43], v[136:139], v[168:171], 0
	v_mfma_f32_16x16x32_bf16 v[28:31], v[128:131], v[176:179], 0
	v_mfma_f32_16x16x32_bf16 v[24:27], v[136:139], v[176:179], 0
	v_mfma_f32_16x16x32_bf16 v[12:15], v[128:131], v[202:205], 0
	v_mfma_f32_16x16x32_bf16 v[8:11], v[136:139], v[202:205], 0
	v_mfma_f32_16x16x32_bf16 v[60:63], v[132:135], v[164:167], v[60:63]
	v_mfma_f32_16x16x32_bf16 v[56:59], v[140:143], v[164:167], v[56:59]
	v_mfma_f32_16x16x32_bf16 v[44:47], v[132:135], v[172:175], v[44:47]
	v_mfma_f32_16x16x32_bf16 v[40:43], v[140:143], v[172:175], v[40:43]
	v_mfma_f32_16x16x32_bf16 v[28:31], v[132:135], v[180:183], v[28:31]
	v_mfma_f32_16x16x32_bf16 v[24:27], v[140:143], v[180:183], v[24:27]
	v_mfma_f32_16x16x32_bf16 v[12:15], v[132:135], v[206:209], v[12:15]
	v_mfma_f32_16x16x32_bf16 v[8:11], v[140:143], v[206:209], v[8:11]
	s_setprio 0
	s_setprio 1
	v_mfma_f32_16x16x32_bf16 v[52:55], v[144:147], v[160:163], 0
	v_mfma_f32_16x16x32_bf16 v[48:51], v[152:155], v[160:163], 0
	v_mfma_f32_16x16x32_bf16 v[36:39], v[144:147], v[168:171], 0
	v_mfma_f32_16x16x32_bf16 v[32:35], v[152:155], v[168:171], 0
	v_mfma_f32_16x16x32_bf16 v[20:23], v[144:147], v[176:179], 0
	v_mfma_f32_16x16x32_bf16 v[16:19], v[152:155], v[176:179], 0
	v_mfma_f32_16x16x32_bf16 v[4:7], v[144:147], v[202:205], 0
	v_mfma_f32_16x16x32_bf16 v[0:3], v[152:155], v[202:205], 0
	v_mfma_f32_16x16x32_bf16 v[52:55], v[148:151], v[164:167], v[52:55]
	v_mfma_f32_16x16x32_bf16 v[48:51], v[156:159], v[164:167], v[48:51]
	v_mfma_f32_16x16x32_bf16 v[36:39], v[148:151], v[172:175], v[36:39]
	v_mfma_f32_16x16x32_bf16 v[32:35], v[156:159], v[172:175], v[32:35]
	v_mfma_f32_16x16x32_bf16 v[20:23], v[148:151], v[180:183], v[20:23]
	v_mfma_f32_16x16x32_bf16 v[16:19], v[156:159], v[180:183], v[16:19]
	v_mfma_f32_16x16x32_bf16 v[4:7], v[148:151], v[206:209], v[4:7]
	v_mfma_f32_16x16x32_bf16 v[0:3], v[156:159], v[206:209], v[0:3]
	s_setprio 0
	s_barrier
	s_add_i32 s73, 0, 0x18000
	s_add_i32 s74, 0, 0x1c000
	v_add_u32_e32 v140, s73, v218
	v_add_u32_e32 v156, s74, v218
	ds_read_b128 v[128:131], v140
	ds_read_b128 v[132:135], v140 offset:1024
	ds_read_b128 v[136:139], v140 offset:2048
	ds_read_b128 v[140:143], v140 offset:3072
	ds_read_b128 v[144:147], v156
	ds_read_b128 v[148:151], v156 offset:1024
	ds_read_b128 v[152:155], v156 offset:2048
	ds_read_b128 v[156:159], v156 offset:3072
	s_add_u32 s50, s50, 0x40000
	s_addc_u32 s51, s51, 0
	s_mov_b32 m0, s61
	v_lshl_add_u64 v[226:227], s[50:51], 0, v[190:191]
	ds_read_b128 v[160:163], v222 offset:32768
	ds_read_b128 v[164:167], v222 offset:33792
	ds_read_b128 v[168:171], v222 offset:34816
	ds_read_b128 v[172:175], v222 offset:35840
	ds_read_b128 v[176:179], v222 offset:36864
	ds_read_b128 v[180:183], v222 offset:37888
	ds_read_b128 v[202:205], v222 offset:38912
	ds_read_b128 v[206:209], v222 offset:39936
	global_load_lds_dwordx4 v[226:227], off
	v_lshl_add_u64 v[226:227], s[50:51], 0, v[186:187]
	s_mov_b32 m0, s62
	s_nop 0
	global_load_lds_dwordx4 v[226:227], off
	s_waitcnt vmcnt(8)
	s_waitcnt lgkmcnt(0)
	s_barrier
	s_setprio 1
	s_waitcnt lgkmcnt(0)
	v_mfma_f32_16x16x32_bf16 v[124:127], v[128:131], v[160:163], v[124:127]
	v_mfma_f32_16x16x32_bf16 v[120:123], v[136:139], v[160:163], v[120:123]
	v_mfma_f32_16x16x32_bf16 v[108:111], v[128:131], v[168:171], v[108:111]
	v_mfma_f32_16x16x32_bf16 v[104:107], v[136:139], v[168:171], v[104:107]
	v_mfma_f32_16x16x32_bf16 v[92:95], v[128:131], v[176:179], v[92:95]
	v_mfma_f32_16x16x32_bf16 v[88:91], v[136:139], v[176:179], v[88:91]
	v_mfma_f32_16x16x32_bf16 v[76:79], v[128:131], v[202:205], v[76:79]
	v_mfma_f32_16x16x32_bf16 v[72:75], v[136:139], v[202:205], v[72:75]
	v_mfma_f32_16x16x32_bf16 v[124:127], v[132:135], v[164:167], v[124:127]
	v_mfma_f32_16x16x32_bf16 v[120:123], v[140:143], v[164:167], v[120:123]
	v_mfma_f32_16x16x32_bf16 v[108:111], v[132:135], v[172:175], v[108:111]
	v_mfma_f32_16x16x32_bf16 v[104:107], v[140:143], v[172:175], v[104:107]
	v_mfma_f32_16x16x32_bf16 v[92:95], v[132:135], v[180:183], v[92:95]
	v_mfma_f32_16x16x32_bf16 v[88:91], v[140:143], v[180:183], v[88:91]
	v_mfma_f32_16x16x32_bf16 v[76:79], v[132:135], v[206:209], v[76:79]
	v_mfma_f32_16x16x32_bf16 v[72:75], v[140:143], v[206:209], v[72:75]
	s_setprio 0
	s_setprio 1
	v_mfma_f32_16x16x32_bf16 v[116:119], v[144:147], v[160:163], v[116:119]
	v_mfma_f32_16x16x32_bf16 v[112:115], v[152:155], v[160:163], v[112:115]
	v_mfma_f32_16x16x32_bf16 v[100:103], v[144:147], v[168:171], v[100:103]
	v_mfma_f32_16x16x32_bf16 v[96:99], v[152:155], v[168:171], v[96:99]
	v_mfma_f32_16x16x32_bf16 v[84:87], v[144:147], v[176:179], v[84:87]
	v_mfma_f32_16x16x32_bf16 v[80:83], v[152:155], v[176:179], v[80:83]
	v_mfma_f32_16x16x32_bf16 v[68:71], v[144:147], v[202:205], v[68:71]
	v_mfma_f32_16x16x32_bf16 v[64:67], v[152:155], v[202:205], v[64:67]
	v_mfma_f32_16x16x32_bf16 v[116:119], v[148:151], v[164:167], v[116:119]
	v_mfma_f32_16x16x32_bf16 v[112:115], v[156:159], v[164:167], v[112:115]
	v_mfma_f32_16x16x32_bf16 v[100:103], v[148:151], v[172:175], v[100:103]
	v_mfma_f32_16x16x32_bf16 v[96:99], v[156:159], v[172:175], v[96:99]
	v_mfma_f32_16x16x32_bf16 v[84:87], v[148:151], v[180:183], v[84:87]
	v_mfma_f32_16x16x32_bf16 v[80:83], v[156:159], v[180:183], v[80:83]
	v_mfma_f32_16x16x32_bf16 v[68:71], v[148:151], v[206:209], v[68:71]
	v_mfma_f32_16x16x32_bf16 v[64:67], v[156:159], v[206:209], v[64:67]
	s_setprio 0
	s_barrier
; #define PG8_STAGE(bufoff, gbase, voff) do { _Pragma("unroll") for (int _i = 0; _i < 2; ++_i) \
;         __builtin_amdgcn_global_load_lds((const unsigned*)((const char*)(gbase) + (voff)[_i]), (PG8_LAS unsigned*)(lds + (bufoff) + ldsw + _i * 8192), 16, 0, 0); } while (0)
; #define PG8_LDA(dst, b, h) do { _Pragma("unroll") for (int m = 0; m < 4; ++m) _Pragma("unroll") for (int k = 0; k < 2; ++k) dst[m][k] = *(const PG8_LAS bf16x8*)(lds + PG8_SA(b, h) + aoff + m * 2048 + k * 1024); } while (0)
; #define PG8_MMA(ai, bj, At, Bt) do { __builtin_amdgcn_s_setprio(1); _Pragma("unroll") for (int m = 0; m < 4; ++m) _Pragma("unroll") for (int n = 0; n < 2; ++n) _Pragma("unroll") for (int k = 0; k < 2; ++k) \
;         acc[ai][bj][m][n] = __builtin_amdgcn_mfma_f32_16x16x32_bf16(Bt[n][k], At[m][k], acc[ai][bj][m][n], 0, 0, 0); __builtin_amdgcn_s_setprio(0); } while (0)
; #define PG8_WAIT_V(n) asm volatile("s_waitcnt vmcnt(" #n ")" ::: "memory")
; #define PG8_WAIT_L(n) asm volatile("s_waitcnt lgkmcnt(" #n ")" ::: "memory")
; #define PG8_BAR __builtin_amdgcn_s_barrier()
; #define PG8_SCHED __builtin_amdgcn_sched_barrier(0)
; template <class Epi, class Sched, bool ALIGN_EPI = false, bool SP2 = false>
; __device__ __forceinline__ void gemm_phase(PG8_LAS unsigned char* lds, const Gemm g, const Sched& S, const Epi& E) {
;     ...
;         for (int t = 0; t < nt; t += 2) {
;     ...
;             PG8_LDA(At, 1, 1); PG8_STAGE(PG8_SB(1, 0), b3, voffB); PG8_STAGE(PG8_SB(1, 1), b3 + hstep, voffB); PG8_STAGE(PG8_SA(1, 0), a3, voffA);
;             PG8_WAIT_V(8); PG8_WAIT_L(0); PG8_BAR; PG8_MMA(1, 0, At, B0); PG8_MMA(1, 1, At, B1); PG8_BAR; PG8_SCHED;
	s_add_i32 s50, s73, s13
	v_lshl_add_u64 v[210:211], v[210:211], 0, s[20:21]
	s_mov_b32 m0, s50
	ds_read_b128 v[160:163], v222 offset:49152
	ds_read_b128 v[164:167], v222 offset:50176
	ds_read_b128 v[168:171], v222 offset:51200
	ds_read_b128 v[172:175], v222 offset:52224
	ds_read_b128 v[176:179], v222 offset:53248
	ds_read_b128 v[180:183], v222 offset:54272
	ds_read_b128 v[202:205], v222 offset:55296
	ds_read_b128 v[206:209], v222 offset:56320
	global_load_lds_dwordx4 v[210:211], off
	s_add_i32 m0, s50, 0x2000
	s_add_u32 s44, s44, 0x40080
	v_lshl_add_u64 v[210:211], v[212:213], 0, s[20:21]
	s_addc_u32 s45, s45, 0
	s_add_i32 s50, s74, s13
	global_load_lds_dwordx4 v[210:211], off
	v_lshl_add_u64 v[210:211], s[44:45], 0, v[188:189]
	s_mov_b32 m0, s50
	s_nop 0
	global_load_lds_dwordx4 v[210:211], off
	v_lshl_add_u64 v[210:211], s[44:45], 0, v[184:185]
	s_add_i32 m0, s50, 0x2000
	s_nop 0
	global_load_lds_dwordx4 v[210:211], off
	v_lshl_add_u64 v[210:211], v[214:215], 0, s[20:21]
	s_mov_b32 m0, s64
	s_nop 0
	global_load_lds_dwordx4 v[210:211], off
	v_lshl_add_u64 v[210:211], v[224:225], 0, s[20:21]
	s_mov_b32 m0, s65
	s_nop 0
	global_load_lds_dwordx4 v[210:211], off
	s_waitcnt vmcnt(8)
	s_waitcnt lgkmcnt(0)
	s_barrier
	s_setprio 1
	s_waitcnt lgkmcnt(0)
	v_mfma_f32_16x16x32_bf16 v[60:63], v[128:131], v[160:163], v[60:63]
	v_mfma_f32_16x16x32_bf16 v[56:59], v[136:139], v[160:163], v[56:59]
	v_mfma_f32_16x16x32_bf16 v[44:47], v[128:131], v[168:171], v[44:47]
	v_mfma_f32_16x16x32_bf16 v[40:43], v[136:139], v[168:171], v[40:43]
	v_mfma_f32_16x16x32_bf16 v[28:31], v[128:131], v[176:179], v[28:31]
	v_mfma_f32_16x16x32_bf16 v[24:27], v[136:139], v[176:179], v[24:27]
	v_mfma_f32_16x16x32_bf16 v[12:15], v[128:131], v[202:205], v[12:15]
	v_mfma_f32_16x16x32_bf16 v[8:11], v[136:139], v[202:205], v[8:11]
	v_mfma_f32_16x16x32_bf16 v[60:63], v[132:135], v[164:167], v[60:63]
	v_mfma_f32_16x16x32_bf16 v[56:59], v[140:143], v[164:167], v[56:59]
	v_mfma_f32_16x16x32_bf16 v[44:47], v[132:135], v[172:175], v[44:47]
	v_mfma_f32_16x16x32_bf16 v[40:43], v[140:143], v[172:175], v[40:43]
	v_mfma_f32_16x16x32_bf16 v[28:31], v[132:135], v[180:183], v[28:31]
	v_mfma_f32_16x16x32_bf16 v[24:27], v[140:143], v[180:183], v[24:27]
	v_mfma_f32_16x16x32_bf16 v[12:15], v[132:135], v[206:209], v[12:15]
	v_mfma_f32_16x16x32_bf16 v[8:11], v[140:143], v[206:209], v[8:11]
	s_setprio 0
	s_setprio 1
	v_mfma_f32_16x16x32_bf16 v[52:55], v[144:147], v[160:163], v[52:55]
	v_mfma_f32_16x16x32_bf16 v[48:51], v[152:155], v[160:163], v[48:51]
	v_mfma_f32_16x16x32_bf16 v[36:39], v[144:147], v[168:171], v[36:39]
	v_mfma_f32_16x16x32_bf16 v[32:35], v[152:155], v[168:171], v[32:35]
	v_mfma_f32_16x16x32_bf16 v[20:23], v[144:147], v[176:179], v[20:23]
	v_mfma_f32_16x16x32_bf16 v[16:19], v[152:155], v[176:179], v[16:19]
	v_mfma_f32_16x16x32_bf16 v[4:7], v[144:147], v[202:205], v[4:7]
	v_mfma_f32_16x16x32_bf16 v[0:3], v[152:155], v[202:205], v[0:3]
	v_mfma_f32_16x16x32_bf16 v[52:55], v[148:151], v[164:167], v[52:55]
	v_mfma_f32_16x16x32_bf16 v[48:51], v[156:159], v[164:167], v[48:51]
	v_mfma_f32_16x16x32_bf16 v[36:39], v[148:151], v[172:175], v[36:39]
	v_mfma_f32_16x16x32_bf16 v[32:35], v[156:159], v[172:175], v[32:35]
	v_mfma_f32_16x16x32_bf16 v[20:23], v[148:151], v[180:183], v[20:23]
	v_mfma_f32_16x16x32_bf16 v[16:19], v[156:159], v[180:183], v[16:19]
	v_mfma_f32_16x16x32_bf16 v[4:7], v[148:151], v[206:209], v[4:7]
	v_mfma_f32_16x16x32_bf16 v[0:3], v[156:159], v[206:209], v[0:3]
	s_setprio 0
	s_barrier
	s_add_i32 s72, s72, 2
	s_add_u32 s36, s36, 0x100
	s_addc_u32 s37, s37, 0
	s_add_u32 s70, s70, 0x100
	s_addc_u32 s71, s71, 0
	s_cmp_gt_u32 s72, 13

; #define PG8_WAIT_V(n) asm volatile("s_waitcnt vmcnt(" #n ")" ::: "memory")
; #define PG8_BAR __builtin_amdgcn_s_barrier()
; template <class Epi, class Sched, bool ALIGN_EPI = false, bool SP2 = false>
; __device__ __forceinline__ void gemm_phase(PG8_LAS unsigned char* lds, const Gemm g, const Sched& S, const Epi& E) {
;     ...
;     PG8_WAIT_V(0);
;     if constexpr (!ALIGN_EPI) { if (wr == 0) PG8_BAR; }
;     PG8_BAR;
; __device__ __forceinline__ void xcd_barrier(const XcdBarrier& b) {
;     asm volatile("s_waitcnt vmcnt(0)" ::: "memory");
;     __syncthreads();
;     if (threadIdx.x == 0) {
;         unsigned* bar = b.bar;
;         __builtin_amdgcn_s_waitcnt(0);
;         unsigned nloc = b.st[0], nx = b.st[1];
;         if (nloc == 0u) { xcd_barrier_complete(bar, b.x, nloc, nx); b.st[0] = nloc; b.st[1] = nx; }
.LBB0_580:
	s_nop 0
	s_nop 0
	s_nop 0
	s_nop 0
	s_nop 0
	s_nop 0
	s_nop 0
	s_nop 0
	s_nop 0
	s_nop 0
	s_nop 0
	s_nop 0
	s_waitcnt vmcnt(0)
	s_barrier
	s_mov_b64 s[14:15], exec
	v_readlane_b32 s16, v254, 0
	v_readlane_b32 s17, v254, 1
	v_readlane_b32 s22, v254, 43
	s_and_b64 s[16:17], s[14:15], s[16:17]
	v_readlane_b32 s23, v254, 44
	s_mov_b64 exec, s[16:17]
	s_cbranch_execz .LBB0_632
	s_add_i32 s13, 0, 0x23f20
	v_mov_b32_e32 v0, s13
	s_waitcnt vmcnt(0) expcnt(0) lgkmcnt(0)
	ds_read_b32 v2, v0
	s_add_i32 s13, 0, 0x23f24
	v_mov_b32_e32 v0, s13
	ds_read_b32 v0, v0
	s_waitcnt lgkmcnt(1)
	v_cmp_ne_u32_e32 vcc, 0, v2
	s_cbranch_vccnz .LBB0_596
	s_mov_b32 s13, 1
	v_mov_b32_e32 v16, 0
	s_branch .LBB0_584

; #define PG8_STAGE(bufoff, gbase, voff) do { _Pragma("unroll") for (int _i = 0; _i < 2; ++_i) \
;         __builtin_amdgcn_global_load_lds((const unsigned*)((const char*)(gbase) + (voff)[_i]), (PG8_LAS unsigned*)(lds + (bufoff) + ldsw + _i * 8192), 16, 0, 0); } while (0)
; #define PG8_LDA(dst, b, h) do { _Pragma("unroll") for (int m = 0; m < 4; ++m) _Pragma("unroll") for (int k = 0; k < 2; ++k) dst[m][k] = *(const PG8_LAS bf16x8*)(lds + PG8_SA(b, h) + aoff + m * 2048 + k * 1024); } while (0)
; template <class Epi, class Sched, bool ALIGN_EPI = false, bool SP2 = false>
; __device__ __forceinline__ void gemm_phase(PG8_LAS unsigned char* lds, const Gemm g, const Sched& S, const Epi& E) {
;     ...
;         const bool has_next = S.next(ui + 1, nxt);
;         const char* nA = has_next ? (const char*)g.A + (size_t)nxt.pm * tstep : cA; const char* nB = has_next ? (const char*)g.Bt + (size_t)nxt.pn * tstep : cB;
;         for (int t = 0; t < nt; t += 2) {
;             const bool last = (t == nt - 2);
;             const char* a1 = cA + (size_t)(t + 1) * kstep;
;             const char* a2 = last ? nA : cA + (size_t)(t + 2) * kstep; const char* b2 = last ? nB : cB + (size_t)(t + 2) * kstep;
;             const char* a3 = a2 + kstep; const char* b3 = b2 + kstep;
;             if (last && has_next) S.a_ready(nxt);
;             if constexpr (SP2) {
;             PG8_LDB(B0, 0, 0); PG8_LDB(B1, 0, 1); PG8_SCHED; PG8_LDA(At, 0, 0); PG8_STAGE(PG8_SA(1, 1), a1 + hstep, voffA);
;             PG8_WAIT_V(8); PG8_WAIT_L(0); PG8_BAR; PG8_MMA(0, 0, At, B0); PG8_MMA(0, 1, At, B1); PG8_BAR; PG8_SCHED;
;             PG8_LDA(At, 0, 1); PG8_STAGE(PG8_SB(0, 0), b2, voffB); PG8_STAGE(PG8_SB(0, 1), b2 + hstep, voffB); PG8_STAGE(PG8_SA(0, 0), a2, voffA);
;             PG8_WAIT_V(8); PG8_WAIT_L(0); PG8_BAR; PG8_MMA(1, 0, At, B0); PG8_MMA(1, 1, At, B1); PG8_BAR; PG8_SCHED;
;             PG8_LDB(B0, 1, 0); PG8_LDB(B1, 1, 1); PG8_SCHED; PG8_LDA(At, 1, 0); PG8_STAGE(PG8_SA(0, 1), a2 + hstep, voffA);
;             PG8_WAIT_V(8); PG8_WAIT_L(0); PG8_BAR; PG8_MMA(0, 0, At, B0); PG8_MMA(0, 1, At, B1); PG8_BAR; PG8_SCHED;
;             PG8_LDA(At, 1, 1); PG8_STAGE(PG8_SB(1, 0), b3, voffB); PG8_STAGE(PG8_SB(1, 1), b3 + hstep, voffB); PG8_STAGE(PG8_SA(1, 0), a3, voffA);
;             PG8_WAIT_V(8); PG8_WAIT_L(0); PG8_BAR; PG8_MMA(1, 0, At, B0); PG8_MMA(1, 1, At, B1); PG8_BAR; PG8_SCHED;
.LBB0_644:
	s_ashr_i32 s27, s26, 31
	s_lshl_b64 s[28:29], s[26:27], 20
	s_add_u32 s28, s13, s28
	s_addc_u32 s29, s47, s29
	s_and_b64 s[30:31], s[38:39], exec
	s_cselect_b32 s27, s29, s37
	s_cselect_b32 s70, s28, s36
	s_ashr_i32 s25, s24, 31
	s_lshl_b64 s[30:31], s[24:25], 20
	s_add_u32 s30, s52, s30
	s_addc_u32 s31, s53, s31
	s_and_b64 s[44:45], s[38:39], exec
	s_cselect_b32 s25, s31, s41
	s_cselect_b32 s71, s30, s40
	s_add_u32 s72, s40, 0x100
	s_addc_u32 s73, s41, 0
	s_mov_b32 s74, -2
	ds_read_b128 v[92:95], v196
	ds_read_b128 v[100:103], v196 offset:1024
	ds_read_b128 v[108:111], v196 offset:2048
	ds_read_b128 v[116:119], v196 offset:3072
	ds_read_b128 v[144:147], v197
	ds_read_b128 v[148:151], v197 offset:1024
	ds_read_b128 v[152:155], v197 offset:2048
	ds_read_b128 v[156:159], v197 offset:3072
	s_add_u32 s40, s36, 0x100
	s_addc_u32 s41, s37, 0
	s_cmp_eq_u32 s74, 28
	s_cselect_b32 s51, s27, s41
	s_cselect_b32 s50, s70, s40
	s_cselect_b32 s45, s25, s73
	s_cselect_b32 s44, s71, s72
	v_lshl_add_u64 v[212:213], s[36:37], 0, v[176:177]
	s_add_i32 m0, s55, 0xc000
	ds_read_b128 v[160:163], v198
	ds_read_b128 v[164:167], v198 offset:1024
	ds_read_b128 v[168:171], v198 offset:2048
	ds_read_b128 v[184:187], v198 offset:3072
	ds_read_b128 v[188:191], v198 offset:4096
	ds_read_b128 v[200:203], v198 offset:5120
	ds_read_b128 v[204:207], v198 offset:6144
	ds_read_b128 v[208:211], v198 offset:7168
	global_load_lds_dwordx4 v[212:213], off
	v_lshl_add_u64 v[212:213], s[36:37], 0, v[178:179]
	s_add_i32 m0, s55, 0xe000
	s_nop 0
	global_load_lds_dwordx4 v[212:213], off
	s_waitcnt vmcnt(8)
	s_waitcnt lgkmcnt(0)
	s_barrier
	s_setprio 1
	s_waitcnt lgkmcnt(0)
	v_mfma_f32_16x16x32_bf16 v[140:143], v[92:95], v[160:163], 0
	v_mfma_f32_16x16x32_bf16 v[136:139], v[108:111], v[160:163], 0
	v_mfma_f32_16x16x32_bf16 v[132:135], v[92:95], v[168:171], 0
	v_mfma_f32_16x16x32_bf16 v[120:123], v[108:111], v[168:171], 0
	v_mfma_f32_16x16x32_bf16 v[112:115], v[92:95], v[188:191], 0
	v_mfma_f32_16x16x32_bf16 v[88:91], v[108:111], v[188:191], 0
	v_mfma_f32_16x16x32_bf16 v[76:79], v[92:95], v[204:207], 0
	v_mfma_f32_16x16x32_bf16 v[72:75], v[108:111], v[204:207], 0
	v_mfma_f32_16x16x32_bf16 v[140:143], v[100:103], v[164:167], v[140:143]
	v_mfma_f32_16x16x32_bf16 v[136:139], v[116:119], v[164:167], v[136:139]
	v_mfma_f32_16x16x32_bf16 v[132:135], v[100:103], v[184:187], v[132:135]
	v_mfma_f32_16x16x32_bf16 v[120:123], v[116:119], v[184:187], v[120:123]
	v_mfma_f32_16x16x32_bf16 v[112:115], v[100:103], v[200:203], v[112:115]
	v_mfma_f32_16x16x32_bf16 v[88:91], v[116:119], v[200:203], v[88:91]
	v_mfma_f32_16x16x32_bf16 v[76:79], v[100:103], v[208:211], v[76:79]
	v_mfma_f32_16x16x32_bf16 v[72:75], v[116:119], v[208:211], v[72:75]
	s_setprio 0
	s_setprio 1
	v_mfma_f32_16x16x32_bf16 v[128:131], v[144:147], v[160:163], 0
	v_mfma_f32_16x16x32_bf16 v[124:127], v[152:155], v[160:163], 0
	v_mfma_f32_16x16x32_bf16 v[104:107], v[144:147], v[168:171], 0
	v_mfma_f32_16x16x32_bf16 v[96:99], v[152:155], v[168:171], 0
	v_mfma_f32_16x16x32_bf16 v[84:87], v[144:147], v[188:191], 0
	v_mfma_f32_16x16x32_bf16 v[80:83], v[152:155], v[188:191], 0
	v_mfma_f32_16x16x32_bf16 v[68:71], v[144:147], v[204:207], 0
	v_mfma_f32_16x16x32_bf16 v[64:67], v[152:155], v[204:207], 0
	v_mfma_f32_16x16x32_bf16 v[128:131], v[148:151], v[164:167], v[128:131]
	v_mfma_f32_16x16x32_bf16 v[124:127], v[156:159], v[164:167], v[124:127]
	v_mfma_f32_16x16x32_bf16 v[104:107], v[148:151], v[184:187], v[104:107]
	v_mfma_f32_16x16x32_bf16 v[96:99], v[156:159], v[184:187], v[96:99]
	v_mfma_f32_16x16x32_bf16 v[84:87], v[148:151], v[200:203], v[84:87]
	v_mfma_f32_16x16x32_bf16 v[80:83], v[156:159], v[200:203], v[80:83]
	v_mfma_f32_16x16x32_bf16 v[68:71], v[148:151], v[208:211], v[68:71]
	v_mfma_f32_16x16x32_bf16 v[64:67], v[156:159], v[208:211], v[64:67]
	s_setprio 0
	s_barrier
	s_add_i32 s36, s68, s54
	v_lshl_add_u64 v[212:213], s[44:45], 0, v[174:175]
	s_mov_b32 m0, s36
	ds_read_b128 v[160:163], v198 offset:16384
	ds_read_b128 v[164:167], v198 offset:17408
	ds_read_b128 v[168:171], v198 offset:18432
	ds_read_b128 v[184:187], v198 offset:19456
	ds_read_b128 v[188:191], v198 offset:20480
	ds_read_b128 v[200:203], v198 offset:21504
	ds_read_b128 v[204:207], v198 offset:22528
	ds_read_b128 v[208:211], v198 offset:23552
	global_load_lds_dwordx4 v[212:213], off
	s_add_i32 m0, s36, 0x2000
	s_add_u32 s36, s44, 0x80000
	v_lshl_add_u64 v[214:215], s[44:45], 0, v[172:173]
	s_addc_u32 s37, s45, 0
	s_add_i32 s75, s69, s54
	global_load_lds_dwordx4 v[214:215], off
	v_lshl_add_u64 v[218:219], s[36:37], 0, v[174:175]
	s_mov_b32 m0, s75
	v_lshl_add_u64 v[220:221], s[50:51], 0, v[172:173]
	global_load_lds_dwordx4 v[218:219], off
	v_lshl_add_u64 v[218:219], s[36:37], 0, v[172:173]
	s_add_i32 m0, s75, 0x2000
	s_nop 0
	global_load_lds_dwordx4 v[218:219], off
	v_lshl_add_u64 v[218:219], s[50:51], 0, v[174:175]
	s_mov_b32 m0, s55
	s_nop 0
	global_load_lds_dwordx4 v[218:219], off
	s_mov_b32 m0, s60
	s_nop 0
	global_load_lds_dwordx4 v[220:221], off
	s_waitcnt vmcnt(8)
	s_waitcnt lgkmcnt(0)
	s_barrier
; #define PG8_STAGE(bufoff, gbase, voff) do { _Pragma("unroll") for (int _i = 0; _i < 2; ++_i) \
;         __builtin_amdgcn_global_load_lds((const unsigned*)((const char*)(gbase) + (voff)[_i]), (PG8_LAS unsigned*)(lds + (bufoff) + ldsw + _i * 8192), 16, 0, 0); } while (0)
; #define PG8_LDA(dst, b, h) do { _Pragma("unroll") for (int m = 0; m < 4; ++m) _Pragma("unroll") for (int k = 0; k < 2; ++k) dst[m][k] = *(const PG8_LAS bf16x8*)(lds + PG8_SA(b, h) + aoff + m * 2048 + k * 1024); } while (0)
; #define PG8_LDB(dst, b, h) do { _Pragma("unroll") for (int n = 0; n < 2; ++n) _Pragma("unroll") for (int k = 0; k < 2; ++k) dst[n][k] = *(const PG8_LAS bf16x8*)(lds + PG8_SB(b, h) + boff + n * 2048 + k * 1024); } while (0)
; #define PG8_MMA(ai, bj, At, Bt) do { __builtin_amdgcn_s_setprio(1); _Pragma("unroll") for (int m = 0; m < 4; ++m) _Pragma("unroll") for (int n = 0; n < 2; ++n) _Pragma("unroll") for (int k = 0; k < 2; ++k) \
;         acc[ai][bj][m][n] = __builtin_amdgcn_mfma_f32_16x16x32_bf16(Bt[n][k], At[m][k], acc[ai][bj][m][n], 0, 0, 0); __builtin_amdgcn_s_setprio(0); } while (0)
; #define PG8_WAIT_V(n) asm volatile("s_waitcnt vmcnt(" #n ")" ::: "memory")
; #define PG8_WAIT_L(n) asm volatile("s_waitcnt lgkmcnt(" #n ")" ::: "memory")
; #define PG8_BAR __builtin_amdgcn_s_barrier()
; #define PG8_SCHED __builtin_amdgcn_sched_barrier(0)
; template <class Epi, class Sched, bool ALIGN_EPI = false, bool SP2 = false>
; __device__ __forceinline__ void gemm_phase(PG8_LAS unsigned char* lds, const Gemm g, const Sched& S, const Epi& E) {
;     ...
;             PG8_WAIT_V(8); PG8_WAIT_L(0); PG8_BAR; PG8_MMA(1, 0, At, B0); PG8_MMA(1, 1, At, B1); PG8_BAR; PG8_SCHED;
;             PG8_LDB(B0, 1, 0); PG8_LDB(B1, 1, 1); PG8_SCHED; PG8_LDA(At, 1, 0); PG8_STAGE(PG8_SA(0, 1), a2 + hstep, voffA);
;             PG8_WAIT_V(8); PG8_WAIT_L(0); PG8_BAR; PG8_MMA(0, 0, At, B0); PG8_MMA(0, 1, At, B1); PG8_BAR; PG8_SCHED;
	s_setprio 1
	s_waitcnt lgkmcnt(0)
	v_mfma_f32_16x16x32_bf16 v[60:63], v[92:95], v[160:163], 0
	v_mfma_f32_16x16x32_bf16 v[56:59], v[108:111], v[160:163], 0
	v_mfma_f32_16x16x32_bf16 v[52:55], v[92:95], v[168:171], 0
	v_mfma_f32_16x16x32_bf16 v[40:43], v[108:111], v[168:171], 0
	v_mfma_f32_16x16x32_bf16 v[36:39], v[92:95], v[188:191], 0
	v_mfma_f32_16x16x32_bf16 v[24:27], v[108:111], v[188:191], 0
	v_mfma_f32_16x16x32_bf16 v[12:15], v[92:95], v[204:207], 0
	v_mfma_f32_16x16x32_bf16 v[8:11], v[108:111], v[204:207], 0
	v_mfma_f32_16x16x32_bf16 v[60:63], v[100:103], v[164:167], v[60:63]
	v_mfma_f32_16x16x32_bf16 v[56:59], v[116:119], v[164:167], v[56:59]
	v_mfma_f32_16x16x32_bf16 v[52:55], v[100:103], v[184:187], v[52:55]
	v_mfma_f32_16x16x32_bf16 v[40:43], v[116:119], v[184:187], v[40:43]
	v_mfma_f32_16x16x32_bf16 v[36:39], v[100:103], v[200:203], v[36:39]
	v_mfma_f32_16x16x32_bf16 v[24:27], v[116:119], v[200:203], v[24:27]
	v_mfma_f32_16x16x32_bf16 v[12:15], v[100:103], v[208:211], v[12:15]
	v_mfma_f32_16x16x32_bf16 v[8:11], v[116:119], v[208:211], v[8:11]
	s_setprio 0
	s_setprio 1
	v_mfma_f32_16x16x32_bf16 v[48:51], v[144:147], v[160:163], 0
	v_mfma_f32_16x16x32_bf16 v[44:47], v[152:155], v[160:163], 0
	v_mfma_f32_16x16x32_bf16 v[32:35], v[144:147], v[168:171], 0
	v_mfma_f32_16x16x32_bf16 v[28:31], v[152:155], v[168:171], 0
	v_mfma_f32_16x16x32_bf16 v[20:23], v[144:147], v[188:191], 0
	v_mfma_f32_16x16x32_bf16 v[16:19], v[152:155], v[188:191], 0
	v_mfma_f32_16x16x32_bf16 v[4:7], v[144:147], v[204:207], 0
	v_mfma_f32_16x16x32_bf16 v[0:3], v[152:155], v[204:207], 0
	v_mfma_f32_16x16x32_bf16 v[48:51], v[148:151], v[164:167], v[48:51]
	v_mfma_f32_16x16x32_bf16 v[44:47], v[156:159], v[164:167], v[44:47]
	v_mfma_f32_16x16x32_bf16 v[32:35], v[148:151], v[184:187], v[32:35]
	v_mfma_f32_16x16x32_bf16 v[28:31], v[156:159], v[184:187], v[28:31]
	v_mfma_f32_16x16x32_bf16 v[20:23], v[148:151], v[200:203], v[20:23]
	v_mfma_f32_16x16x32_bf16 v[16:19], v[156:159], v[200:203], v[16:19]
	v_mfma_f32_16x16x32_bf16 v[4:7], v[148:151], v[208:211], v[4:7]
	v_mfma_f32_16x16x32_bf16 v[0:3], v[156:159], v[208:211], v[0:3]
	s_setprio 0
	s_barrier
	s_add_i32 s75, 0, 0x18000
	s_add_i32 s76, 0, 0x1c000
	v_add_u32_e32 v116, s75, v194
	v_add_u32_e32 v156, s76, v194
	ds_read_b128 v[92:95], v116
	ds_read_b128 v[100:103], v116 offset:1024
	ds_read_b128 v[108:111], v116 offset:2048
	ds_read_b128 v[116:119], v116 offset:3072
	ds_read_b128 v[144:147], v156
	ds_read_b128 v[148:151], v156 offset:1024
	ds_read_b128 v[152:155], v156 offset:2048
	ds_read_b128 v[156:159], v156 offset:3072
	s_add_u32 s36, s50, 0x80000
	s_addc_u32 s37, s51, 0
	s_mov_b32 m0, s61
	v_lshl_add_u64 v[222:223], s[36:37], 0, v[174:175]
	ds_read_b128 v[160:163], v198 offset:32768
	ds_read_b128 v[164:167], v198 offset:33792
	ds_read_b128 v[168:171], v198 offset:34816
	ds_read_b128 v[184:187], v198 offset:35840
	ds_read_b128 v[188:191], v198 offset:36864
	ds_read_b128 v[200:203], v198 offset:37888
	ds_read_b128 v[204:207], v198 offset:38912
	ds_read_b128 v[208:211], v198 offset:39936
	global_load_lds_dwordx4 v[222:223], off
	v_lshl_add_u64 v[222:223], s[36:37], 0, v[172:173]
	s_mov_b32 m0, s62
	s_nop 0
	global_load_lds_dwordx4 v[222:223], off
	s_waitcnt vmcnt(8)
	s_waitcnt lgkmcnt(0)
	s_barrier
	s_setprio 1
	s_waitcnt lgkmcnt(0)
	v_mfma_f32_16x16x32_bf16 v[140:143], v[92:95], v[160:163], v[140:143]
	v_mfma_f32_16x16x32_bf16 v[136:139], v[108:111], v[160:163], v[136:139]
	v_mfma_f32_16x16x32_bf16 v[132:135], v[92:95], v[168:171], v[132:135]
	v_mfma_f32_16x16x32_bf16 v[120:123], v[108:111], v[168:171], v[120:123]
	v_mfma_f32_16x16x32_bf16 v[112:115], v[92:95], v[188:191], v[112:115]
	v_mfma_f32_16x16x32_bf16 v[88:91], v[108:111], v[188:191], v[88:91]
	v_mfma_f32_16x16x32_bf16 v[76:79], v[92:95], v[204:207], v[76:79]
	v_mfma_f32_16x16x32_bf16 v[72:75], v[108:111], v[204:207], v[72:75]
	v_mfma_f32_16x16x32_bf16 v[140:143], v[100:103], v[164:167], v[140:143]
	v_mfma_f32_16x16x32_bf16 v[136:139], v[116:119], v[164:167], v[136:139]
	v_mfma_f32_16x16x32_bf16 v[132:135], v[100:103], v[184:187], v[132:135]
	v_mfma_f32_16x16x32_bf16 v[120:123], v[116:119], v[184:187], v[120:123]
	v_mfma_f32_16x16x32_bf16 v[112:115], v[100:103], v[200:203], v[112:115]
	v_mfma_f32_16x16x32_bf16 v[88:91], v[116:119], v[200:203], v[88:91]
	v_mfma_f32_16x16x32_bf16 v[76:79], v[100:103], v[208:211], v[76:79]
	v_mfma_f32_16x16x32_bf16 v[72:75], v[116:119], v[208:211], v[72:75]
	s_setprio 0
	s_setprio 1
	v_mfma_f32_16x16x32_bf16 v[128:131], v[144:147], v[160:163], v[128:131]
	v_mfma_f32_16x16x32_bf16 v[124:127], v[152:155], v[160:163], v[124:127]
	v_mfma_f32_16x16x32_bf16 v[104:107], v[144:147], v[168:171], v[104:107]
	v_mfma_f32_16x16x32_bf16 v[96:99], v[152:155], v[168:171], v[96:99]
	v_mfma_f32_16x16x32_bf16 v[84:87], v[144:147], v[188:191], v[84:87]
	v_mfma_f32_16x16x32_bf16 v[80:83], v[152:155], v[188:191], v[80:83]
	v_mfma_f32_16x16x32_bf16 v[68:71], v[144:147], v[204:207], v[68:71]
	v_mfma_f32_16x16x32_bf16 v[64:67], v[152:155], v[204:207], v[64:67]
	v_mfma_f32_16x16x32_bf16 v[128:131], v[148:151], v[164:167], v[128:131]
	v_mfma_f32_16x16x32_bf16 v[124:127], v[156:159], v[164:167], v[124:127]
	v_mfma_f32_16x16x32_bf16 v[104:107], v[148:151], v[184:187], v[104:107]
	v_mfma_f32_16x16x32_bf16 v[96:99], v[156:159], v[184:187], v[96:99]
	v_mfma_f32_16x16x32_bf16 v[84:87], v[148:151], v[200:203], v[84:87]
	v_mfma_f32_16x16x32_bf16 v[80:83], v[156:159], v[200:203], v[80:83]
	v_mfma_f32_16x16x32_bf16 v[68:71], v[148:151], v[208:211], v[68:71]
	v_mfma_f32_16x16x32_bf16 v[64:67], v[156:159], v[208:211], v[64:67]
	s_setprio 0
	s_barrier
; #define PG8_STAGE(bufoff, gbase, voff) do { _Pragma("unroll") for (int _i = 0; _i < 2; ++_i) \
;         __builtin_amdgcn_global_load_lds((const unsigned*)((const char*)(gbase) + (voff)[_i]), (PG8_LAS unsigned*)(lds + (bufoff) + ldsw + _i * 8192), 16, 0, 0); } while (0)
; #define PG8_LDA(dst, b, h) do { _Pragma("unroll") for (int m = 0; m < 4; ++m) _Pragma("unroll") for (int k = 0; k < 2; ++k) dst[m][k] = *(const PG8_LAS bf16x8*)(lds + PG8_SA(b, h) + aoff + m * 2048 + k * 1024); } while (0)
; #define PG8_MMA(ai, bj, At, Bt) do { __builtin_amdgcn_s_setprio(1); _Pragma("unroll") for (int m = 0; m < 4; ++m) _Pragma("unroll") for (int n = 0; n < 2; ++n) _Pragma("unroll") for (int k = 0; k < 2; ++k) \
;         acc[ai][bj][m][n] = __builtin_amdgcn_mfma_f32_16x16x32_bf16(Bt[n][k], At[m][k], acc[ai][bj][m][n], 0, 0, 0); __builtin_amdgcn_s_setprio(0); } while (0)
; #define PG8_WAIT_V(n) asm volatile("s_waitcnt vmcnt(" #n ")" ::: "memory")
; #define PG8_WAIT_L(n) asm volatile("s_waitcnt lgkmcnt(" #n ")" ::: "memory")
; #define PG8_BAR __builtin_amdgcn_s_barrier()
; #define PG8_SCHED __builtin_amdgcn_sched_barrier(0)
; template <class Epi, class Sched, bool ALIGN_EPI = false, bool SP2 = false>
; __device__ __forceinline__ void gemm_phase(PG8_LAS unsigned char* lds, const Gemm g, const Sched& S, const Epi& E) {
;     ...
;         for (int t = 0; t < nt; t += 2) {
;     ...
;             PG8_LDA(At, 1, 1); PG8_STAGE(PG8_SB(1, 0), b3, voffB); PG8_STAGE(PG8_SB(1, 1), b3 + hstep, voffB); PG8_STAGE(PG8_SA(1, 0), a3, voffA);
;             PG8_WAIT_V(8); PG8_WAIT_L(0); PG8_BAR; PG8_MMA(1, 0, At, B0); PG8_MMA(1, 1, At, B1); PG8_BAR; PG8_SCHED;
	s_add_i32 s36, s75, s54
	v_lshl_add_u64 v[212:213], v[212:213], 0, s[20:21]
	s_mov_b32 m0, s36
	ds_read_b128 v[160:163], v198 offset:49152
	ds_read_b128 v[164:167], v198 offset:50176
	ds_read_b128 v[168:171], v198 offset:51200
	ds_read_b128 v[184:187], v198 offset:52224
	ds_read_b128 v[188:191], v198 offset:53248
	ds_read_b128 v[200:203], v198 offset:54272
	ds_read_b128 v[204:207], v198 offset:55296
	ds_read_b128 v[208:211], v198 offset:56320
	global_load_lds_dwordx4 v[212:213], off
	s_add_i32 m0, s36, 0x2000
	s_add_u32 s36, s44, 0x80080
	v_lshl_add_u64 v[212:213], v[214:215], 0, s[20:21]
	s_addc_u32 s37, s45, 0
	s_add_i32 s44, s76, s54
	global_load_lds_dwordx4 v[212:213], off
	v_lshl_add_u64 v[212:213], s[36:37], 0, v[174:175]
	s_mov_b32 m0, s44
	s_nop 0
	global_load_lds_dwordx4 v[212:213], off
	v_lshl_add_u64 v[212:213], s[36:37], 0, v[172:173]
	s_add_i32 m0, s44, 0x2000
	s_nop 0
	global_load_lds_dwordx4 v[212:213], off
	v_lshl_add_u64 v[212:213], v[218:219], 0, s[20:21]
	s_mov_b32 m0, s66
	s_nop 0
	global_load_lds_dwordx4 v[212:213], off
	v_lshl_add_u64 v[212:213], v[220:221], 0, s[20:21]
	s_mov_b32 m0, s67
	s_nop 0
	global_load_lds_dwordx4 v[212:213], off
	s_waitcnt vmcnt(8)
	s_waitcnt lgkmcnt(0)
	s_barrier
	s_setprio 1
	s_waitcnt lgkmcnt(0)
	v_mfma_f32_16x16x32_bf16 v[60:63], v[92:95], v[160:163], v[60:63]
	v_mfma_f32_16x16x32_bf16 v[56:59], v[108:111], v[160:163], v[56:59]
	v_mfma_f32_16x16x32_bf16 v[52:55], v[92:95], v[168:171], v[52:55]
	v_mfma_f32_16x16x32_bf16 v[40:43], v[108:111], v[168:171], v[40:43]
	v_mfma_f32_16x16x32_bf16 v[36:39], v[92:95], v[188:191], v[36:39]
	v_mfma_f32_16x16x32_bf16 v[24:27], v[108:111], v[188:191], v[24:27]
	v_mfma_f32_16x16x32_bf16 v[12:15], v[92:95], v[204:207], v[12:15]
	v_mfma_f32_16x16x32_bf16 v[8:11], v[108:111], v[204:207], v[8:11]
	v_mfma_f32_16x16x32_bf16 v[60:63], v[100:103], v[164:167], v[60:63]
	v_mfma_f32_16x16x32_bf16 v[56:59], v[116:119], v[164:167], v[56:59]
	v_mfma_f32_16x16x32_bf16 v[52:55], v[100:103], v[184:187], v[52:55]
	v_mfma_f32_16x16x32_bf16 v[40:43], v[116:119], v[184:187], v[40:43]
	v_mfma_f32_16x16x32_bf16 v[36:39], v[100:103], v[200:203], v[36:39]
	v_mfma_f32_16x16x32_bf16 v[24:27], v[116:119], v[200:203], v[24:27]
	v_mfma_f32_16x16x32_bf16 v[12:15], v[100:103], v[208:211], v[12:15]
	v_mfma_f32_16x16x32_bf16 v[8:11], v[116:119], v[208:211], v[8:11]
	s_setprio 0
	s_setprio 1
	v_mfma_f32_16x16x32_bf16 v[48:51], v[144:147], v[160:163], v[48:51]
	v_mfma_f32_16x16x32_bf16 v[44:47], v[152:155], v[160:163], v[44:47]
	v_mfma_f32_16x16x32_bf16 v[32:35], v[144:147], v[168:171], v[32:35]
	v_mfma_f32_16x16x32_bf16 v[28:31], v[152:155], v[168:171], v[28:31]
	v_mfma_f32_16x16x32_bf16 v[20:23], v[144:147], v[188:191], v[20:23]
	v_mfma_f32_16x16x32_bf16 v[16:19], v[152:155], v[188:191], v[16:19]
	v_mfma_f32_16x16x32_bf16 v[4:7], v[144:147], v[204:207], v[4:7]
	v_mfma_f32_16x16x32_bf16 v[0:3], v[152:155], v[204:207], v[0:3]
	v_mfma_f32_16x16x32_bf16 v[48:51], v[148:151], v[164:167], v[48:51]
	v_mfma_f32_16x16x32_bf16 v[44:47], v[156:159], v[164:167], v[44:47]
	v_mfma_f32_16x16x32_bf16 v[32:35], v[148:151], v[184:187], v[32:35]
	v_mfma_f32_16x16x32_bf16 v[28:31], v[156:159], v[184:187], v[28:31]
	v_mfma_f32_16x16x32_bf16 v[20:23], v[148:151], v[200:203], v[20:23]
	v_mfma_f32_16x16x32_bf16 v[16:19], v[156:159], v[200:203], v[16:19]
	v_mfma_f32_16x16x32_bf16 v[4:7], v[148:151], v[208:211], v[4:7]
	v_mfma_f32_16x16x32_bf16 v[0:3], v[156:159], v[208:211], v[0:3]
	s_setprio 0
	s_barrier
	s_add_i32 s74, s74, 2
	s_add_u32 s72, s72, 0x100
	s_addc_u32 s73, s73, 0
	s_cmp_gt_u32 s74, 29
	s_mov_b64 s[36:37], s[40:41]

; #define PG8_WAIT_V(n) asm volatile("s_waitcnt vmcnt(" #n ")" ::: "memory")
; #define PG8_BAR __builtin_amdgcn_s_barrier()
; #define WSP(off) ((bf16*)((unsigned char*)kargp(25) + (off)))
; template <class Epi, class Sched, bool ALIGN_EPI = false, bool SP2 = false>
; __device__ __forceinline__ void gemm_phase(PG8_LAS unsigned char* lds, const Gemm g, const Sched& S, const Epi& E) {
;     ...
;     const int tid = tid_, wid = __builtin_amdgcn_readfirstlane(tid >> 6), lane = tid & 63, wr = wid >> 2, wc = wid & 3, fr = lane & 15, fq = lane >> 4;
;     const int K = g.K, nt = K / BK;
;     unsigned voffA[2], voffB[2];
; #pragma unroll
;     for (int i = 0; i < 2; ++i) { int R, C; stage_rc(tid * 16 + i * 8192, R, C); const int Rb = Epi::PERM ? ((R & ~31) + perm32(R & 31)) : R;
;         voffA[i] = (unsigned)(R * K + C) * 2u; voffB[i] = (unsigned)(Rb * K + C) * 2u; }
;     const size_t kstep = (size_t)(BK * 2);
;     const size_t hstep = (size_t)HALF * K * 2;
;     const size_t tstep = 2 * hstep;
;     const unsigned ldsw = (unsigned)wid * 1024u;
;     const int aoff = lds_byte(wr * 64 + fr, fq * 8), boff = lds_byte(wc * 32 + fr, fq * 8);
;     ...
;     Unit cur, nxt; int ui = 0;
;     if (!S.next(0, cur)) return;
;     f32x4 acc[2][2][4][2];
; #pragma unroll
;     for (int a = 0; a < 2; ++a)
; #pragma unroll
;         for (int b = 0; b < 2; ++b)
; #pragma unroll
;             for (int m = 0; m < 4; ++m)
; #pragma unroll
;                 for (int n = 0; n < 2; ++n) acc[a][b][m][n] = (f32x4){0.f, 0.f, 0.f, 0.f};
;     bf16x8 At[4][2], B0[2][2], B1[2][2];
;     const char* cA = (const char*)g.A + (size_t)cur.pm * tstep; const char* cB = (const char*)g.Bt + (size_t)cur.pn * tstep;
;     S.a_ready(cur);
;     if constexpr (SP2) {
;         PG8_STAGE(PG8_SB(0, 0), cB, voffB); PG8_STAGE(PG8_SB(0, 1), cB + hstep, voffB); PG8_STAGE(PG8_SA(0, 0), cA, voffA); PG8_STAGE(PG8_SA(0, 1), cA + hstep, voffA);
;         if (wr == 1) PG8_BAR;
;         PG8_WAIT_V(2); PG8_BAR;
; __global__ void __launch_bounds__(NTHR, 2) mega_fwd(Args args) {
;     ...
;         bf16* XN = WSP(WS_XN); bf16* W1 = WSP(WS_W1); bf16* HB = WSP(WS_HB);
;         pg8::Gemm g{XN, W1, T, FF, DM}; pg8::StaticOrder S; S.init(T, FF, G, bx, WGM_P9);
;         pg8::EpiRelu2 E{HB, FF};
;         pg8::gemm_phase<pg8::EpiRelu2, pg8::StaticOrder, true, true>(L, g, S, E);
.LBB0_762:
	s_or_b64 exec, exec, s[12:13]
	s_nop 0
	s_nop 0
	s_nop 0
	s_nop 0
	s_nop 0
	s_nop 0
	s_nop 0
	s_nop 0
	s_nop 0
	s_nop 0
	s_nop 0
	s_nop 0
	s_nop 0
	s_nop 0
	s_nop 0
	s_nop 0
	s_nop 0
	s_nop 0
	s_nop 0
	s_nop 0
	s_mov_b64 s[14:15], s[0:1]
	s_mov_b64 s[16:17], s[0:1]
	s_mov_b64 s[12:13], s[0:1]
	v_mov_b32_e32 v14, v216
	s_waitcnt lgkmcnt(0)
	s_barrier
	s_cmpk_lt_i32 s2, 0x1000
	s_nop 0
	v_readfirstlane_b32 s18, v14
	s_cbranch_scc0 .LBB0_782
	v_lshlrev_b32_e32 v0, 4, v14
	v_add_u32_e32 v1, 0x2000, v0
	v_ashrrev_i32_e32 v2, 31, v1
	v_lshrrev_b32_e32 v2, 22, v2
	v_add_u32_e32 v2, v1, v2
	v_ashrrev_i32_e32 v8, 10, v2
	v_mul_i32_i24_e32 v2, 0x400, v8
	v_sub_u32_e32 v1, v1, v2
	v_lshrrev_b32_e32 v2, 4, v1
	v_bitop3_b32 v1, v2, v1, 32 bitop3:0x6c
	v_ashrrev_i32_e32 v2, 31, v1
	s_load_dwordx2 s[14:15], s[14:15], 0xc8
	s_nop 0
	s_load_dwordx2 s[16:17], s[16:17], 0xc8
	v_lshrrev_b32_e32 v2, 26, v2
	v_add_u32_e32 v2, v1, v2
	v_lshlrev_b32_e32 v3, 3, v8
	v_ashrrev_i32_e32 v9, 6, v2
	v_and_b32_e32 v3, -16, v3
	v_add_u32_e32 v3, v9, v3
	s_waitcnt lgkmcnt(0)
	s_add_u32 s40, s14, 0x7800000
	v_and_b32_e32 v4, 3, v9
	s_mov_b32 s14, 0xfffe0
	v_lshrrev_b32_e32 v5, 2, v3
	v_lshlrev_b32_e32 v6, 1, v3
	v_and_b32_e32 v2, 0xc0, v2
	v_and_or_b32 v4, v3, s14, v4
	v_and_b32_e32 v5, 4, v5
	v_and_b32_e32 v6, 24, v6
	v_sub_u32_e32 v1, v1, v2
	v_mov_b32_e32 v2, 1
	v_or3_b32 v4, v4, v5, v6
	v_lshlrev_b32_e32 v5, 5, v8
	v_ashrrev_i16_sdwa v1, v2, sext(v1) dst_sel:DWORD dst_unused:UNUSED_PAD src0_sel:DWORD src1_sel:BYTE_0
	v_and_b32_e32 v5, 32, v5
	v_bfe_i32 v10, v1, 0, 16
	v_add_lshl_u32 v1, v5, v10, 1
	s_waitcnt vmcnt(0)
	v_lshl_add_u32 v128, v4, 12, v1
	v_lshl_add_u32 v130, v3, 12, v1
	v_bfe_i32 v1, v14, 27, 1
	v_lshrrev_b32_e32 v1, 22, v1
	v_add_u32_e32 v1, v0, v1
	v_and_b32_e32 v1, 0xfffffc00, v1
	v_sub_u32_e32 v0, v0, v1
	v_lshrrev_b32_e32 v1, 4, v0
	v_ashrrev_i32_e32 v3, 31, v14
	v_bitop3_b32 v0, v1, v0, 32 bitop3:0x6c
	v_lshrrev_b32_e32 v3, 26, v3
	v_ashrrev_i32_e32 v1, 31, v0
	v_add_u32_e32 v3, v14, v3
	s_addc_u32 s41, s15, 0
	v_lshrrev_b32_e32 v1, 26, v1
	v_ashrrev_i32_e32 v12, 6, v3
	s_add_u32 s44, s16, 0x3600000
	v_add_u32_e32 v1, v0, v1
	v_lshlrev_b32_e32 v3, 3, v12
	s_addc_u32 s45, s17, 0
	s_ashr_i32 s19, s18, 6
	v_ashrrev_i32_e32 v11, 6, v1
	v_and_b32_e32 v3, -16, v3
	s_ashr_i32 s20, s18, 8
	s_lshl_b32 s47, s19, 10
	v_add_u32_e32 v3, v11, v3
	v_and_b32_e32 v4, 3, v11
	s_lshl_b32 s17, s59, 9
	v_and_or_b32 v4, v3, s14, v4
	s_mul_i32 s16, s59, 0x201
	s_and_b64 s[14:15], s[42:43], exec
	s_cselect_b32 s14, s16, s17
	s_add_i32 s14, s14, s56
	s_ashr_i32 s15, s14, 31
	s_lshr_b32 s15, s15, 24
	s_add_i32 s15, s14, s15
	s_ashr_i32 s16, s15, 8
	s_and_b32 s15, s15, 0xff00
	s_sub_i32 s15, s14, s15
	s_sext_i32_i16 s14, s15
	s_bfe_u32 s14, s14, 0x3001c
	s_add_i32 s17, s15, s14
	s_sext_i32_i16 s14, s17
	s_and_b32 s17, s17, 0xfff8
	s_sub_i32 s15, s15, s17
	s_lshl_b32 s16, s16, 3
	s_sext_i32_i16 s15, s15
	v_lshrrev_b32_e32 v5, 2, v3
	v_lshlrev_b32_e32 v6, 1, v3
	v_and_b32_e32 v1, 0xc0, v1
	s_lshr_b32 s14, s14, 3
	s_add_i32 s28, s16, s15
	v_and_b32_e32 v5, 4, v5
	v_and_b32_e32 v6, 24, v6
	v_sub_u32_e32 v0, v0, v1
	s_ashr_i32 s29, s28, 31
	s_bfe_i64 s[22:23], s[14:15], 0x100000
	v_or3_b32 v4, v4, v5, v6
	v_lshlrev_b32_e32 v5, 5, v12
	v_ashrrev_i16_sdwa v0, v2, sext(v0) dst_sel:DWORD dst_unused:UNUSED_PAD src0_sel:DWORD src1_sel:BYTE_0
	s_lshl_b64 s[16:17], s[28:29], 20
	s_lshl_b64 s[22:23], s[22:23], 20
	v_and_b32_e32 v5, 32, v5
	v_bfe_i32 v13, v0, 0, 16
	s_add_u32 s34, s44, s22
	v_add_lshl_u32 v0, v5, v13, 1
	s_addc_u32 s35, s45, s23
	s_add_i32 s50, s47, 0
	v_lshl_add_u32 v132, v4, 12, v0
	s_add_i32 m0, s50, 0x10000
	v_lshl_add_u32 v134, v3, 12, v0
	global_load_lds_dwordx4 v132, s[34:35]
	s_add_i32 m0, s50, 0x12000
	s_add_u32 s22, s34, 0x80000
	global_load_lds_dwordx4 v128, s[34:35]
	s_addc_u32 s23, s35, 0
	s_add_i32 m0, s50, 0x14000
	v_mov_b32_e32 v133, 0
	global_load_lds_dwordx4 v132, s[22:23]
	s_add_i32 m0, s50, 0x16000
	s_add_u32 s30, s40, s16
	s_addc_u32 s31, s41, s17
	s_add_i32 s51, s50, 0x2000
	global_load_lds_dwordx4 v128, s[22:23]
	s_mov_b32 m0, s50
	s_add_u32 s16, s30, 0x80000
	global_load_lds_dwordx4 v134, s[30:31]
	s_mov_b32 m0, s51
	s_addc_u32 s17, s31, 0
	s_add_i32 s52, s50, 0x4000
	global_load_lds_dwordx4 v130, s[30:31]
	s_mov_b32 m0, s52
	s_add_i32 s53, s50, 0x6000
	global_load_lds_dwordx4 v134, s[16:17]
	s_mov_b32 m0, s53
	v_mov_b32_e32 v129, v133
	global_load_lds_dwordx4 v130, s[16:17]
	s_load_dwordx2 s[16:17], s[12:13], 0xc8
	v_mov_b32_e32 v135, v133
	v_mov_b32_e32 v131, v133
	s_cmp_eq_u32 s20, 1
	s_mov_b32 s54, 0
	v_lshl_add_u64 v[6:7], s[34:35], 0, v[132:133]
	v_lshl_add_u64 v[4:5], s[34:35], 0, v[128:129]
	v_lshl_add_u64 v[0:1], s[30:31], 0, v[134:135]
	s_cselect_b64 s[12:13], -1, 0
	s_cmp_lg_u32 s20, 1
	v_lshl_add_u64 v[2:3], s[30:31], 0, v[130:131]
	s_cbranch_scc1 .LBB0_765
	s_barrier

; #define PG8_STAGE(bufoff, gbase, voff) do { _Pragma("unroll") for (int _i = 0; _i < 2; ++_i) \
;         __builtin_amdgcn_global_load_lds((const unsigned*)((const char*)(gbase) + (voff)[_i]), (PG8_LAS unsigned*)(lds + (bufoff) + ldsw + _i * 8192), 16, 0, 0); } while (0)
; #define PG8_LDA(dst, b, h) do { _Pragma("unroll") for (int m = 0; m < 4; ++m) _Pragma("unroll") for (int k = 0; k < 2; ++k) dst[m][k] = *(const PG8_LAS bf16x8*)(lds + PG8_SA(b, h) + aoff + m * 2048 + k * 1024); } while (0)
; template <class Epi, class Sched, bool ALIGN_EPI = false, bool SP2 = false>
; __device__ __forceinline__ void gemm_phase(PG8_LAS unsigned char* lds, const Gemm g, const Sched& S, const Epi& E) {
;     ...
;         const bool has_next = S.next(ui + 1, nxt);
;         const char* nA = has_next ? (const char*)g.A + (size_t)nxt.pm * tstep : cA; const char* nB = has_next ? (const char*)g.Bt + (size_t)nxt.pn * tstep : cB;
;         for (int t = 0; t < nt; t += 2) {
;             const bool last = (t == nt - 2);
;             const char* a1 = cA + (size_t)(t + 1) * kstep;
;             const char* a2 = last ? nA : cA + (size_t)(t + 2) * kstep; const char* b2 = last ? nB : cB + (size_t)(t + 2) * kstep;
;             const char* a3 = a2 + kstep; const char* b3 = b2 + kstep;
;             if (last && has_next) S.a_ready(nxt);
;             if constexpr (SP2) {
;             PG8_LDB(B0, 0, 0); PG8_LDB(B1, 0, 1); PG8_SCHED; PG8_LDA(At, 0, 0); PG8_STAGE(PG8_SA(1, 1), a1 + hstep, voffA);
;             PG8_WAIT_V(8); PG8_WAIT_L(0); PG8_BAR; PG8_MMA(0, 0, At, B0); PG8_MMA(0, 1, At, B1); PG8_BAR; PG8_SCHED;
;             PG8_LDA(At, 0, 1); PG8_STAGE(PG8_SB(0, 0), b2, voffB); PG8_STAGE(PG8_SB(0, 1), b2 + hstep, voffB); PG8_STAGE(PG8_SA(0, 0), a2, voffA);
;             PG8_WAIT_V(8); PG8_WAIT_L(0); PG8_BAR; PG8_MMA(1, 0, At, B0); PG8_MMA(1, 1, At, B1); PG8_BAR; PG8_SCHED;
;             PG8_LDB(B0, 1, 0); PG8_LDB(B1, 1, 1); PG8_SCHED; PG8_LDA(At, 1, 0); PG8_STAGE(PG8_SA(0, 1), a2 + hstep, voffA);
;             PG8_WAIT_V(8); PG8_WAIT_L(0); PG8_BAR; PG8_MMA(0, 0, At, B0); PG8_MMA(0, 1, At, B1); PG8_BAR; PG8_SCHED;
;             PG8_LDA(At, 1, 1); PG8_STAGE(PG8_SB(1, 0), b3, voffB); PG8_STAGE(PG8_SB(1, 1), b3 + hstep, voffB); PG8_STAGE(PG8_SA(1, 0), a3, voffA);
;             PG8_WAIT_V(8); PG8_WAIT_L(0); PG8_BAR; PG8_MMA(1, 0, At, B0); PG8_MMA(1, 1, At, B1); PG8_BAR; PG8_SCHED;
.LBB0_774:
	s_ashr_i32 s23, s22, 31
	s_lshl_b64 s[24:25], s[22:23], 20
	s_add_u32 s24, s40, s24
	s_addc_u32 s25, s41, s25
	s_and_b64 s[26:27], s[38:39], exec
	s_cselect_b32 s23, s25, s31
	s_cselect_b32 s62, s24, s30
	s_ashr_i32 s21, s20, 31
	s_lshl_b64 s[26:27], s[20:21], 20
	s_add_u32 s26, s44, s26
	s_addc_u32 s27, s45, s27
	s_and_b64 s[36:37], s[38:39], exec
	s_cselect_b32 s21, s27, s35
	s_cselect_b32 s63, s26, s34
	s_add_u32 s30, s30, 0x80080
	s_addc_u32 s31, s31, 0
	s_add_u32 s64, s34, 0x100
	s_addc_u32 s65, s35, 0
	s_mov_b32 s66, -2
	ds_read_b128 v[152:155], v149
	ds_read_b128 v[156:159], v149 offset:1024
	ds_read_b128 v[160:163], v149 offset:2048
	ds_read_b128 v[164:167], v149 offset:3072
	ds_read_b128 v[168:171], v150
	ds_read_b128 v[172:175], v150 offset:1024
	ds_read_b128 v[176:179], v150 offset:2048
	ds_read_b128 v[180:183], v150 offset:3072
	s_add_u32 s34, s30, 0xfff80080
	s_addc_u32 s35, s31, -1
	s_cmp_eq_u32 s66, 28
	s_cselect_b32 s37, s23, s35
	s_cselect_b32 s36, s62, s34
	s_cselect_b32 s35, s21, s65
	s_cselect_b32 s34, s63, s64
	v_lshl_add_u64 v[144:145], s[30:31], 0, v[136:137]
	s_add_i32 m0, s50, 0xc000
	ds_read_b128 v[184:187], v151
	ds_read_b128 v[188:191], v151 offset:1024
	ds_read_b128 v[192:195], v151 offset:2048
	ds_read_b128 v[196:199], v151 offset:3072
	ds_read_b128 v[200:203], v151 offset:4096
	ds_read_b128 v[204:207], v151 offset:5120
	ds_read_b128 v[208:211], v151 offset:6144
	ds_read_b128 v[212:215], v151 offset:7168
	global_load_lds_dwordx4 v[144:145], off
	v_lshl_add_u64 v[144:145], s[30:31], 0, v[138:139]
	s_add_i32 m0, s50, 0xe000
	s_nop 0
	global_load_lds_dwordx4 v[144:145], off
	s_waitcnt vmcnt(8)
	s_waitcnt lgkmcnt(0)
	s_barrier
	s_setprio 1
	s_waitcnt lgkmcnt(0)
	v_mfma_f32_16x16x32_bf16 v[124:127], v[152:155], v[184:187], 0
	v_mfma_f32_16x16x32_bf16 v[120:123], v[160:163], v[184:187], 0
	v_mfma_f32_16x16x32_bf16 v[108:111], v[152:155], v[192:195], 0
	v_mfma_f32_16x16x32_bf16 v[104:107], v[160:163], v[192:195], 0
	v_mfma_f32_16x16x32_bf16 v[92:95], v[152:155], v[200:203], 0
	v_mfma_f32_16x16x32_bf16 v[88:91], v[160:163], v[200:203], 0
	v_mfma_f32_16x16x32_bf16 v[76:79], v[152:155], v[208:211], 0
	v_mfma_f32_16x16x32_bf16 v[72:75], v[160:163], v[208:211], 0
	v_mfma_f32_16x16x32_bf16 v[124:127], v[156:159], v[188:191], v[124:127]
	v_mfma_f32_16x16x32_bf16 v[120:123], v[164:167], v[188:191], v[120:123]
	v_mfma_f32_16x16x32_bf16 v[108:111], v[156:159], v[196:199], v[108:111]
	v_mfma_f32_16x16x32_bf16 v[104:107], v[164:167], v[196:199], v[104:107]
	v_mfma_f32_16x16x32_bf16 v[92:95], v[156:159], v[204:207], v[92:95]
	v_mfma_f32_16x16x32_bf16 v[88:91], v[164:167], v[204:207], v[88:91]
	v_mfma_f32_16x16x32_bf16 v[76:79], v[156:159], v[212:215], v[76:79]
	v_mfma_f32_16x16x32_bf16 v[72:75], v[164:167], v[212:215], v[72:75]
	s_setprio 0
	s_setprio 1
	v_mfma_f32_16x16x32_bf16 v[116:119], v[168:171], v[184:187], 0
	v_mfma_f32_16x16x32_bf16 v[112:115], v[176:179], v[184:187], 0
	v_mfma_f32_16x16x32_bf16 v[100:103], v[168:171], v[192:195], 0
	v_mfma_f32_16x16x32_bf16 v[96:99], v[176:179], v[192:195], 0
	v_mfma_f32_16x16x32_bf16 v[84:87], v[168:171], v[200:203], 0
	v_mfma_f32_16x16x32_bf16 v[80:83], v[176:179], v[200:203], 0
	v_mfma_f32_16x16x32_bf16 v[68:71], v[168:171], v[208:211], 0
	v_mfma_f32_16x16x32_bf16 v[64:67], v[176:179], v[208:211], 0
	v_mfma_f32_16x16x32_bf16 v[116:119], v[172:175], v[188:191], v[116:119]
	v_mfma_f32_16x16x32_bf16 v[112:115], v[180:183], v[188:191], v[112:115]
	v_mfma_f32_16x16x32_bf16 v[100:103], v[172:175], v[196:199], v[100:103]
	v_mfma_f32_16x16x32_bf16 v[96:99], v[180:183], v[196:199], v[96:99]
	v_mfma_f32_16x16x32_bf16 v[84:87], v[172:175], v[204:207], v[84:87]
	v_mfma_f32_16x16x32_bf16 v[80:83], v[180:183], v[204:207], v[80:83]
	v_mfma_f32_16x16x32_bf16 v[68:71], v[172:175], v[212:215], v[68:71]
	v_mfma_f32_16x16x32_bf16 v[64:67], v[180:183], v[212:215], v[64:67]
	s_setprio 0
	s_barrier
	s_add_i32 s67, s60, s47
	v_lshl_add_u64 v[144:145], s[34:35], 0, v[132:133]
	s_mov_b32 m0, s67
	ds_read_b128 v[184:187], v151 offset:16384
	ds_read_b128 v[188:191], v151 offset:17408
	ds_read_b128 v[192:195], v151 offset:18432
	ds_read_b128 v[196:199], v151 offset:19456
	ds_read_b128 v[200:203], v151 offset:20480
	ds_read_b128 v[204:207], v151 offset:21504
	ds_read_b128 v[208:211], v151 offset:22528
	ds_read_b128 v[212:215], v151 offset:23552
	global_load_lds_dwordx4 v[144:145], off
	s_add_i32 m0, s67, 0x2000
	s_add_u32 s68, s34, 0x80000
	v_lshl_add_u64 v[218:219], s[34:35], 0, v[128:129]
	s_addc_u32 s69, s35, 0
	s_add_i32 s67, s61, s47
	global_load_lds_dwordx4 v[218:219], off
	v_lshl_add_u64 v[220:221], s[68:69], 0, v[132:133]
	s_mov_b32 m0, s67
	v_lshl_add_u64 v[222:223], s[36:37], 0, v[130:131]
	global_load_lds_dwordx4 v[220:221], off
	v_lshl_add_u64 v[220:221], s[68:69], 0, v[128:129]
	s_add_i32 m0, s67, 0x2000
	s_nop 0
	global_load_lds_dwordx4 v[220:221], off
	v_lshl_add_u64 v[220:221], s[36:37], 0, v[134:135]
	s_mov_b32 m0, s50
	s_nop 0
	global_load_lds_dwordx4 v[220:221], off
	s_mov_b32 m0, s51
	s_nop 0
	global_load_lds_dwordx4 v[222:223], off
	s_waitcnt vmcnt(8)
	s_waitcnt lgkmcnt(0)
	s_barrier
; #define PG8_STAGE(bufoff, gbase, voff) do { _Pragma("unroll") for (int _i = 0; _i < 2; ++_i) \
;         __builtin_amdgcn_global_load_lds((const unsigned*)((const char*)(gbase) + (voff)[_i]), (PG8_LAS unsigned*)(lds + (bufoff) + ldsw + _i * 8192), 16, 0, 0); } while (0)
; #define PG8_LDA(dst, b, h) do { _Pragma("unroll") for (int m = 0; m < 4; ++m) _Pragma("unroll") for (int k = 0; k < 2; ++k) dst[m][k] = *(const PG8_LAS bf16x8*)(lds + PG8_SA(b, h) + aoff + m * 2048 + k * 1024); } while (0)
; #define PG8_LDB(dst, b, h) do { _Pragma("unroll") for (int n = 0; n < 2; ++n) _Pragma("unroll") for (int k = 0; k < 2; ++k) dst[n][k] = *(const PG8_LAS bf16x8*)(lds + PG8_SB(b, h) + boff + n * 2048 + k * 1024); } while (0)
; #define PG8_MMA(ai, bj, At, Bt) do { __builtin_amdgcn_s_setprio(1); _Pragma("unroll") for (int m = 0; m < 4; ++m) _Pragma("unroll") for (int n = 0; n < 2; ++n) _Pragma("unroll") for (int k = 0; k < 2; ++k) \
;         acc[ai][bj][m][n] = __builtin_amdgcn_mfma_f32_16x16x32_bf16(Bt[n][k], At[m][k], acc[ai][bj][m][n], 0, 0, 0); __builtin_amdgcn_s_setprio(0); } while (0)
; #define PG8_WAIT_V(n) asm volatile("s_waitcnt vmcnt(" #n ")" ::: "memory")
; #define PG8_WAIT_L(n) asm volatile("s_waitcnt lgkmcnt(" #n ")" ::: "memory")
; #define PG8_BAR __builtin_amdgcn_s_barrier()
; #define PG8_SCHED __builtin_amdgcn_sched_barrier(0)
; template <class Epi, class Sched, bool ALIGN_EPI = false, bool SP2 = false>
; __device__ __forceinline__ void gemm_phase(PG8_LAS unsigned char* lds, const Gemm g, const Sched& S, const Epi& E) {
;     ...
;             PG8_WAIT_V(8); PG8_WAIT_L(0); PG8_BAR; PG8_MMA(1, 0, At, B0); PG8_MMA(1, 1, At, B1); PG8_BAR; PG8_SCHED;
;             PG8_LDB(B0, 1, 0); PG8_LDB(B1, 1, 1); PG8_SCHED; PG8_LDA(At, 1, 0); PG8_STAGE(PG8_SA(0, 1), a2 + hstep, voffA);
;             PG8_WAIT_V(8); PG8_WAIT_L(0); PG8_BAR; PG8_MMA(0, 0, At, B0); PG8_MMA(0, 1, At, B1); PG8_BAR; PG8_SCHED;
	s_setprio 1
	s_waitcnt lgkmcnt(0)
	v_mfma_f32_16x16x32_bf16 v[60:63], v[152:155], v[184:187], 0
	v_mfma_f32_16x16x32_bf16 v[56:59], v[160:163], v[184:187], 0
	v_mfma_f32_16x16x32_bf16 v[44:47], v[152:155], v[192:195], 0
	v_mfma_f32_16x16x32_bf16 v[40:43], v[160:163], v[192:195], 0
	v_mfma_f32_16x16x32_bf16 v[28:31], v[152:155], v[200:203], 0
	v_mfma_f32_16x16x32_bf16 v[24:27], v[160:163], v[200:203], 0
	v_mfma_f32_16x16x32_bf16 v[12:15], v[152:155], v[208:211], 0
	v_mfma_f32_16x16x32_bf16 v[8:11], v[160:163], v[208:211], 0
	v_mfma_f32_16x16x32_bf16 v[60:63], v[156:159], v[188:191], v[60:63]
	v_mfma_f32_16x16x32_bf16 v[56:59], v[164:167], v[188:191], v[56:59]
	v_mfma_f32_16x16x32_bf16 v[44:47], v[156:159], v[196:199], v[44:47]
	v_mfma_f32_16x16x32_bf16 v[40:43], v[164:167], v[196:199], v[40:43]
	v_mfma_f32_16x16x32_bf16 v[28:31], v[156:159], v[204:207], v[28:31]
	v_mfma_f32_16x16x32_bf16 v[24:27], v[164:167], v[204:207], v[24:27]
	v_mfma_f32_16x16x32_bf16 v[12:15], v[156:159], v[212:215], v[12:15]
	v_mfma_f32_16x16x32_bf16 v[8:11], v[164:167], v[212:215], v[8:11]
	s_setprio 0
	s_setprio 1
	v_mfma_f32_16x16x32_bf16 v[52:55], v[168:171], v[184:187], 0
	v_mfma_f32_16x16x32_bf16 v[48:51], v[176:179], v[184:187], 0
	v_mfma_f32_16x16x32_bf16 v[36:39], v[168:171], v[192:195], 0
	v_mfma_f32_16x16x32_bf16 v[32:35], v[176:179], v[192:195], 0
	v_mfma_f32_16x16x32_bf16 v[20:23], v[168:171], v[200:203], 0
	v_mfma_f32_16x16x32_bf16 v[16:19], v[176:179], v[200:203], 0
	v_mfma_f32_16x16x32_bf16 v[4:7], v[168:171], v[208:211], 0
	v_mfma_f32_16x16x32_bf16 v[0:3], v[176:179], v[208:211], 0
	v_mfma_f32_16x16x32_bf16 v[52:55], v[172:175], v[188:191], v[52:55]
	v_mfma_f32_16x16x32_bf16 v[48:51], v[180:183], v[188:191], v[48:51]
	v_mfma_f32_16x16x32_bf16 v[36:39], v[172:175], v[196:199], v[36:39]
	v_mfma_f32_16x16x32_bf16 v[32:35], v[180:183], v[196:199], v[32:35]
	v_mfma_f32_16x16x32_bf16 v[20:23], v[172:175], v[204:207], v[20:23]
	v_mfma_f32_16x16x32_bf16 v[16:19], v[180:183], v[204:207], v[16:19]
	v_mfma_f32_16x16x32_bf16 v[4:7], v[172:175], v[212:215], v[4:7]
	v_mfma_f32_16x16x32_bf16 v[0:3], v[180:183], v[212:215], v[0:3]
	s_setprio 0
	s_barrier
	s_add_i32 s67, 0, 0x18000
	s_add_i32 s68, 0, 0x1c000
	v_add_u32_e32 v164, s67, v147
	v_add_u32_e32 v180, s68, v147
	ds_read_b128 v[152:155], v164
	ds_read_b128 v[156:159], v164 offset:1024
	ds_read_b128 v[160:163], v164 offset:2048
	ds_read_b128 v[164:167], v164 offset:3072
	ds_read_b128 v[168:171], v180
	ds_read_b128 v[172:175], v180 offset:1024
	ds_read_b128 v[176:179], v180 offset:2048
	ds_read_b128 v[180:183], v180 offset:3072
	s_add_u32 s36, s36, 0x80000
	s_addc_u32 s37, s37, 0
	s_mov_b32 m0, s52
	v_lshl_add_u64 v[224:225], s[36:37], 0, v[134:135]
	ds_read_b128 v[184:187], v151 offset:32768
	ds_read_b128 v[188:191], v151 offset:33792
	ds_read_b128 v[192:195], v151 offset:34816
	ds_read_b128 v[196:199], v151 offset:35840
	ds_read_b128 v[200:203], v151 offset:36864
	ds_read_b128 v[204:207], v151 offset:37888
	ds_read_b128 v[208:211], v151 offset:38912
	ds_read_b128 v[212:215], v151 offset:39936
	global_load_lds_dwordx4 v[224:225], off
	v_lshl_add_u64 v[224:225], s[36:37], 0, v[130:131]
	s_mov_b32 m0, s53
	s_nop 0
	global_load_lds_dwordx4 v[224:225], off
	s_waitcnt vmcnt(8)
	s_waitcnt lgkmcnt(0)
	s_barrier
	s_setprio 1
	s_waitcnt lgkmcnt(0)
	v_mfma_f32_16x16x32_bf16 v[124:127], v[152:155], v[184:187], v[124:127]
	v_mfma_f32_16x16x32_bf16 v[120:123], v[160:163], v[184:187], v[120:123]
	v_mfma_f32_16x16x32_bf16 v[108:111], v[152:155], v[192:195], v[108:111]
	v_mfma_f32_16x16x32_bf16 v[104:107], v[160:163], v[192:195], v[104:107]
	v_mfma_f32_16x16x32_bf16 v[92:95], v[152:155], v[200:203], v[92:95]
	v_mfma_f32_16x16x32_bf16 v[88:91], v[160:163], v[200:203], v[88:91]
	v_mfma_f32_16x16x32_bf16 v[76:79], v[152:155], v[208:211], v[76:79]
	v_mfma_f32_16x16x32_bf16 v[72:75], v[160:163], v[208:211], v[72:75]
	v_mfma_f32_16x16x32_bf16 v[124:127], v[156:159], v[188:191], v[124:127]
	v_mfma_f32_16x16x32_bf16 v[120:123], v[164:167], v[188:191], v[120:123]
	v_mfma_f32_16x16x32_bf16 v[108:111], v[156:159], v[196:199], v[108:111]
	v_mfma_f32_16x16x32_bf16 v[104:107], v[164:167], v[196:199], v[104:107]
	v_mfma_f32_16x16x32_bf16 v[92:95], v[156:159], v[204:207], v[92:95]
	v_mfma_f32_16x16x32_bf16 v[88:91], v[164:167], v[204:207], v[88:91]
	v_mfma_f32_16x16x32_bf16 v[76:79], v[156:159], v[212:215], v[76:79]
	v_mfma_f32_16x16x32_bf16 v[72:75], v[164:167], v[212:215], v[72:75]
	s_setprio 0
	s_setprio 1
	v_mfma_f32_16x16x32_bf16 v[116:119], v[168:171], v[184:187], v[116:119]
	v_mfma_f32_16x16x32_bf16 v[112:115], v[176:179], v[184:187], v[112:115]
	v_mfma_f32_16x16x32_bf16 v[100:103], v[168:171], v[192:195], v[100:103]
	v_mfma_f32_16x16x32_bf16 v[96:99], v[176:179], v[192:195], v[96:99]
	v_mfma_f32_16x16x32_bf16 v[84:87], v[168:171], v[200:203], v[84:87]
	v_mfma_f32_16x16x32_bf16 v[80:83], v[176:179], v[200:203], v[80:83]
	v_mfma_f32_16x16x32_bf16 v[68:71], v[168:171], v[208:211], v[68:71]
	v_mfma_f32_16x16x32_bf16 v[64:67], v[176:179], v[208:211], v[64:67]
	v_mfma_f32_16x16x32_bf16 v[116:119], v[172:175], v[188:191], v[116:119]
	v_mfma_f32_16x16x32_bf16 v[112:115], v[180:183], v[188:191], v[112:115]
	v_mfma_f32_16x16x32_bf16 v[100:103], v[172:175], v[196:199], v[100:103]
	v_mfma_f32_16x16x32_bf16 v[96:99], v[180:183], v[196:199], v[96:99]
	v_mfma_f32_16x16x32_bf16 v[84:87], v[172:175], v[204:207], v[84:87]
	v_mfma_f32_16x16x32_bf16 v[80:83], v[180:183], v[204:207], v[80:83]
	v_mfma_f32_16x16x32_bf16 v[68:71], v[172:175], v[212:215], v[68:71]
	v_mfma_f32_16x16x32_bf16 v[64:67], v[180:183], v[212:215], v[64:67]
	s_setprio 0
	s_barrier
; #define PG8_STAGE(bufoff, gbase, voff) do { _Pragma("unroll") for (int _i = 0; _i < 2; ++_i) \
;         __builtin_amdgcn_global_load_lds((const unsigned*)((const char*)(gbase) + (voff)[_i]), (PG8_LAS unsigned*)(lds + (bufoff) + ldsw + _i * 8192), 16, 0, 0); } while (0)
; #define PG8_LDA(dst, b, h) do { _Pragma("unroll") for (int m = 0; m < 4; ++m) _Pragma("unroll") for (int k = 0; k < 2; ++k) dst[m][k] = *(const PG8_LAS bf16x8*)(lds + PG8_SA(b, h) + aoff + m * 2048 + k * 1024); } while (0)
; #define PG8_MMA(ai, bj, At, Bt) do { __builtin_amdgcn_s_setprio(1); _Pragma("unroll") for (int m = 0; m < 4; ++m) _Pragma("unroll") for (int n = 0; n < 2; ++n) _Pragma("unroll") for (int k = 0; k < 2; ++k) \
;         acc[ai][bj][m][n] = __builtin_amdgcn_mfma_f32_16x16x32_bf16(Bt[n][k], At[m][k], acc[ai][bj][m][n], 0, 0, 0); __builtin_amdgcn_s_setprio(0); } while (0)
; #define PG8_WAIT_V(n) asm volatile("s_waitcnt vmcnt(" #n ")" ::: "memory")
; #define PG8_WAIT_L(n) asm volatile("s_waitcnt lgkmcnt(" #n ")" ::: "memory")
; #define PG8_BAR __builtin_amdgcn_s_barrier()
; #define PG8_SCHED __builtin_amdgcn_sched_barrier(0)
; template <class Epi, class Sched, bool ALIGN_EPI = false, bool SP2 = false>
; __device__ __forceinline__ void gemm_phase(PG8_LAS unsigned char* lds, const Gemm g, const Sched& S, const Epi& E) {
;     ...
;         for (int t = 0; t < nt; t += 2) {
;     ...
;             PG8_LDA(At, 1, 1); PG8_STAGE(PG8_SB(1, 0), b3, voffB); PG8_STAGE(PG8_SB(1, 1), b3 + hstep, voffB); PG8_STAGE(PG8_SA(1, 0), a3, voffA);
;             PG8_WAIT_V(8); PG8_WAIT_L(0); PG8_BAR; PG8_MMA(1, 0, At, B0); PG8_MMA(1, 1, At, B1); PG8_BAR; PG8_SCHED;
	s_add_i32 s36, s67, s47
	v_lshl_add_u64 v[144:145], v[144:145], 0, s[16:17]
	s_mov_b32 m0, s36
	ds_read_b128 v[184:187], v151 offset:49152
	ds_read_b128 v[188:191], v151 offset:50176
	ds_read_b128 v[192:195], v151 offset:51200
	ds_read_b128 v[196:199], v151 offset:52224
	ds_read_b128 v[200:203], v151 offset:53248
	ds_read_b128 v[204:207], v151 offset:54272
	ds_read_b128 v[208:211], v151 offset:55296
	ds_read_b128 v[212:215], v151 offset:56320
	global_load_lds_dwordx4 v[144:145], off
	s_add_i32 m0, s36, 0x2000
	s_add_u32 s34, s34, 0x80080
	v_lshl_add_u64 v[144:145], v[218:219], 0, s[16:17]
	s_addc_u32 s35, s35, 0
	s_add_i32 s36, s68, s47
	global_load_lds_dwordx4 v[144:145], off
	v_lshl_add_u64 v[144:145], s[34:35], 0, v[132:133]
	s_mov_b32 m0, s36
	s_nop 0
	global_load_lds_dwordx4 v[144:145], off
	v_lshl_add_u64 v[144:145], s[34:35], 0, v[128:129]
	s_add_i32 m0, s36, 0x2000
	s_nop 0
	global_load_lds_dwordx4 v[144:145], off
	v_lshl_add_u64 v[144:145], v[220:221], 0, s[16:17]
	s_mov_b32 m0, s55
	s_nop 0
	global_load_lds_dwordx4 v[144:145], off
	v_lshl_add_u64 v[144:145], v[222:223], 0, s[16:17]
	s_mov_b32 m0, s59
	s_nop 0
	global_load_lds_dwordx4 v[144:145], off
	s_waitcnt vmcnt(8)
	s_waitcnt lgkmcnt(0)
	s_barrier
	s_setprio 1
	s_waitcnt lgkmcnt(0)
	v_mfma_f32_16x16x32_bf16 v[60:63], v[152:155], v[184:187], v[60:63]
	v_mfma_f32_16x16x32_bf16 v[56:59], v[160:163], v[184:187], v[56:59]
	v_mfma_f32_16x16x32_bf16 v[44:47], v[152:155], v[192:195], v[44:47]
	v_mfma_f32_16x16x32_bf16 v[40:43], v[160:163], v[192:195], v[40:43]
	v_mfma_f32_16x16x32_bf16 v[28:31], v[152:155], v[200:203], v[28:31]
	v_mfma_f32_16x16x32_bf16 v[24:27], v[160:163], v[200:203], v[24:27]
	v_mfma_f32_16x16x32_bf16 v[12:15], v[152:155], v[208:211], v[12:15]
	v_mfma_f32_16x16x32_bf16 v[8:11], v[160:163], v[208:211], v[8:11]
	v_mfma_f32_16x16x32_bf16 v[60:63], v[156:159], v[188:191], v[60:63]
	v_mfma_f32_16x16x32_bf16 v[56:59], v[164:167], v[188:191], v[56:59]
	v_mfma_f32_16x16x32_bf16 v[44:47], v[156:159], v[196:199], v[44:47]
	v_mfma_f32_16x16x32_bf16 v[40:43], v[164:167], v[196:199], v[40:43]
	v_mfma_f32_16x16x32_bf16 v[28:31], v[156:159], v[204:207], v[28:31]
	v_mfma_f32_16x16x32_bf16 v[24:27], v[164:167], v[204:207], v[24:27]
	v_mfma_f32_16x16x32_bf16 v[12:15], v[156:159], v[212:215], v[12:15]
	v_mfma_f32_16x16x32_bf16 v[8:11], v[164:167], v[212:215], v[8:11]
	s_setprio 0
	s_setprio 1
	v_mfma_f32_16x16x32_bf16 v[52:55], v[168:171], v[184:187], v[52:55]
	v_mfma_f32_16x16x32_bf16 v[48:51], v[176:179], v[184:187], v[48:51]
	v_mfma_f32_16x16x32_bf16 v[36:39], v[168:171], v[192:195], v[36:39]
	v_mfma_f32_16x16x32_bf16 v[32:35], v[176:179], v[192:195], v[32:35]
	v_mfma_f32_16x16x32_bf16 v[20:23], v[168:171], v[200:203], v[20:23]
	v_mfma_f32_16x16x32_bf16 v[16:19], v[176:179], v[200:203], v[16:19]
	v_mfma_f32_16x16x32_bf16 v[4:7], v[168:171], v[208:211], v[4:7]
	v_mfma_f32_16x16x32_bf16 v[0:3], v[176:179], v[208:211], v[0:3]
	v_mfma_f32_16x16x32_bf16 v[52:55], v[172:175], v[188:191], v[52:55]
	v_mfma_f32_16x16x32_bf16 v[48:51], v[180:183], v[188:191], v[48:51]
	v_mfma_f32_16x16x32_bf16 v[36:39], v[172:175], v[196:199], v[36:39]
	v_mfma_f32_16x16x32_bf16 v[32:35], v[180:183], v[196:199], v[32:35]
	v_mfma_f32_16x16x32_bf16 v[20:23], v[172:175], v[204:207], v[20:23]
	v_mfma_f32_16x16x32_bf16 v[16:19], v[180:183], v[204:207], v[16:19]
	v_mfma_f32_16x16x32_bf16 v[4:7], v[172:175], v[212:215], v[4:7]
	v_mfma_f32_16x16x32_bf16 v[0:3], v[180:183], v[212:215], v[0:3]
	s_setprio 0
	s_barrier
	s_add_i32 s66, s66, 2
	s_add_u32 s30, s30, 0x100
	s_addc_u32 s31, s31, 0
	s_add_u32 s64, s64, 0x100
	s_addc_u32 s65, s65, 0
	s_cmp_gt_u32 s66, 29

; __device__ __forceinline__ unsigned xb_ld(unsigned* p)              { return __hip_atomic_load(p, __ATOMIC_RELAXED, __HIP_MEMORY_SCOPE_AGENT); }
; __device__ __forceinline__ unsigned xb_add(unsigned* p, unsigned v) { return __hip_atomic_fetch_add(p, v, __ATOMIC_RELAXED, __HIP_MEMORY_SCOPE_AGENT); }
; #define XB_SPIN(cond, bar) do { unsigned _sp = 0; while (cond) { __builtin_amdgcn_s_sleep(1); \
;     if ((++_sp & 255u) == 0u) { if (xb_ld(&(bar)[XB_TMO])) break; if (_sp > XB_SPIN_CAP) { atomicAdd(&(bar)[XB_TMO], 1u); break; } } } } while (0)
; __device__ __forceinline__ void xcd_barrier(const XcdBarrier& b) {
;     ...
;             else XB_SPIN(xb_ld(&bar[XB_TOPGEN]) == tg, bar);
;             __builtin_amdgcn_fence(__ATOMIC_ACQUIRE, "agent");
;             xb_add(&bar[XB_XGEN(b.x)], 1u);
;             asm volatile("s_waitcnt vmcnt(0)" ::: "memory");
;         } else {
;             XB_SPIN(xb_ld(&bar[XB_XGEN(b.x)]) == gen, bar);
.LBB0_829:
	s_or_b64 exec, exec, s[4:5]
	s_nop 0
	s_nop 0
	s_nop 0
	s_nop 0
	s_nop 0
	s_nop 0
	s_nop 0
	s_nop 0
	s_nop 0
	s_nop 0
	s_nop 0
	s_nop 0
	s_and_saveexec_b64 s[4:5], s[6:7]
	s_cbranch_execz .LBB0_831
	v_mov_b32_e32 v2, 1
	global_atomic_add v[0:1], v2, off

; #define PG8_STAGE(bufoff, gbase, voff) do { _Pragma("unroll") for (int _i = 0; _i < 2; ++_i) \
;         __builtin_amdgcn_global_load_lds((const unsigned*)((const char*)(gbase) + (voff)[_i]), (PG8_LAS unsigned*)(lds + (bufoff) + ldsw + _i * 8192), 16, 0, 0); } while (0)
; #define PG8_LDA(dst, b, h) do { _Pragma("unroll") for (int m = 0; m < 4; ++m) _Pragma("unroll") for (int k = 0; k < 2; ++k) dst[m][k] = *(const PG8_LAS bf16x8*)(lds + PG8_SA(b, h) + aoff + m * 2048 + k * 1024); } while (0)
; template <class Epi, class Sched, bool ALIGN_EPI = false, bool SP2 = false>
; __device__ __forceinline__ void gemm_phase(PG8_LAS unsigned char* lds, const Gemm g, const Sched& S, const Epi& E) {
;     ...
;         const bool has_next = S.next(ui + 1, nxt);
;         const char* nA = has_next ? (const char*)g.A + (size_t)nxt.pm * tstep : cA; const char* nB = has_next ? (const char*)g.Bt + (size_t)nxt.pn * tstep : cB;
;         for (int t = 0; t < nt; t += 2) {
;             const bool last = (t == nt - 2);
;             const char* a1 = cA + (size_t)(t + 1) * kstep;
;             const char* a2 = last ? nA : cA + (size_t)(t + 2) * kstep; const char* b2 = last ? nB : cB + (size_t)(t + 2) * kstep;
;             const char* a3 = a2 + kstep; const char* b3 = b2 + kstep;
;             if (last && has_next) S.a_ready(nxt);
;             if constexpr (SP2) {
;             PG8_LDB(B0, 0, 0); PG8_LDB(B1, 0, 1); PG8_SCHED; PG8_LDA(At, 0, 0); PG8_STAGE(PG8_SA(1, 1), a1 + hstep, voffA);
;             PG8_WAIT_V(8); PG8_WAIT_L(0); PG8_BAR; PG8_MMA(0, 0, At, B0); PG8_MMA(0, 1, At, B1); PG8_BAR; PG8_SCHED;
;             PG8_LDA(At, 0, 1); PG8_STAGE(PG8_SB(0, 0), b2, voffB); PG8_STAGE(PG8_SB(0, 1), b2 + hstep, voffB); PG8_STAGE(PG8_SA(0, 0), a2, voffA);
;             PG8_WAIT_V(8); PG8_WAIT_L(0); PG8_BAR; PG8_MMA(1, 0, At, B0); PG8_MMA(1, 1, At, B1); PG8_BAR; PG8_SCHED;
;             PG8_LDB(B0, 1, 0); PG8_LDB(B1, 1, 1); PG8_SCHED; PG8_LDA(At, 1, 0); PG8_STAGE(PG8_SA(0, 1), a2 + hstep, voffA);
;             PG8_WAIT_V(8); PG8_WAIT_L(0); PG8_BAR; PG8_MMA(0, 0, At, B0); PG8_MMA(0, 1, At, B1); PG8_BAR; PG8_SCHED;
;             PG8_LDA(At, 1, 1); PG8_STAGE(PG8_SB(1, 0), b3, voffB); PG8_STAGE(PG8_SB(1, 1), b3 + hstep, voffB); PG8_STAGE(PG8_SA(1, 0), a3, voffA);
;             PG8_WAIT_V(8); PG8_WAIT_L(0); PG8_BAR; PG8_MMA(1, 0, At, B0); PG8_MMA(1, 1, At, B1); PG8_BAR; PG8_SCHED;
.LBB0_846:
	s_ashr_i32 s23, s22, 31
	s_lshl_b64 s[24:25], s[22:23], 22
	s_add_u32 s24, s40, s24
	s_addc_u32 s25, s41, s25
	s_and_b64 s[26:27], s[0:1], exec
	s_cselect_b32 s23, s25, s31
	s_cselect_b32 s57, s24, s30
	s_ashr_i32 s21, s20, 31
	s_lshl_b64 s[26:27], s[20:21], 22
	s_add_u32 s26, s44, s26
	s_addc_u32 s27, s45, s27
	s_and_b64 s[36:37], s[0:1], exec
	s_cselect_b32 s21, s27, s35
	s_cselect_b32 s58, s26, s34
	s_add_u32 s59, s34, 0x100
	s_addc_u32 s60, s35, 0
	s_mov_b32 s61, -2
	ds_read_b128 v[72:75], v165
	ds_read_b128 v[84:87], v165 offset:1024
	ds_read_b128 v[92:95], v165 offset:2048
	ds_read_b128 v[108:111], v165 offset:3072
	ds_read_b128 v[156:159], v166
	ds_read_b128 v[168:171], v166 offset:1024
	ds_read_b128 v[172:175], v166 offset:2048
	ds_read_b128 v[176:179], v166 offset:3072
	s_add_u32 s34, s30, 0x100
	s_addc_u32 s35, s31, 0
	s_cmpk_eq_i32 s61, 0x7c
	s_cselect_b32 s39, s23, s35
	s_cselect_b32 s38, s57, s34
	s_cselect_b32 s37, s21, s60
	s_cselect_b32 s36, s58, s59
	v_lshl_add_u64 v[160:161], s[30:31], 0, v[148:149]
	s_add_i32 m0, s42, 0xc000
	ds_read_b128 v[180:183], v167
	ds_read_b128 v[184:187], v167 offset:1024
	ds_read_b128 v[188:191], v167 offset:2048
	ds_read_b128 v[192:195], v167 offset:3072
	ds_read_b128 v[196:199], v167 offset:4096
	ds_read_b128 v[200:203], v167 offset:5120
	ds_read_b128 v[204:207], v167 offset:6144
	ds_read_b128 v[208:211], v167 offset:7168
	global_load_lds_dwordx4 v[160:161], off
	v_lshl_add_u64 v[160:161], s[30:31], 0, v[150:151]
	s_add_i32 m0, s42, 0xe000
	s_nop 0
	global_load_lds_dwordx4 v[160:161], off
	s_waitcnt vmcnt(8)
	s_waitcnt lgkmcnt(0)
	s_barrier
	s_setprio 1
	s_waitcnt lgkmcnt(0)
	v_mfma_f32_16x16x32_bf16 v[140:143], v[72:75], v[180:183], 0
	v_mfma_f32_16x16x32_bf16 v[136:139], v[92:95], v[180:183], 0
	v_mfma_f32_16x16x32_bf16 v[132:135], v[72:75], v[188:191], 0
	v_mfma_f32_16x16x32_bf16 v[128:131], v[92:95], v[188:191], 0
	v_mfma_f32_16x16x32_bf16 v[120:123], v[72:75], v[196:199], 0
	v_mfma_f32_16x16x32_bf16 v[112:115], v[92:95], v[196:199], 0
	v_mfma_f32_16x16x32_bf16 v[100:103], v[72:75], v[204:207], 0
	v_mfma_f32_16x16x32_bf16 v[88:91], v[92:95], v[204:207], 0
	v_mfma_f32_16x16x32_bf16 v[140:143], v[84:87], v[184:187], v[140:143]
	v_mfma_f32_16x16x32_bf16 v[136:139], v[108:111], v[184:187], v[136:139]
	v_mfma_f32_16x16x32_bf16 v[132:135], v[84:87], v[192:195], v[132:135]
	v_mfma_f32_16x16x32_bf16 v[128:131], v[108:111], v[192:195], v[128:131]
	v_mfma_f32_16x16x32_bf16 v[120:123], v[84:87], v[200:203], v[120:123]
	v_mfma_f32_16x16x32_bf16 v[112:115], v[108:111], v[200:203], v[112:115]
	v_mfma_f32_16x16x32_bf16 v[100:103], v[84:87], v[208:211], v[100:103]
	v_mfma_f32_16x16x32_bf16 v[88:91], v[108:111], v[208:211], v[88:91]
	s_setprio 0
	s_setprio 1
	v_mfma_f32_16x16x32_bf16 v[124:127], v[156:159], v[180:183], 0
	v_mfma_f32_16x16x32_bf16 v[116:119], v[172:175], v[180:183], 0
	v_mfma_f32_16x16x32_bf16 v[104:107], v[156:159], v[188:191], 0
	v_mfma_f32_16x16x32_bf16 v[96:99], v[172:175], v[188:191], 0
	v_mfma_f32_16x16x32_bf16 v[80:83], v[156:159], v[196:199], 0
	v_mfma_f32_16x16x32_bf16 v[76:79], v[172:175], v[196:199], 0
	v_mfma_f32_16x16x32_bf16 v[68:71], v[156:159], v[204:207], 0
	v_mfma_f32_16x16x32_bf16 v[64:67], v[172:175], v[204:207], 0
	v_mfma_f32_16x16x32_bf16 v[124:127], v[168:171], v[184:187], v[124:127]
	v_mfma_f32_16x16x32_bf16 v[116:119], v[176:179], v[184:187], v[116:119]
	v_mfma_f32_16x16x32_bf16 v[104:107], v[168:171], v[192:195], v[104:107]
	v_mfma_f32_16x16x32_bf16 v[96:99], v[176:179], v[192:195], v[96:99]
	v_mfma_f32_16x16x32_bf16 v[80:83], v[168:171], v[200:203], v[80:83]
	v_mfma_f32_16x16x32_bf16 v[76:79], v[176:179], v[200:203], v[76:79]
	v_mfma_f32_16x16x32_bf16 v[68:71], v[168:171], v[208:211], v[68:71]
	v_mfma_f32_16x16x32_bf16 v[64:67], v[176:179], v[208:211], v[64:67]
	s_setprio 0
	s_barrier
	s_add_i32 s30, s55, s47
	v_lshl_add_u64 v[160:161], s[36:37], 0, v[146:147]
	s_mov_b32 m0, s30
	ds_read_b128 v[180:183], v167 offset:16384
	ds_read_b128 v[184:187], v167 offset:17408
	ds_read_b128 v[188:191], v167 offset:18432
	ds_read_b128 v[192:195], v167 offset:19456
	ds_read_b128 v[196:199], v167 offset:20480
	ds_read_b128 v[200:203], v167 offset:21504
	ds_read_b128 v[204:207], v167 offset:22528
	ds_read_b128 v[208:211], v167 offset:23552
	global_load_lds_dwordx4 v[160:161], off
	s_add_i32 m0, s30, 0x2000
	s_add_u32 s30, s36, 0x200000
	v_lshl_add_u64 v[212:213], s[36:37], 0, v[144:145]
	s_addc_u32 s31, s37, 0
	s_add_i32 s62, s56, s47
	global_load_lds_dwordx4 v[212:213], off
	v_lshl_add_u64 v[214:215], s[30:31], 0, v[146:147]
	s_mov_b32 m0, s62
	v_lshl_add_u64 v[216:217], s[38:39], 0, v[144:145]
	global_load_lds_dwordx4 v[214:215], off
	v_lshl_add_u64 v[214:215], s[30:31], 0, v[144:145]
	s_add_i32 m0, s62, 0x2000
	s_nop 0
	global_load_lds_dwordx4 v[214:215], off
	v_lshl_add_u64 v[214:215], s[38:39], 0, v[146:147]
	s_mov_b32 m0, s42
	s_nop 0
	global_load_lds_dwordx4 v[214:215], off
	s_mov_b32 m0, s43
	s_nop 0
	global_load_lds_dwordx4 v[216:217], off
	s_waitcnt vmcnt(8)
	s_waitcnt lgkmcnt(0)
	s_barrier
; #define PG8_STAGE(bufoff, gbase, voff) do { _Pragma("unroll") for (int _i = 0; _i < 2; ++_i) \
;         __builtin_amdgcn_global_load_lds((const unsigned*)((const char*)(gbase) + (voff)[_i]), (PG8_LAS unsigned*)(lds + (bufoff) + ldsw + _i * 8192), 16, 0, 0); } while (0)
; #define PG8_LDA(dst, b, h) do { _Pragma("unroll") for (int m = 0; m < 4; ++m) _Pragma("unroll") for (int k = 0; k < 2; ++k) dst[m][k] = *(const PG8_LAS bf16x8*)(lds + PG8_SA(b, h) + aoff + m * 2048 + k * 1024); } while (0)
; #define PG8_LDB(dst, b, h) do { _Pragma("unroll") for (int n = 0; n < 2; ++n) _Pragma("unroll") for (int k = 0; k < 2; ++k) dst[n][k] = *(const PG8_LAS bf16x8*)(lds + PG8_SB(b, h) + boff + n * 2048 + k * 1024); } while (0)
; #define PG8_MMA(ai, bj, At, Bt) do { __builtin_amdgcn_s_setprio(1); _Pragma("unroll") for (int m = 0; m < 4; ++m) _Pragma("unroll") for (int n = 0; n < 2; ++n) _Pragma("unroll") for (int k = 0; k < 2; ++k) \
;         acc[ai][bj][m][n] = __builtin_amdgcn_mfma_f32_16x16x32_bf16(Bt[n][k], At[m][k], acc[ai][bj][m][n], 0, 0, 0); __builtin_amdgcn_s_setprio(0); } while (0)
; #define PG8_WAIT_V(n) asm volatile("s_waitcnt vmcnt(" #n ")" ::: "memory")
; #define PG8_WAIT_L(n) asm volatile("s_waitcnt lgkmcnt(" #n ")" ::: "memory")
; #define PG8_BAR __builtin_amdgcn_s_barrier()
; #define PG8_SCHED __builtin_amdgcn_sched_barrier(0)
; template <class Epi, class Sched, bool ALIGN_EPI = false, bool SP2 = false>
; __device__ __forceinline__ void gemm_phase(PG8_LAS unsigned char* lds, const Gemm g, const Sched& S, const Epi& E) {
;     ...
;             PG8_WAIT_V(8); PG8_WAIT_L(0); PG8_BAR; PG8_MMA(1, 0, At, B0); PG8_MMA(1, 1, At, B1); PG8_BAR; PG8_SCHED;
;             PG8_LDB(B0, 1, 0); PG8_LDB(B1, 1, 1); PG8_SCHED; PG8_LDA(At, 1, 0); PG8_STAGE(PG8_SA(0, 1), a2 + hstep, voffA);
;             PG8_WAIT_V(8); PG8_WAIT_L(0); PG8_BAR; PG8_MMA(0, 0, At, B0); PG8_MMA(0, 1, At, B1); PG8_BAR; PG8_SCHED;
	s_setprio 1
	s_waitcnt lgkmcnt(0)
	v_mfma_f32_16x16x32_bf16 v[60:63], v[72:75], v[180:183], 0
	v_mfma_f32_16x16x32_bf16 v[56:59], v[92:95], v[180:183], 0
	v_mfma_f32_16x16x32_bf16 v[52:55], v[72:75], v[188:191], 0
	v_mfma_f32_16x16x32_bf16 v[44:47], v[92:95], v[188:191], 0
	v_mfma_f32_16x16x32_bf16 v[36:39], v[72:75], v[196:199], 0
	v_mfma_f32_16x16x32_bf16 v[28:31], v[92:95], v[196:199], 0
	v_mfma_f32_16x16x32_bf16 v[20:23], v[72:75], v[204:207], 0
	v_mfma_f32_16x16x32_bf16 v[12:15], v[92:95], v[204:207], 0
	v_mfma_f32_16x16x32_bf16 v[60:63], v[84:87], v[184:187], v[60:63]
	v_mfma_f32_16x16x32_bf16 v[56:59], v[108:111], v[184:187], v[56:59]
	v_mfma_f32_16x16x32_bf16 v[52:55], v[84:87], v[192:195], v[52:55]
	v_mfma_f32_16x16x32_bf16 v[44:47], v[108:111], v[192:195], v[44:47]
	v_mfma_f32_16x16x32_bf16 v[36:39], v[84:87], v[200:203], v[36:39]
	v_mfma_f32_16x16x32_bf16 v[28:31], v[108:111], v[200:203], v[28:31]
	v_mfma_f32_16x16x32_bf16 v[20:23], v[84:87], v[208:211], v[20:23]
	v_mfma_f32_16x16x32_bf16 v[12:15], v[108:111], v[208:211], v[12:15]
	s_setprio 0
	s_setprio 1
	v_mfma_f32_16x16x32_bf16 v[48:51], v[156:159], v[180:183], 0
	v_mfma_f32_16x16x32_bf16 v[40:43], v[172:175], v[180:183], 0
	v_mfma_f32_16x16x32_bf16 v[32:35], v[156:159], v[188:191], 0
	v_mfma_f32_16x16x32_bf16 v[24:27], v[172:175], v[188:191], 0
	v_mfma_f32_16x16x32_bf16 v[16:19], v[156:159], v[196:199], 0
	v_mfma_f32_16x16x32_bf16 v[8:11], v[172:175], v[196:199], 0
	v_mfma_f32_16x16x32_bf16 v[4:7], v[156:159], v[204:207], 0
	v_mfma_f32_16x16x32_bf16 v[0:3], v[172:175], v[204:207], 0
	v_mfma_f32_16x16x32_bf16 v[48:51], v[168:171], v[184:187], v[48:51]
	v_mfma_f32_16x16x32_bf16 v[40:43], v[176:179], v[184:187], v[40:43]
	v_mfma_f32_16x16x32_bf16 v[32:35], v[168:171], v[192:195], v[32:35]
	v_mfma_f32_16x16x32_bf16 v[24:27], v[176:179], v[192:195], v[24:27]
	v_mfma_f32_16x16x32_bf16 v[16:19], v[168:171], v[200:203], v[16:19]
	v_mfma_f32_16x16x32_bf16 v[8:11], v[176:179], v[200:203], v[8:11]
	v_mfma_f32_16x16x32_bf16 v[4:7], v[168:171], v[208:211], v[4:7]
	v_mfma_f32_16x16x32_bf16 v[0:3], v[176:179], v[208:211], v[0:3]
	s_setprio 0
	s_barrier
	s_add_i32 s62, 0, 0x18000
	s_add_i32 s63, 0, 0x1c000
	v_add_u32_e32 v108, s62, v163
	v_add_u32_e32 v176, s63, v163
	ds_read_b128 v[72:75], v108
	ds_read_b128 v[84:87], v108 offset:1024
	ds_read_b128 v[92:95], v108 offset:2048
	ds_read_b128 v[108:111], v108 offset:3072
	ds_read_b128 v[156:159], v176
	ds_read_b128 v[168:171], v176 offset:1024
	ds_read_b128 v[172:175], v176 offset:2048
	ds_read_b128 v[176:179], v176 offset:3072
	s_add_u32 s30, s38, 0x200000
	s_addc_u32 s31, s39, 0
	s_mov_b32 m0, s48
	v_lshl_add_u64 v[218:219], s[30:31], 0, v[146:147]
	ds_read_b128 v[180:183], v167 offset:32768
	ds_read_b128 v[184:187], v167 offset:33792
	ds_read_b128 v[188:191], v167 offset:34816
	ds_read_b128 v[192:195], v167 offset:35840
	ds_read_b128 v[196:199], v167 offset:36864
	ds_read_b128 v[200:203], v167 offset:37888
	ds_read_b128 v[204:207], v167 offset:38912
	ds_read_b128 v[208:211], v167 offset:39936
	global_load_lds_dwordx4 v[218:219], off
	v_lshl_add_u64 v[218:219], s[30:31], 0, v[144:145]
	s_mov_b32 m0, s49
	s_nop 0
	global_load_lds_dwordx4 v[218:219], off
	s_waitcnt vmcnt(8)
	s_waitcnt lgkmcnt(0)
	s_barrier
	s_setprio 1
	s_waitcnt lgkmcnt(0)
	v_mfma_f32_16x16x32_bf16 v[140:143], v[72:75], v[180:183], v[140:143]
	v_mfma_f32_16x16x32_bf16 v[136:139], v[92:95], v[180:183], v[136:139]
	v_mfma_f32_16x16x32_bf16 v[132:135], v[72:75], v[188:191], v[132:135]
	v_mfma_f32_16x16x32_bf16 v[128:131], v[92:95], v[188:191], v[128:131]
	v_mfma_f32_16x16x32_bf16 v[120:123], v[72:75], v[196:199], v[120:123]
	v_mfma_f32_16x16x32_bf16 v[112:115], v[92:95], v[196:199], v[112:115]
	v_mfma_f32_16x16x32_bf16 v[100:103], v[72:75], v[204:207], v[100:103]
	v_mfma_f32_16x16x32_bf16 v[88:91], v[92:95], v[204:207], v[88:91]
	v_mfma_f32_16x16x32_bf16 v[140:143], v[84:87], v[184:187], v[140:143]
	v_mfma_f32_16x16x32_bf16 v[136:139], v[108:111], v[184:187], v[136:139]
	v_mfma_f32_16x16x32_bf16 v[132:135], v[84:87], v[192:195], v[132:135]
	v_mfma_f32_16x16x32_bf16 v[128:131], v[108:111], v[192:195], v[128:131]
	v_mfma_f32_16x16x32_bf16 v[120:123], v[84:87], v[200:203], v[120:123]
	v_mfma_f32_16x16x32_bf16 v[112:115], v[108:111], v[200:203], v[112:115]
	v_mfma_f32_16x16x32_bf16 v[100:103], v[84:87], v[208:211], v[100:103]
	v_mfma_f32_16x16x32_bf16 v[88:91], v[108:111], v[208:211], v[88:91]
	s_setprio 0
	s_setprio 1
	v_mfma_f32_16x16x32_bf16 v[124:127], v[156:159], v[180:183], v[124:127]
	v_mfma_f32_16x16x32_bf16 v[116:119], v[172:175], v[180:183], v[116:119]
	v_mfma_f32_16x16x32_bf16 v[104:107], v[156:159], v[188:191], v[104:107]
	v_mfma_f32_16x16x32_bf16 v[96:99], v[172:175], v[188:191], v[96:99]
	v_mfma_f32_16x16x32_bf16 v[80:83], v[156:159], v[196:199], v[80:83]
	v_mfma_f32_16x16x32_bf16 v[76:79], v[172:175], v[196:199], v[76:79]
	v_mfma_f32_16x16x32_bf16 v[68:71], v[156:159], v[204:207], v[68:71]
	v_mfma_f32_16x16x32_bf16 v[64:67], v[172:175], v[204:207], v[64:67]
	v_mfma_f32_16x16x32_bf16 v[124:127], v[168:171], v[184:187], v[124:127]
	v_mfma_f32_16x16x32_bf16 v[116:119], v[176:179], v[184:187], v[116:119]
	v_mfma_f32_16x16x32_bf16 v[104:107], v[168:171], v[192:195], v[104:107]
	v_mfma_f32_16x16x32_bf16 v[96:99], v[176:179], v[192:195], v[96:99]
	v_mfma_f32_16x16x32_bf16 v[80:83], v[168:171], v[200:203], v[80:83]
	v_mfma_f32_16x16x32_bf16 v[76:79], v[176:179], v[200:203], v[76:79]
	v_mfma_f32_16x16x32_bf16 v[68:71], v[168:171], v[208:211], v[68:71]
	v_mfma_f32_16x16x32_bf16 v[64:67], v[176:179], v[208:211], v[64:67]
	s_setprio 0
	s_barrier
; #define PG8_STAGE(bufoff, gbase, voff) do { _Pragma("unroll") for (int _i = 0; _i < 2; ++_i) \
;         __builtin_amdgcn_global_load_lds((const unsigned*)((const char*)(gbase) + (voff)[_i]), (PG8_LAS unsigned*)(lds + (bufoff) + ldsw + _i * 8192), 16, 0, 0); } while (0)
; #define PG8_LDA(dst, b, h) do { _Pragma("unroll") for (int m = 0; m < 4; ++m) _Pragma("unroll") for (int k = 0; k < 2; ++k) dst[m][k] = *(const PG8_LAS bf16x8*)(lds + PG8_SA(b, h) + aoff + m * 2048 + k * 1024); } while (0)
; #define PG8_MMA(ai, bj, At, Bt) do { __builtin_amdgcn_s_setprio(1); _Pragma("unroll") for (int m = 0; m < 4; ++m) _Pragma("unroll") for (int n = 0; n < 2; ++n) _Pragma("unroll") for (int k = 0; k < 2; ++k) \
;         acc[ai][bj][m][n] = __builtin_amdgcn_mfma_f32_16x16x32_bf16(Bt[n][k], At[m][k], acc[ai][bj][m][n], 0, 0, 0); __builtin_amdgcn_s_setprio(0); } while (0)
; #define PG8_WAIT_V(n) asm volatile("s_waitcnt vmcnt(" #n ")" ::: "memory")
; #define PG8_WAIT_L(n) asm volatile("s_waitcnt lgkmcnt(" #n ")" ::: "memory")
; #define PG8_BAR __builtin_amdgcn_s_barrier()
; #define PG8_SCHED __builtin_amdgcn_sched_barrier(0)
; template <class Epi, class Sched, bool ALIGN_EPI = false, bool SP2 = false>
; __device__ __forceinline__ void gemm_phase(PG8_LAS unsigned char* lds, const Gemm g, const Sched& S, const Epi& E) {
;     ...
;         for (int t = 0; t < nt; t += 2) {
;     ...
;             PG8_LDA(At, 1, 1); PG8_STAGE(PG8_SB(1, 0), b3, voffB); PG8_STAGE(PG8_SB(1, 1), b3 + hstep, voffB); PG8_STAGE(PG8_SA(1, 0), a3, voffA);
;             PG8_WAIT_V(8); PG8_WAIT_L(0); PG8_BAR; PG8_MMA(1, 0, At, B0); PG8_MMA(1, 1, At, B1); PG8_BAR; PG8_SCHED;
	s_add_i32 s30, s62, s47
	v_lshl_add_u64 v[160:161], v[160:161], 0, s[8:9]
	s_mov_b32 m0, s30
	ds_read_b128 v[180:183], v167 offset:49152
	ds_read_b128 v[184:187], v167 offset:50176
	ds_read_b128 v[188:191], v167 offset:51200
	ds_read_b128 v[192:195], v167 offset:52224
	ds_read_b128 v[196:199], v167 offset:53248
	ds_read_b128 v[200:203], v167 offset:54272
	ds_read_b128 v[204:207], v167 offset:55296
	ds_read_b128 v[208:211], v167 offset:56320
	global_load_lds_dwordx4 v[160:161], off
	s_add_i32 m0, s30, 0x2000
	s_add_u32 s30, s36, 0x200080
	v_lshl_add_u64 v[160:161], v[212:213], 0, s[8:9]
	s_addc_u32 s31, s37, 0
	s_add_i32 s36, s63, s47
	global_load_lds_dwordx4 v[160:161], off
	v_lshl_add_u64 v[160:161], s[30:31], 0, v[146:147]
	s_mov_b32 m0, s36
	s_nop 0
	global_load_lds_dwordx4 v[160:161], off
	v_lshl_add_u64 v[160:161], s[30:31], 0, v[144:145]
	s_add_i32 m0, s36, 0x2000
	s_nop 0
	global_load_lds_dwordx4 v[160:161], off
	v_lshl_add_u64 v[160:161], v[214:215], 0, s[8:9]
	s_mov_b32 m0, s53
	s_nop 0
	global_load_lds_dwordx4 v[160:161], off
	v_lshl_add_u64 v[160:161], v[216:217], 0, s[8:9]
	s_mov_b32 m0, s54
	s_nop 0
	global_load_lds_dwordx4 v[160:161], off
	s_waitcnt vmcnt(8)
	s_waitcnt lgkmcnt(0)
	s_barrier
	s_setprio 1
	s_waitcnt lgkmcnt(0)
	v_mfma_f32_16x16x32_bf16 v[60:63], v[72:75], v[180:183], v[60:63]
	v_mfma_f32_16x16x32_bf16 v[56:59], v[92:95], v[180:183], v[56:59]
	v_mfma_f32_16x16x32_bf16 v[52:55], v[72:75], v[188:191], v[52:55]
	v_mfma_f32_16x16x32_bf16 v[44:47], v[92:95], v[188:191], v[44:47]
	v_mfma_f32_16x16x32_bf16 v[36:39], v[72:75], v[196:199], v[36:39]
	v_mfma_f32_16x16x32_bf16 v[28:31], v[92:95], v[196:199], v[28:31]
	v_mfma_f32_16x16x32_bf16 v[20:23], v[72:75], v[204:207], v[20:23]
	v_mfma_f32_16x16x32_bf16 v[12:15], v[92:95], v[204:207], v[12:15]
	v_mfma_f32_16x16x32_bf16 v[60:63], v[84:87], v[184:187], v[60:63]
	v_mfma_f32_16x16x32_bf16 v[56:59], v[108:111], v[184:187], v[56:59]
	v_mfma_f32_16x16x32_bf16 v[52:55], v[84:87], v[192:195], v[52:55]
	v_mfma_f32_16x16x32_bf16 v[44:47], v[108:111], v[192:195], v[44:47]
	v_mfma_f32_16x16x32_bf16 v[36:39], v[84:87], v[200:203], v[36:39]
	v_mfma_f32_16x16x32_bf16 v[28:31], v[108:111], v[200:203], v[28:31]
	v_mfma_f32_16x16x32_bf16 v[20:23], v[84:87], v[208:211], v[20:23]
	v_mfma_f32_16x16x32_bf16 v[12:15], v[108:111], v[208:211], v[12:15]
	s_setprio 0
	s_setprio 1
	v_mfma_f32_16x16x32_bf16 v[48:51], v[156:159], v[180:183], v[48:51]
	v_mfma_f32_16x16x32_bf16 v[40:43], v[172:175], v[180:183], v[40:43]
	v_mfma_f32_16x16x32_bf16 v[32:35], v[156:159], v[188:191], v[32:35]
	v_mfma_f32_16x16x32_bf16 v[24:27], v[172:175], v[188:191], v[24:27]
	v_mfma_f32_16x16x32_bf16 v[16:19], v[156:159], v[196:199], v[16:19]
	v_mfma_f32_16x16x32_bf16 v[8:11], v[172:175], v[196:199], v[8:11]
	v_mfma_f32_16x16x32_bf16 v[4:7], v[156:159], v[204:207], v[4:7]
	v_mfma_f32_16x16x32_bf16 v[0:3], v[172:175], v[204:207], v[0:3]
	v_mfma_f32_16x16x32_bf16 v[48:51], v[168:171], v[184:187], v[48:51]
	v_mfma_f32_16x16x32_bf16 v[40:43], v[176:179], v[184:187], v[40:43]
	v_mfma_f32_16x16x32_bf16 v[32:35], v[168:171], v[192:195], v[32:35]
	v_mfma_f32_16x16x32_bf16 v[24:27], v[176:179], v[192:195], v[24:27]
	v_mfma_f32_16x16x32_bf16 v[16:19], v[168:171], v[200:203], v[16:19]
	v_mfma_f32_16x16x32_bf16 v[8:11], v[176:179], v[200:203], v[8:11]
	v_mfma_f32_16x16x32_bf16 v[4:7], v[168:171], v[208:211], v[4:7]
	v_mfma_f32_16x16x32_bf16 v[0:3], v[176:179], v[208:211], v[0:3]
	s_setprio 0
	s_barrier
	s_add_i32 s61, s61, 2
	s_add_u32 s59, s59, 0x100
	s_addc_u32 s60, s60, 0
	s_cmpk_gt_u32 s61, 0x7d
	s_mov_b64 s[30:31], s[34:35]
